# GEMM K loops: the mid-block s_setprio 0/1 dip inside each 32-MFMA block replaced by nops (priority held for the whole block)
# speedup vs baseline: 1.0032x; 1.0025x over previous
; #define PG8_STAGE(bufoff, gbase, voff) do { _Pragma("unroll") for (int _i = 0; _i < 2; ++_i) \
;         __builtin_amdgcn_global_load_lds((const unsigned*)((const char*)(gbase) + (voff)[_i]), (PG8_LAS unsigned*)(lds + (bufoff) + ldsw + _i * 8192), 16, 0, 0); } while (0)
; #define PG8_LDA(dst, b, h) do { _Pragma("unroll") for (int m = 0; m < 4; ++m) _Pragma("unroll") for (int k = 0; k < 2; ++k) dst[m][k] = *(const PG8_LAS bf16x8*)(lds + PG8_SA(b, h) + aoff + m * 2048 + k * 1024); } while (0)
; #define PG8_LDB(dst, b, h) do { _Pragma("unroll") for (int n = 0; n < 2; ++n) _Pragma("unroll") for (int k = 0; k < 2; ++k) dst[n][k] = *(const PG8_LAS bf16x8*)(lds + PG8_SB(b, h) + boff + n * 2048 + k * 1024); } while (0)
; #define PG8_MMA(ai, bj, At, Bt) do { __builtin_amdgcn_s_setprio(1); _Pragma("unroll") for (int m = 0; m < 4; ++m) _Pragma("unroll") for (int n = 0; n < 2; ++n) _Pragma("unroll") for (int k = 0; k < 2; ++k) \
;         acc[ai][bj][m][n] = __builtin_amdgcn_mfma_f32_16x16x32_bf16(Bt[n][k], At[m][k], acc[ai][bj][m][n], 0, 0, 0); __builtin_amdgcn_s_setprio(0); } while (0)
; #define PG8_WAIT_V(n) asm volatile("s_waitcnt vmcnt(" #n ")" ::: "memory")
; #define PG8_WAIT_L(n) asm volatile("s_waitcnt lgkmcnt(" #n ")" ::: "memory")
; template <class Epi, class Sched, bool ALIGN_EPI = false, bool SP2 = false>
; __device__ __forceinline__ void gemm_phase(PG8_LAS unsigned char* lds, const Gemm g, const Sched& S, const Epi& E) {
;     ...
;             const bool last = (t == nt - 2);
;             const char* a1 = cA + (size_t)(t + 1) * kstep;
;             const char* a2 = last ? nA : cA + (size_t)(t + 2) * kstep; const char* b2 = last ? nB : cB + (size_t)(t + 2) * kstep;
;             const char* a3 = a2 + kstep; const char* b3 = b2 + kstep;
;             if (last && has_next) S.a_ready(nxt);
;             if constexpr (SP2) {
;             PG8_LDB(B0, 0, 0); PG8_LDB(B1, 0, 1); PG8_SCHED; PG8_LDA(At, 0, 0); PG8_STAGE(PG8_SA(1, 1), a1 + hstep, voffA);
;             PG8_WAIT_V(8); PG8_WAIT_L(0); PG8_BAR; PG8_MMA(0, 0, At, B0); PG8_MMA(0, 1, At, B1); PG8_BAR; PG8_SCHED;
;             PG8_LDA(At, 0, 1); PG8_STAGE(PG8_SB(0, 0), b2, voffB); PG8_STAGE(PG8_SB(0, 1), b2 + hstep, voffB); PG8_STAGE(PG8_SA(0, 0), a2, voffA);
;             PG8_WAIT_V(8); PG8_WAIT_L(0); PG8_BAR; PG8_MMA(1, 0, At, B0); PG8_MMA(1, 1, At, B1); PG8_BAR; PG8_SCHED;
.LBB0_427:
	s_add_u32 s28, s8, 0xfffc0080
	s_addc_u32 s29, s9, -1
	s_cmp_eq_u32 s39, 12
	s_cselect_b32 s37, s5, s29
	s_cselect_b32 s36, s7, s28
	s_cselect_b32 s29, s12, s38
	s_cselect_b32 s28, s21, s23
	v_lshl_add_u64 v[160:161], s[8:9], 0, v[140:141]
	s_add_i32 m0, s63, 0xc000
	ds_read_b128 v[152:155], v162
	global_load_lds_dwordx4 v[160:161], off
	v_lshl_add_u64 v[160:161], s[8:9], 0, v[142:143]
	s_add_i32 m0, s63, 0xe000
	ds_read_b128 v[156:159], v162 offset:1024
	global_load_lds_dwordx4 v[160:161], off
	ds_read_b128 v[166:169], v162 offset:2048
	ds_read_b128 v[170:173], v162 offset:3072
	ds_read_b128 v[174:177], v163
	ds_read_b128 v[178:181], v163 offset:1024
	ds_read_b128 v[182:185], v163 offset:2048
	ds_read_b128 v[186:189], v163 offset:3072
	ds_read_b128 v[190:193], v164
	ds_read_b128 v[194:197], v164 offset:1024
	ds_read_b128 v[198:201], v164 offset:2048
	ds_read_b128 v[202:205], v164 offset:3072
	ds_read_b128 v[206:209], v164 offset:4096
	ds_read_b128 v[210:213], v164 offset:5120
	ds_read_b128 v[214:217], v164 offset:6144
	ds_read_b128 v[218:221], v164 offset:7168
	s_waitcnt vmcnt(8)
	s_waitcnt lgkmcnt(0)
	s_barrier
	s_setprio 1
	s_waitcnt lgkmcnt(0)
	v_mfma_f32_16x16x32_bf16 v[124:127], v[152:155], v[190:193], v[124:127]
	v_mfma_f32_16x16x32_bf16 v[120:123], v[166:169], v[190:193], v[120:123]
	v_mfma_f32_16x16x32_bf16 v[108:111], v[152:155], v[198:201], v[108:111]
	v_mfma_f32_16x16x32_bf16 v[104:107], v[166:169], v[198:201], v[104:107]
	v_mfma_f32_16x16x32_bf16 v[92:95], v[152:155], v[206:209], v[92:95]
	v_mfma_f32_16x16x32_bf16 v[88:91], v[166:169], v[206:209], v[88:91]
	v_mfma_f32_16x16x32_bf16 v[76:79], v[152:155], v[214:217], v[76:79]
	v_mfma_f32_16x16x32_bf16 v[72:75], v[166:169], v[214:217], v[72:75]
	v_mfma_f32_16x16x32_bf16 v[124:127], v[156:159], v[194:197], v[124:127]
	v_mfma_f32_16x16x32_bf16 v[120:123], v[170:173], v[194:197], v[120:123]
	v_mfma_f32_16x16x32_bf16 v[108:111], v[156:159], v[202:205], v[108:111]
	v_mfma_f32_16x16x32_bf16 v[104:107], v[170:173], v[202:205], v[104:107]
	v_mfma_f32_16x16x32_bf16 v[92:95], v[156:159], v[210:213], v[92:95]
	v_mfma_f32_16x16x32_bf16 v[88:91], v[170:173], v[210:213], v[88:91]
	v_mfma_f32_16x16x32_bf16 v[76:79], v[156:159], v[218:221], v[76:79]
	v_mfma_f32_16x16x32_bf16 v[72:75], v[170:173], v[218:221], v[72:75]
	s_nop 0
	s_nop 0
	v_mfma_f32_16x16x32_bf16 v[116:119], v[174:177], v[190:193], v[116:119]
	v_mfma_f32_16x16x32_bf16 v[112:115], v[182:185], v[190:193], v[112:115]
	v_mfma_f32_16x16x32_bf16 v[100:103], v[174:177], v[198:201], v[100:103]
	v_mfma_f32_16x16x32_bf16 v[96:99], v[182:185], v[198:201], v[96:99]
	v_mfma_f32_16x16x32_bf16 v[84:87], v[174:177], v[206:209], v[84:87]
	v_mfma_f32_16x16x32_bf16 v[80:83], v[182:185], v[206:209], v[80:83]
	v_mfma_f32_16x16x32_bf16 v[68:71], v[174:177], v[214:217], v[68:71]
	v_mfma_f32_16x16x32_bf16 v[64:67], v[182:185], v[214:217], v[64:67]
	v_mfma_f32_16x16x32_bf16 v[116:119], v[178:181], v[194:197], v[116:119]
	v_mfma_f32_16x16x32_bf16 v[112:115], v[186:189], v[194:197], v[112:115]
	v_mfma_f32_16x16x32_bf16 v[100:103], v[178:181], v[202:205], v[100:103]
	v_mfma_f32_16x16x32_bf16 v[96:99], v[186:189], v[202:205], v[96:99]
	v_mfma_f32_16x16x32_bf16 v[84:87], v[178:181], v[210:213], v[84:87]
	v_mfma_f32_16x16x32_bf16 v[80:83], v[186:189], v[210:213], v[80:83]
	v_mfma_f32_16x16x32_bf16 v[68:71], v[178:181], v[218:221], v[68:71]
	v_mfma_f32_16x16x32_bf16 v[64:67], v[186:189], v[218:221], v[64:67]
	s_setprio 0
	s_barrier
	s_add_i32 s42, s79, s62
	v_lshl_add_u64 v[160:161], s[28:29], 0, v[130:131]
	s_mov_b32 m0, s42
	v_lshl_add_u64 v[222:223], s[28:29], 0, v[134:135]
	global_load_lds_dwordx4 v[160:161], off
	s_add_i32 m0, s42, 0x2000
	s_add_u32 s42, s28, 0x40000
	s_addc_u32 s43, s29, 0
	s_add_i32 s44, s84, s62
	global_load_lds_dwordx4 v[222:223], off
	v_lshl_add_u64 v[224:225], s[42:43], 0, v[130:131]
	s_mov_b32 m0, s44
	v_lshl_add_u64 v[226:227], s[36:37], 0, v[132:133]
	global_load_lds_dwordx4 v[224:225], off
	v_lshl_add_u64 v[224:225], s[42:43], 0, v[134:135]
	s_add_i32 m0, s44, 0x2000
	ds_read_b128 v[190:193], v164 offset:16384
	global_load_lds_dwordx4 v[224:225], off
	v_lshl_add_u64 v[224:225], s[36:37], 0, v[128:129]
	s_mov_b32 m0, s63
	ds_read_b128 v[194:197], v164 offset:17408
	global_load_lds_dwordx4 v[224:225], off
	s_mov_b32 m0, s68
	ds_read_b128 v[198:201], v164 offset:18432
	global_load_lds_dwordx4 v[226:227], off
	ds_read_b128 v[202:205], v164 offset:19456
	ds_read_b128 v[206:209], v164 offset:20480
	ds_read_b128 v[210:213], v164 offset:21504
	ds_read_b128 v[214:217], v164 offset:22528
	ds_read_b128 v[218:221], v164 offset:23552
	s_waitcnt vmcnt(8)
	s_waitcnt lgkmcnt(0)
	s_barrier
; #define PG8_STAGE(bufoff, gbase, voff) do { _Pragma("unroll") for (int _i = 0; _i < 2; ++_i) \
;         __builtin_amdgcn_global_load_lds((const unsigned*)((const char*)(gbase) + (voff)[_i]), (PG8_LAS unsigned*)(lds + (bufoff) + ldsw + _i * 8192), 16, 0, 0); } while (0)
; #define PG8_LDA(dst, b, h) do { _Pragma("unroll") for (int m = 0; m < 4; ++m) _Pragma("unroll") for (int k = 0; k < 2; ++k) dst[m][k] = *(const PG8_LAS bf16x8*)(lds + PG8_SA(b, h) + aoff + m * 2048 + k * 1024); } while (0)
; #define PG8_LDB(dst, b, h) do { _Pragma("unroll") for (int n = 0; n < 2; ++n) _Pragma("unroll") for (int k = 0; k < 2; ++k) dst[n][k] = *(const PG8_LAS bf16x8*)(lds + PG8_SB(b, h) + boff + n * 2048 + k * 1024); } while (0)
; #define PG8_MMA(ai, bj, At, Bt) do { __builtin_amdgcn_s_setprio(1); _Pragma("unroll") for (int m = 0; m < 4; ++m) _Pragma("unroll") for (int n = 0; n < 2; ++n) _Pragma("unroll") for (int k = 0; k < 2; ++k) \
;         acc[ai][bj][m][n] = __builtin_amdgcn_mfma_f32_16x16x32_bf16(Bt[n][k], At[m][k], acc[ai][bj][m][n], 0, 0, 0); __builtin_amdgcn_s_setprio(0); } while (0)
; #define PG8_WAIT_V(n) asm volatile("s_waitcnt vmcnt(" #n ")" ::: "memory")
; #define PG8_WAIT_L(n) asm volatile("s_waitcnt lgkmcnt(" #n ")" ::: "memory")
; #define PG8_BAR __builtin_amdgcn_s_barrier()
; #define PG8_SCHED __builtin_amdgcn_sched_barrier(0)
; template <class Epi, class Sched, bool ALIGN_EPI = false, bool SP2 = false>
; __device__ __forceinline__ void gemm_phase(PG8_LAS unsigned char* lds, const Gemm g, const Sched& S, const Epi& E) {
;     ...
;             PG8_WAIT_V(8); PG8_WAIT_L(0); PG8_BAR; PG8_MMA(1, 0, At, B0); PG8_MMA(1, 1, At, B1); PG8_BAR; PG8_SCHED;
;             PG8_LDB(B0, 1, 0); PG8_LDB(B1, 1, 1); PG8_SCHED; PG8_LDA(At, 1, 0); PG8_STAGE(PG8_SA(0, 1), a2 + hstep, voffA);
;             PG8_WAIT_V(8); PG8_WAIT_L(0); PG8_BAR; PG8_MMA(0, 0, At, B0); PG8_MMA(0, 1, At, B1); PG8_BAR; PG8_SCHED;
	s_setprio 1
	s_waitcnt lgkmcnt(0)
	v_mfma_f32_16x16x32_bf16 v[60:63], v[152:155], v[190:193], v[60:63]
	v_mfma_f32_16x16x32_bf16 v[56:59], v[166:169], v[190:193], v[56:59]
	v_mfma_f32_16x16x32_bf16 v[44:47], v[152:155], v[198:201], v[44:47]
	v_mfma_f32_16x16x32_bf16 v[40:43], v[166:169], v[198:201], v[40:43]
	v_mfma_f32_16x16x32_bf16 v[28:31], v[152:155], v[206:209], v[28:31]
	v_mfma_f32_16x16x32_bf16 v[24:27], v[166:169], v[206:209], v[24:27]
	v_mfma_f32_16x16x32_bf16 v[12:15], v[152:155], v[214:217], v[12:15]
	v_mfma_f32_16x16x32_bf16 v[8:11], v[166:169], v[214:217], v[8:11]
	v_mfma_f32_16x16x32_bf16 v[60:63], v[156:159], v[194:197], v[60:63]
	v_mfma_f32_16x16x32_bf16 v[56:59], v[170:173], v[194:197], v[56:59]
	v_mfma_f32_16x16x32_bf16 v[44:47], v[156:159], v[202:205], v[44:47]
	v_mfma_f32_16x16x32_bf16 v[40:43], v[170:173], v[202:205], v[40:43]
	v_mfma_f32_16x16x32_bf16 v[28:31], v[156:159], v[210:213], v[28:31]
	v_mfma_f32_16x16x32_bf16 v[24:27], v[170:173], v[210:213], v[24:27]
	v_mfma_f32_16x16x32_bf16 v[12:15], v[156:159], v[218:221], v[12:15]
	v_mfma_f32_16x16x32_bf16 v[8:11], v[170:173], v[218:221], v[8:11]
	s_nop 0
	s_nop 0
	v_mfma_f32_16x16x32_bf16 v[52:55], v[174:177], v[190:193], v[52:55]
	v_mfma_f32_16x16x32_bf16 v[48:51], v[182:185], v[190:193], v[48:51]
	v_mfma_f32_16x16x32_bf16 v[36:39], v[174:177], v[198:201], v[36:39]
	v_mfma_f32_16x16x32_bf16 v[32:35], v[182:185], v[198:201], v[32:35]
	v_mfma_f32_16x16x32_bf16 v[20:23], v[174:177], v[206:209], v[20:23]
	v_mfma_f32_16x16x32_bf16 v[16:19], v[182:185], v[206:209], v[16:19]
	v_mfma_f32_16x16x32_bf16 v[4:7], v[174:177], v[214:217], v[4:7]
	v_mfma_f32_16x16x32_bf16 v[0:3], v[182:185], v[214:217], v[0:3]
	v_mfma_f32_16x16x32_bf16 v[52:55], v[178:181], v[194:197], v[52:55]
	v_mfma_f32_16x16x32_bf16 v[48:51], v[186:189], v[194:197], v[48:51]
	v_mfma_f32_16x16x32_bf16 v[36:39], v[178:181], v[202:205], v[36:39]
	v_mfma_f32_16x16x32_bf16 v[32:35], v[186:189], v[202:205], v[32:35]
	v_mfma_f32_16x16x32_bf16 v[20:23], v[178:181], v[210:213], v[20:23]
	v_mfma_f32_16x16x32_bf16 v[16:19], v[186:189], v[210:213], v[16:19]
	v_mfma_f32_16x16x32_bf16 v[4:7], v[178:181], v[218:221], v[4:7]
	v_mfma_f32_16x16x32_bf16 v[0:3], v[186:189], v[218:221], v[0:3]
	s_setprio 0
	s_barrier
	s_add_i32 s42, 0, 0x18000
	s_add_i32 s43, 0, 0x1c000
	s_add_u32 s36, s36, 0x40000
	s_addc_u32 s37, s37, 0
	s_mov_b32 m0, s50
	v_lshl_add_u64 v[228:229], s[36:37], 0, v[128:129]
	global_load_lds_dwordx4 v[228:229], off
	v_lshl_add_u64 v[228:229], s[36:37], 0, v[132:133]
	s_mov_b32 m0, s51
	v_add_u32_e32 v136, s42, v149
	global_load_lds_dwordx4 v[228:229], off
	ds_read_b128 v[152:155], v136
	ds_read_b128 v[156:159], v136 offset:1024
	ds_read_b128 v[166:169], v136 offset:2048
	ds_read_b128 v[170:173], v136 offset:3072
	v_add_u32_e32 v136, s43, v149
	ds_read_b128 v[174:177], v136
	ds_read_b128 v[178:181], v136 offset:1024
	ds_read_b128 v[182:185], v136 offset:2048
	ds_read_b128 v[186:189], v136 offset:3072
	ds_read_b128 v[190:193], v164 offset:32768
	ds_read_b128 v[194:197], v164 offset:33792
	ds_read_b128 v[198:201], v164 offset:34816
	ds_read_b128 v[202:205], v164 offset:35840
	ds_read_b128 v[206:209], v164 offset:36864
	ds_read_b128 v[210:213], v164 offset:37888
	ds_read_b128 v[214:217], v164 offset:38912
	ds_read_b128 v[218:221], v164 offset:39936
	s_waitcnt vmcnt(8)
	s_waitcnt lgkmcnt(0)
	s_barrier
	s_setprio 1
	s_waitcnt lgkmcnt(0)
	v_mfma_f32_16x16x32_bf16 v[124:127], v[152:155], v[190:193], v[124:127]
	v_mfma_f32_16x16x32_bf16 v[120:123], v[166:169], v[190:193], v[120:123]
	v_mfma_f32_16x16x32_bf16 v[108:111], v[152:155], v[198:201], v[108:111]
	v_mfma_f32_16x16x32_bf16 v[104:107], v[166:169], v[198:201], v[104:107]
	v_mfma_f32_16x16x32_bf16 v[92:95], v[152:155], v[206:209], v[92:95]
	v_mfma_f32_16x16x32_bf16 v[88:91], v[166:169], v[206:209], v[88:91]
	v_mfma_f32_16x16x32_bf16 v[76:79], v[152:155], v[214:217], v[76:79]
	v_mfma_f32_16x16x32_bf16 v[72:75], v[166:169], v[214:217], v[72:75]
	v_mfma_f32_16x16x32_bf16 v[124:127], v[156:159], v[194:197], v[124:127]
	v_mfma_f32_16x16x32_bf16 v[120:123], v[170:173], v[194:197], v[120:123]
	v_mfma_f32_16x16x32_bf16 v[108:111], v[156:159], v[202:205], v[108:111]
	v_mfma_f32_16x16x32_bf16 v[104:107], v[170:173], v[202:205], v[104:107]
	v_mfma_f32_16x16x32_bf16 v[92:95], v[156:159], v[210:213], v[92:95]
	v_mfma_f32_16x16x32_bf16 v[88:91], v[170:173], v[210:213], v[88:91]
	v_mfma_f32_16x16x32_bf16 v[76:79], v[156:159], v[218:221], v[76:79]
	v_mfma_f32_16x16x32_bf16 v[72:75], v[170:173], v[218:221], v[72:75]
	s_nop 0
	s_nop 0
	v_mfma_f32_16x16x32_bf16 v[116:119], v[174:177], v[190:193], v[116:119]
	v_mfma_f32_16x16x32_bf16 v[112:115], v[182:185], v[190:193], v[112:115]
	v_mfma_f32_16x16x32_bf16 v[100:103], v[174:177], v[198:201], v[100:103]
	v_mfma_f32_16x16x32_bf16 v[96:99], v[182:185], v[198:201], v[96:99]
	v_mfma_f32_16x16x32_bf16 v[84:87], v[174:177], v[206:209], v[84:87]
	v_mfma_f32_16x16x32_bf16 v[80:83], v[182:185], v[206:209], v[80:83]
	v_mfma_f32_16x16x32_bf16 v[68:71], v[174:177], v[214:217], v[68:71]
	v_mfma_f32_16x16x32_bf16 v[64:67], v[182:185], v[214:217], v[64:67]
	v_mfma_f32_16x16x32_bf16 v[116:119], v[178:181], v[194:197], v[116:119]
	v_mfma_f32_16x16x32_bf16 v[112:115], v[186:189], v[194:197], v[112:115]
	v_mfma_f32_16x16x32_bf16 v[100:103], v[178:181], v[202:205], v[100:103]
	v_mfma_f32_16x16x32_bf16 v[96:99], v[186:189], v[202:205], v[96:99]
	v_mfma_f32_16x16x32_bf16 v[84:87], v[178:181], v[210:213], v[84:87]
	v_mfma_f32_16x16x32_bf16 v[80:83], v[186:189], v[210:213], v[80:83]
	v_mfma_f32_16x16x32_bf16 v[68:71], v[178:181], v[218:221], v[68:71]
	v_mfma_f32_16x16x32_bf16 v[64:67], v[186:189], v[218:221], v[64:67]
	s_setprio 0
	s_barrier
; #define PG8_STAGE(bufoff, gbase, voff) do { _Pragma("unroll") for (int _i = 0; _i < 2; ++_i) \
;         __builtin_amdgcn_global_load_lds((const unsigned*)((const char*)(gbase) + (voff)[_i]), (PG8_LAS unsigned*)(lds + (bufoff) + ldsw + _i * 8192), 16, 0, 0); } while (0)
; #define PG8_LDA(dst, b, h) do { _Pragma("unroll") for (int m = 0; m < 4; ++m) _Pragma("unroll") for (int k = 0; k < 2; ++k) dst[m][k] = *(const PG8_LAS bf16x8*)(lds + PG8_SA(b, h) + aoff + m * 2048 + k * 1024); } while (0)
; #define PG8_MMA(ai, bj, At, Bt) do { __builtin_amdgcn_s_setprio(1); _Pragma("unroll") for (int m = 0; m < 4; ++m) _Pragma("unroll") for (int n = 0; n < 2; ++n) _Pragma("unroll") for (int k = 0; k < 2; ++k) \
;         acc[ai][bj][m][n] = __builtin_amdgcn_mfma_f32_16x16x32_bf16(Bt[n][k], At[m][k], acc[ai][bj][m][n], 0, 0, 0); __builtin_amdgcn_s_setprio(0); } while (0)
; #define PG8_WAIT_V(n) asm volatile("s_waitcnt vmcnt(" #n ")" ::: "memory")
; #define PG8_WAIT_L(n) asm volatile("s_waitcnt lgkmcnt(" #n ")" ::: "memory")
; #define PG8_BAR __builtin_amdgcn_s_barrier()
; #define PG8_SCHED __builtin_amdgcn_sched_barrier(0)
; template <class Epi, class Sched, bool ALIGN_EPI = false, bool SP2 = false>
; __device__ __forceinline__ void gemm_phase(PG8_LAS unsigned char* lds, const Gemm g, const Sched& S, const Epi& E) {
;     ...
;             PG8_LDA(At, 1, 1); PG8_STAGE(PG8_SB(1, 0), b3, voffB); PG8_STAGE(PG8_SB(1, 1), b3 + hstep, voffB); PG8_STAGE(PG8_SA(1, 0), a3, voffA);
;             PG8_WAIT_V(8); PG8_WAIT_L(0); PG8_BAR; PG8_MMA(1, 0, At, B0); PG8_MMA(1, 1, At, B1); PG8_BAR; PG8_SCHED;
;     ...
;         if constexpr (ALIGN_EPI) { if (wr == 0) PG8_BAR; }
	s_add_i32 s36, s42, s62
	v_lshl_add_u64 v[160:161], v[160:161], 0, s[16:17]
	s_mov_b32 m0, s36
	ds_read_b128 v[190:193], v164 offset:49152
	global_load_lds_dwordx4 v[160:161], off
	s_add_i32 m0, s36, 0x2000
	s_add_u32 s28, s28, 0x40080
	v_lshl_add_u64 v[160:161], v[222:223], 0, s[16:17]
	s_addc_u32 s29, s29, 0
	s_add_i32 s36, s43, s62
	global_load_lds_dwordx4 v[160:161], off
	v_lshl_add_u64 v[160:161], s[28:29], 0, v[130:131]
	s_mov_b32 m0, s36
	ds_read_b128 v[194:197], v164 offset:50176
	global_load_lds_dwordx4 v[160:161], off
	v_lshl_add_u64 v[160:161], s[28:29], 0, v[134:135]
	s_add_i32 m0, s36, 0x2000
	ds_read_b128 v[198:201], v164 offset:51200
	global_load_lds_dwordx4 v[160:161], off
	v_lshl_add_u64 v[160:161], v[224:225], 0, s[16:17]
	s_mov_b32 m0, s69
	ds_read_b128 v[202:205], v164 offset:52224
	global_load_lds_dwordx4 v[160:161], off
	v_lshl_add_u64 v[160:161], v[226:227], 0, s[16:17]
	s_mov_b32 m0, s70
	ds_read_b128 v[206:209], v164 offset:53248
	global_load_lds_dwordx4 v[160:161], off
	ds_read_b128 v[210:213], v164 offset:54272
	ds_read_b128 v[214:217], v164 offset:55296
	ds_read_b128 v[218:221], v164 offset:56320
	s_waitcnt vmcnt(8)
	s_waitcnt lgkmcnt(0)
	s_barrier
	s_setprio 1
	s_waitcnt lgkmcnt(0)
	v_mfma_f32_16x16x32_bf16 v[60:63], v[152:155], v[190:193], v[60:63]
	v_mfma_f32_16x16x32_bf16 v[56:59], v[166:169], v[190:193], v[56:59]
	v_mfma_f32_16x16x32_bf16 v[44:47], v[152:155], v[198:201], v[44:47]
	v_mfma_f32_16x16x32_bf16 v[40:43], v[166:169], v[198:201], v[40:43]
	v_mfma_f32_16x16x32_bf16 v[28:31], v[152:155], v[206:209], v[28:31]
	v_mfma_f32_16x16x32_bf16 v[24:27], v[166:169], v[206:209], v[24:27]
	v_mfma_f32_16x16x32_bf16 v[12:15], v[152:155], v[214:217], v[12:15]
	v_mfma_f32_16x16x32_bf16 v[8:11], v[166:169], v[214:217], v[8:11]
	v_mfma_f32_16x16x32_bf16 v[60:63], v[156:159], v[194:197], v[60:63]
	v_mfma_f32_16x16x32_bf16 v[56:59], v[170:173], v[194:197], v[56:59]
	v_mfma_f32_16x16x32_bf16 v[44:47], v[156:159], v[202:205], v[44:47]
	v_mfma_f32_16x16x32_bf16 v[40:43], v[170:173], v[202:205], v[40:43]
	v_mfma_f32_16x16x32_bf16 v[28:31], v[156:159], v[210:213], v[28:31]
	v_mfma_f32_16x16x32_bf16 v[24:27], v[170:173], v[210:213], v[24:27]
	v_mfma_f32_16x16x32_bf16 v[12:15], v[156:159], v[218:221], v[12:15]
	v_mfma_f32_16x16x32_bf16 v[8:11], v[170:173], v[218:221], v[8:11]
	s_nop 0
	s_nop 0
	v_mfma_f32_16x16x32_bf16 v[52:55], v[174:177], v[190:193], v[52:55]
	v_mfma_f32_16x16x32_bf16 v[48:51], v[182:185], v[190:193], v[48:51]
	v_mfma_f32_16x16x32_bf16 v[36:39], v[174:177], v[198:201], v[36:39]
	v_mfma_f32_16x16x32_bf16 v[32:35], v[182:185], v[198:201], v[32:35]
	v_mfma_f32_16x16x32_bf16 v[20:23], v[174:177], v[206:209], v[20:23]
	v_mfma_f32_16x16x32_bf16 v[16:19], v[182:185], v[206:209], v[16:19]
	v_mfma_f32_16x16x32_bf16 v[4:7], v[174:177], v[214:217], v[4:7]
	v_mfma_f32_16x16x32_bf16 v[0:3], v[182:185], v[214:217], v[0:3]
	v_mfma_f32_16x16x32_bf16 v[52:55], v[178:181], v[194:197], v[52:55]
	v_mfma_f32_16x16x32_bf16 v[48:51], v[186:189], v[194:197], v[48:51]
	v_mfma_f32_16x16x32_bf16 v[36:39], v[178:181], v[202:205], v[36:39]
	v_mfma_f32_16x16x32_bf16 v[32:35], v[186:189], v[202:205], v[32:35]
	v_mfma_f32_16x16x32_bf16 v[20:23], v[178:181], v[210:213], v[20:23]
	v_mfma_f32_16x16x32_bf16 v[16:19], v[186:189], v[210:213], v[16:19]
	v_mfma_f32_16x16x32_bf16 v[4:7], v[178:181], v[218:221], v[4:7]
	v_mfma_f32_16x16x32_bf16 v[0:3], v[186:189], v[218:221], v[0:3]
	s_setprio 0
	s_barrier
	s_add_i32 s39, s39, 2
	s_add_u32 s8, s8, 0x100
	s_addc_u32 s9, s9, 0
	s_add_u32 s23, s23, 0x100
	s_addc_u32 s38, s38, 0
	s_cmp_gt_u32 s39, 13
	s_cbranch_scc0 .LBB0_427
	s_nop 0
	s_nop 0
	s_nop 0
	s_nop 0
	s_nop 0
	s_nop 0
	s_nop 0
	s_nop 0
	s_nop 0
	s_and_b64 vcc, exec, s[18:19]
	s_cbranch_vccz .LBB0_430
	s_barrier

; #define PG8_STAGE(bufoff, gbase, voff) do { _Pragma("unroll") for (int _i = 0; _i < 2; ++_i) \
;         __builtin_amdgcn_global_load_lds((const unsigned*)((const char*)(gbase) + (voff)[_i]), (PG8_LAS unsigned*)(lds + (bufoff) + ldsw + _i * 8192), 16, 0, 0); } while (0)
; #define PG8_LDA(dst, b, h) do { _Pragma("unroll") for (int m = 0; m < 4; ++m) _Pragma("unroll") for (int k = 0; k < 2; ++k) dst[m][k] = *(const PG8_LAS bf16x8*)(lds + PG8_SA(b, h) + aoff + m * 2048 + k * 1024); } while (0)
; #define PG8_LDB(dst, b, h) do { _Pragma("unroll") for (int n = 0; n < 2; ++n) _Pragma("unroll") for (int k = 0; k < 2; ++k) dst[n][k] = *(const PG8_LAS bf16x8*)(lds + PG8_SB(b, h) + boff + n * 2048 + k * 1024); } while (0)
; #define PG8_MMA(ai, bj, At, Bt) do { __builtin_amdgcn_s_setprio(1); _Pragma("unroll") for (int m = 0; m < 4; ++m) _Pragma("unroll") for (int n = 0; n < 2; ++n) _Pragma("unroll") for (int k = 0; k < 2; ++k) \
;         acc[ai][bj][m][n] = __builtin_amdgcn_mfma_f32_16x16x32_bf16(Bt[n][k], At[m][k], acc[ai][bj][m][n], 0, 0, 0); __builtin_amdgcn_s_setprio(0); } while (0)
; #define PG8_WAIT_V(n) asm volatile("s_waitcnt vmcnt(" #n ")" ::: "memory")
; #define PG8_WAIT_L(n) asm volatile("s_waitcnt lgkmcnt(" #n ")" ::: "memory")
; template <class Epi, class Sched, bool ALIGN_EPI = false, bool SP2 = false>
; __device__ __forceinline__ void gemm_phase(PG8_LAS unsigned char* lds, const Gemm g, const Sched& S, const Epi& E) {
;     ...
;             const bool last = (t == nt - 2);
;             const char* a1 = cA + (size_t)(t + 1) * kstep;
;             const char* a2 = last ? nA : cA + (size_t)(t + 2) * kstep; const char* b2 = last ? nB : cB + (size_t)(t + 2) * kstep;
;             const char* a3 = a2 + kstep; const char* b3 = b2 + kstep;
;             if (last && has_next) S.a_ready(nxt);
;             if constexpr (SP2) {
;             PG8_LDB(B0, 0, 0); PG8_LDB(B1, 0, 1); PG8_SCHED; PG8_LDA(At, 0, 0); PG8_STAGE(PG8_SA(1, 1), a1 + hstep, voffA);
;             PG8_WAIT_V(8); PG8_WAIT_L(0); PG8_BAR; PG8_MMA(0, 0, At, B0); PG8_MMA(0, 1, At, B1); PG8_BAR; PG8_SCHED;
;             PG8_LDA(At, 0, 1); PG8_STAGE(PG8_SB(0, 0), b2, voffB); PG8_STAGE(PG8_SB(0, 1), b2 + hstep, voffB); PG8_STAGE(PG8_SA(0, 0), a2, voffA);
;             PG8_WAIT_V(8); PG8_WAIT_L(0); PG8_BAR; PG8_MMA(1, 0, At, B0); PG8_MMA(1, 1, At, B1); PG8_BAR; PG8_SCHED;
.LBB0_1247:
	s_add_u32 s6, s4, 0xfffc0080
	s_addc_u32 s7, s5, -1
	s_cmp_eq_u32 s56, 12
	s_cselect_b32 s9, s10, s7
	s_cselect_b32 s8, s11, s6
	s_cselect_b32 s7, s27, s53
	s_cselect_b32 s6, s29, s52
	v_lshl_add_u64 v[154:155], s[4:5], 0, v[136:137]
	s_add_i32 m0, s40, 0xc000
	ds_read_b128 v[144:147], v163
	global_load_lds_dwordx4 v[154:155], off
	v_lshl_add_u64 v[154:155], s[4:5], 0, v[138:139]
	s_add_i32 m0, s40, 0xe000
	ds_read_b128 v[174:177], v163 offset:1024
	global_load_lds_dwordx4 v[154:155], off
	ds_read_b128 v[178:181], v163 offset:2048
	ds_read_b128 v[182:185], v163 offset:3072
	ds_read_b128 v[186:189], v170
	ds_read_b128 v[190:193], v170 offset:1024
	ds_read_b128 v[194:197], v170 offset:2048
	ds_read_b128 v[198:201], v170 offset:3072
	ds_read_b128 v[202:205], v171
	ds_read_b128 v[206:209], v171 offset:1024
	ds_read_b128 v[210:213], v171 offset:2048
	ds_read_b128 v[214:217], v171 offset:3072
	ds_read_b128 v[218:221], v171 offset:4096
	ds_read_b128 v[222:225], v171 offset:5120
	ds_read_b128 v[226:229], v171 offset:6144
	ds_read_b128 v[230:233], v171 offset:7168
	s_waitcnt vmcnt(8)
	s_waitcnt lgkmcnt(0)
	s_barrier
	s_setprio 1
	s_waitcnt lgkmcnt(0)
	v_mfma_f32_16x16x32_bf16 v[124:127], v[144:147], v[202:205], v[124:127]
	v_mfma_f32_16x16x32_bf16 v[120:123], v[178:181], v[202:205], v[120:123]
	v_mfma_f32_16x16x32_bf16 v[108:111], v[144:147], v[210:213], v[108:111]
	v_mfma_f32_16x16x32_bf16 v[104:107], v[178:181], v[210:213], v[104:107]
	v_mfma_f32_16x16x32_bf16 v[92:95], v[144:147], v[218:221], v[92:95]
	v_mfma_f32_16x16x32_bf16 v[88:91], v[178:181], v[218:221], v[88:91]
	v_mfma_f32_16x16x32_bf16 v[76:79], v[144:147], v[226:229], v[76:79]
	v_mfma_f32_16x16x32_bf16 v[72:75], v[178:181], v[226:229], v[72:75]
	v_mfma_f32_16x16x32_bf16 v[124:127], v[174:177], v[206:209], v[124:127]
	v_mfma_f32_16x16x32_bf16 v[120:123], v[182:185], v[206:209], v[120:123]
	v_mfma_f32_16x16x32_bf16 v[108:111], v[174:177], v[214:217], v[108:111]
	v_mfma_f32_16x16x32_bf16 v[104:107], v[182:185], v[214:217], v[104:107]
	v_mfma_f32_16x16x32_bf16 v[92:95], v[174:177], v[222:225], v[92:95]
	v_mfma_f32_16x16x32_bf16 v[88:91], v[182:185], v[222:225], v[88:91]
	v_mfma_f32_16x16x32_bf16 v[76:79], v[174:177], v[230:233], v[76:79]
	v_mfma_f32_16x16x32_bf16 v[72:75], v[182:185], v[230:233], v[72:75]
	s_nop 0
	s_nop 0
	v_mfma_f32_16x16x32_bf16 v[116:119], v[186:189], v[202:205], v[116:119]
	v_mfma_f32_16x16x32_bf16 v[112:115], v[194:197], v[202:205], v[112:115]
	v_mfma_f32_16x16x32_bf16 v[100:103], v[186:189], v[210:213], v[100:103]
	v_mfma_f32_16x16x32_bf16 v[96:99], v[194:197], v[210:213], v[96:99]
	v_mfma_f32_16x16x32_bf16 v[84:87], v[186:189], v[218:221], v[84:87]
	v_mfma_f32_16x16x32_bf16 v[80:83], v[194:197], v[218:221], v[80:83]
	v_mfma_f32_16x16x32_bf16 v[68:71], v[186:189], v[226:229], v[68:71]
	v_mfma_f32_16x16x32_bf16 v[64:67], v[194:197], v[226:229], v[64:67]
	v_mfma_f32_16x16x32_bf16 v[116:119], v[190:193], v[206:209], v[116:119]
	v_mfma_f32_16x16x32_bf16 v[112:115], v[198:201], v[206:209], v[112:115]
	v_mfma_f32_16x16x32_bf16 v[100:103], v[190:193], v[214:217], v[100:103]
	v_mfma_f32_16x16x32_bf16 v[96:99], v[198:201], v[214:217], v[96:99]
	v_mfma_f32_16x16x32_bf16 v[84:87], v[190:193], v[222:225], v[84:87]
	v_mfma_f32_16x16x32_bf16 v[80:83], v[198:201], v[222:225], v[80:83]
	v_mfma_f32_16x16x32_bf16 v[68:71], v[190:193], v[230:233], v[68:71]
	v_mfma_f32_16x16x32_bf16 v[64:67], v[198:201], v[230:233], v[64:67]
	s_setprio 0
	s_barrier
	s_add_i32 s57, s60, s39
	v_lshl_add_u64 v[154:155], s[6:7], 0, v[130:131]
	s_mov_b32 m0, s57
	v_lshl_add_u64 v[234:235], s[6:7], 0, v[134:135]
	global_load_lds_dwordx4 v[154:155], off
	s_add_i32 m0, s57, 0x2000
	s_add_u32 s70, s6, 0x40000
	s_addc_u32 s71, s7, 0
	s_add_i32 s57, s61, s39
	global_load_lds_dwordx4 v[234:235], off
	v_lshl_add_u64 v[236:237], s[70:71], 0, v[130:131]
	s_mov_b32 m0, s57
	v_lshl_add_u64 v[238:239], s[8:9], 0, v[132:133]
	global_load_lds_dwordx4 v[236:237], off
	v_lshl_add_u64 v[236:237], s[70:71], 0, v[134:135]
	s_add_i32 m0, s57, 0x2000
	ds_read_b128 v[202:205], v171 offset:16384
	global_load_lds_dwordx4 v[236:237], off
	v_lshl_add_u64 v[236:237], s[8:9], 0, v[128:129]
	s_mov_b32 m0, s40
	ds_read_b128 v[206:209], v171 offset:17408
	global_load_lds_dwordx4 v[236:237], off
	s_mov_b32 m0, s41
	ds_read_b128 v[210:213], v171 offset:18432
	global_load_lds_dwordx4 v[238:239], off
	ds_read_b128 v[214:217], v171 offset:19456
	ds_read_b128 v[218:221], v171 offset:20480
	ds_read_b128 v[222:225], v171 offset:21504
	ds_read_b128 v[226:229], v171 offset:22528
	ds_read_b128 v[230:233], v171 offset:23552
	s_waitcnt vmcnt(8)
	s_waitcnt lgkmcnt(0)
	s_barrier
; #define PG8_STAGE(bufoff, gbase, voff) do { _Pragma("unroll") for (int _i = 0; _i < 2; ++_i) \
;         __builtin_amdgcn_global_load_lds((const unsigned*)((const char*)(gbase) + (voff)[_i]), (PG8_LAS unsigned*)(lds + (bufoff) + ldsw + _i * 8192), 16, 0, 0); } while (0)
; #define PG8_LDA(dst, b, h) do { _Pragma("unroll") for (int m = 0; m < 4; ++m) _Pragma("unroll") for (int k = 0; k < 2; ++k) dst[m][k] = *(const PG8_LAS bf16x8*)(lds + PG8_SA(b, h) + aoff + m * 2048 + k * 1024); } while (0)
; #define PG8_LDB(dst, b, h) do { _Pragma("unroll") for (int n = 0; n < 2; ++n) _Pragma("unroll") for (int k = 0; k < 2; ++k) dst[n][k] = *(const PG8_LAS bf16x8*)(lds + PG8_SB(b, h) + boff + n * 2048 + k * 1024); } while (0)
; #define PG8_MMA(ai, bj, At, Bt) do { __builtin_amdgcn_s_setprio(1); _Pragma("unroll") for (int m = 0; m < 4; ++m) _Pragma("unroll") for (int n = 0; n < 2; ++n) _Pragma("unroll") for (int k = 0; k < 2; ++k) \
;         acc[ai][bj][m][n] = __builtin_amdgcn_mfma_f32_16x16x32_bf16(Bt[n][k], At[m][k], acc[ai][bj][m][n], 0, 0, 0); __builtin_amdgcn_s_setprio(0); } while (0)
; #define PG8_WAIT_V(n) asm volatile("s_waitcnt vmcnt(" #n ")" ::: "memory")
; #define PG8_WAIT_L(n) asm volatile("s_waitcnt lgkmcnt(" #n ")" ::: "memory")
; #define PG8_BAR __builtin_amdgcn_s_barrier()
; #define PG8_SCHED __builtin_amdgcn_sched_barrier(0)
; template <class Epi, class Sched, bool ALIGN_EPI = false, bool SP2 = false>
; __device__ __forceinline__ void gemm_phase(PG8_LAS unsigned char* lds, const Gemm g, const Sched& S, const Epi& E) {
;     ...
;             PG8_WAIT_V(8); PG8_WAIT_L(0); PG8_BAR; PG8_MMA(1, 0, At, B0); PG8_MMA(1, 1, At, B1); PG8_BAR; PG8_SCHED;
;             PG8_LDB(B0, 1, 0); PG8_LDB(B1, 1, 1); PG8_SCHED; PG8_LDA(At, 1, 0); PG8_STAGE(PG8_SA(0, 1), a2 + hstep, voffA);
;             PG8_WAIT_V(8); PG8_WAIT_L(0); PG8_BAR; PG8_MMA(0, 0, At, B0); PG8_MMA(0, 1, At, B1); PG8_BAR; PG8_SCHED;
	s_setprio 1
	s_waitcnt lgkmcnt(0)
	v_mfma_f32_16x16x32_bf16 v[60:63], v[144:147], v[202:205], v[60:63]
	v_mfma_f32_16x16x32_bf16 v[56:59], v[178:181], v[202:205], v[56:59]
	v_mfma_f32_16x16x32_bf16 v[44:47], v[144:147], v[210:213], v[44:47]
	v_mfma_f32_16x16x32_bf16 v[40:43], v[178:181], v[210:213], v[40:43]
	v_mfma_f32_16x16x32_bf16 v[28:31], v[144:147], v[218:221], v[28:31]
	v_mfma_f32_16x16x32_bf16 v[24:27], v[178:181], v[218:221], v[24:27]
	v_mfma_f32_16x16x32_bf16 v[12:15], v[144:147], v[226:229], v[12:15]
	v_mfma_f32_16x16x32_bf16 v[8:11], v[178:181], v[226:229], v[8:11]
	v_mfma_f32_16x16x32_bf16 v[60:63], v[174:177], v[206:209], v[60:63]
	v_mfma_f32_16x16x32_bf16 v[56:59], v[182:185], v[206:209], v[56:59]
	v_mfma_f32_16x16x32_bf16 v[44:47], v[174:177], v[214:217], v[44:47]
	v_mfma_f32_16x16x32_bf16 v[40:43], v[182:185], v[214:217], v[40:43]
	v_mfma_f32_16x16x32_bf16 v[28:31], v[174:177], v[222:225], v[28:31]
	v_mfma_f32_16x16x32_bf16 v[24:27], v[182:185], v[222:225], v[24:27]
	v_mfma_f32_16x16x32_bf16 v[12:15], v[174:177], v[230:233], v[12:15]
	v_mfma_f32_16x16x32_bf16 v[8:11], v[182:185], v[230:233], v[8:11]
	s_nop 0
	s_nop 0
	v_mfma_f32_16x16x32_bf16 v[52:55], v[186:189], v[202:205], v[52:55]
	v_mfma_f32_16x16x32_bf16 v[48:51], v[194:197], v[202:205], v[48:51]
	v_mfma_f32_16x16x32_bf16 v[36:39], v[186:189], v[210:213], v[36:39]
	v_mfma_f32_16x16x32_bf16 v[32:35], v[194:197], v[210:213], v[32:35]
	v_mfma_f32_16x16x32_bf16 v[20:23], v[186:189], v[218:221], v[20:23]
	v_mfma_f32_16x16x32_bf16 v[16:19], v[194:197], v[218:221], v[16:19]
	v_mfma_f32_16x16x32_bf16 v[4:7], v[186:189], v[226:229], v[4:7]
	v_mfma_f32_16x16x32_bf16 v[0:3], v[194:197], v[226:229], v[0:3]
	v_mfma_f32_16x16x32_bf16 v[52:55], v[190:193], v[206:209], v[52:55]
	v_mfma_f32_16x16x32_bf16 v[48:51], v[198:201], v[206:209], v[48:51]
	v_mfma_f32_16x16x32_bf16 v[36:39], v[190:193], v[214:217], v[36:39]
	v_mfma_f32_16x16x32_bf16 v[32:35], v[198:201], v[214:217], v[32:35]
	v_mfma_f32_16x16x32_bf16 v[20:23], v[190:193], v[222:225], v[20:23]
	v_mfma_f32_16x16x32_bf16 v[16:19], v[198:201], v[222:225], v[16:19]
	v_mfma_f32_16x16x32_bf16 v[4:7], v[190:193], v[230:233], v[4:7]
	v_mfma_f32_16x16x32_bf16 v[0:3], v[198:201], v[230:233], v[0:3]
	s_setprio 0
	s_barrier
	s_add_i32 s57, 0, 0x18000
	s_add_i32 s69, 0, 0x1c000
	s_add_u32 s8, s8, 0x40000
	s_addc_u32 s9, s9, 0
	s_mov_b32 m0, s42
	v_lshl_add_u64 v[240:241], s[8:9], 0, v[128:129]
	global_load_lds_dwordx4 v[240:241], off
	v_lshl_add_u64 v[240:241], s[8:9], 0, v[132:133]
	s_mov_b32 m0, s43
	v_add_u32_e32 v152, s57, v161
	global_load_lds_dwordx4 v[240:241], off
	ds_read_b128 v[144:147], v152
	ds_read_b128 v[174:177], v152 offset:1024
	ds_read_b128 v[178:181], v152 offset:2048
	ds_read_b128 v[182:185], v152 offset:3072
	v_add_u32_e32 v152, s69, v161
	ds_read_b128 v[186:189], v152
	ds_read_b128 v[190:193], v152 offset:1024
	ds_read_b128 v[194:197], v152 offset:2048
	ds_read_b128 v[198:201], v152 offset:3072
	ds_read_b128 v[202:205], v171 offset:32768
	ds_read_b128 v[206:209], v171 offset:33792
	ds_read_b128 v[210:213], v171 offset:34816
	ds_read_b128 v[214:217], v171 offset:35840
	ds_read_b128 v[218:221], v171 offset:36864
	ds_read_b128 v[222:225], v171 offset:37888
	ds_read_b128 v[226:229], v171 offset:38912
	ds_read_b128 v[230:233], v171 offset:39936
	s_waitcnt vmcnt(8)
	s_waitcnt lgkmcnt(0)
	s_barrier
	s_setprio 1
	s_waitcnt lgkmcnt(0)
	v_mfma_f32_16x16x32_bf16 v[124:127], v[144:147], v[202:205], v[124:127]
	v_mfma_f32_16x16x32_bf16 v[120:123], v[178:181], v[202:205], v[120:123]
	v_mfma_f32_16x16x32_bf16 v[108:111], v[144:147], v[210:213], v[108:111]
	v_mfma_f32_16x16x32_bf16 v[104:107], v[178:181], v[210:213], v[104:107]
	v_mfma_f32_16x16x32_bf16 v[92:95], v[144:147], v[218:221], v[92:95]
	v_mfma_f32_16x16x32_bf16 v[88:91], v[178:181], v[218:221], v[88:91]
	v_mfma_f32_16x16x32_bf16 v[76:79], v[144:147], v[226:229], v[76:79]
	v_mfma_f32_16x16x32_bf16 v[72:75], v[178:181], v[226:229], v[72:75]
	v_mfma_f32_16x16x32_bf16 v[124:127], v[174:177], v[206:209], v[124:127]
	v_mfma_f32_16x16x32_bf16 v[120:123], v[182:185], v[206:209], v[120:123]
	v_mfma_f32_16x16x32_bf16 v[108:111], v[174:177], v[214:217], v[108:111]
	v_mfma_f32_16x16x32_bf16 v[104:107], v[182:185], v[214:217], v[104:107]
	v_mfma_f32_16x16x32_bf16 v[92:95], v[174:177], v[222:225], v[92:95]
	v_mfma_f32_16x16x32_bf16 v[88:91], v[182:185], v[222:225], v[88:91]
	v_mfma_f32_16x16x32_bf16 v[76:79], v[174:177], v[230:233], v[76:79]
	v_mfma_f32_16x16x32_bf16 v[72:75], v[182:185], v[230:233], v[72:75]
	s_nop 0
	s_nop 0
	v_mfma_f32_16x16x32_bf16 v[116:119], v[186:189], v[202:205], v[116:119]
	v_mfma_f32_16x16x32_bf16 v[112:115], v[194:197], v[202:205], v[112:115]
	v_mfma_f32_16x16x32_bf16 v[100:103], v[186:189], v[210:213], v[100:103]
	v_mfma_f32_16x16x32_bf16 v[96:99], v[194:197], v[210:213], v[96:99]
	v_mfma_f32_16x16x32_bf16 v[84:87], v[186:189], v[218:221], v[84:87]
	v_mfma_f32_16x16x32_bf16 v[80:83], v[194:197], v[218:221], v[80:83]
	v_mfma_f32_16x16x32_bf16 v[68:71], v[186:189], v[226:229], v[68:71]
	v_mfma_f32_16x16x32_bf16 v[64:67], v[194:197], v[226:229], v[64:67]
	v_mfma_f32_16x16x32_bf16 v[116:119], v[190:193], v[206:209], v[116:119]
	v_mfma_f32_16x16x32_bf16 v[112:115], v[198:201], v[206:209], v[112:115]
	v_mfma_f32_16x16x32_bf16 v[100:103], v[190:193], v[214:217], v[100:103]
	v_mfma_f32_16x16x32_bf16 v[96:99], v[198:201], v[214:217], v[96:99]
	v_mfma_f32_16x16x32_bf16 v[84:87], v[190:193], v[222:225], v[84:87]
	v_mfma_f32_16x16x32_bf16 v[80:83], v[198:201], v[222:225], v[80:83]
	v_mfma_f32_16x16x32_bf16 v[68:71], v[190:193], v[230:233], v[68:71]
	v_mfma_f32_16x16x32_bf16 v[64:67], v[198:201], v[230:233], v[64:67]
	s_setprio 0
	s_barrier
; #define PG8_STAGE(bufoff, gbase, voff) do { _Pragma("unroll") for (int _i = 0; _i < 2; ++_i) \
;         __builtin_amdgcn_global_load_lds((const unsigned*)((const char*)(gbase) + (voff)[_i]), (PG8_LAS unsigned*)(lds + (bufoff) + ldsw + _i * 8192), 16, 0, 0); } while (0)
; #define PG8_LDA(dst, b, h) do { _Pragma("unroll") for (int m = 0; m < 4; ++m) _Pragma("unroll") for (int k = 0; k < 2; ++k) dst[m][k] = *(const PG8_LAS bf16x8*)(lds + PG8_SA(b, h) + aoff + m * 2048 + k * 1024); } while (0)
; #define PG8_MMA(ai, bj, At, Bt) do { __builtin_amdgcn_s_setprio(1); _Pragma("unroll") for (int m = 0; m < 4; ++m) _Pragma("unroll") for (int n = 0; n < 2; ++n) _Pragma("unroll") for (int k = 0; k < 2; ++k) \
;         acc[ai][bj][m][n] = __builtin_amdgcn_mfma_f32_16x16x32_bf16(Bt[n][k], At[m][k], acc[ai][bj][m][n], 0, 0, 0); __builtin_amdgcn_s_setprio(0); } while (0)
; #define PG8_WAIT_V(n) asm volatile("s_waitcnt vmcnt(" #n ")" ::: "memory")
; #define PG8_WAIT_L(n) asm volatile("s_waitcnt lgkmcnt(" #n ")" ::: "memory")
; #define PG8_BAR __builtin_amdgcn_s_barrier()
; #define PG8_SCHED __builtin_amdgcn_sched_barrier(0)
; template <class Epi, class Sched, bool ALIGN_EPI = false, bool SP2 = false>
; __device__ __forceinline__ void gemm_phase(PG8_LAS unsigned char* lds, const Gemm g, const Sched& S, const Epi& E) {
;     ...
;             PG8_LDA(At, 1, 1); PG8_STAGE(PG8_SB(1, 0), b3, voffB); PG8_STAGE(PG8_SB(1, 1), b3 + hstep, voffB); PG8_STAGE(PG8_SA(1, 0), a3, voffA);
;             PG8_WAIT_V(8); PG8_WAIT_L(0); PG8_BAR; PG8_MMA(1, 0, At, B0); PG8_MMA(1, 1, At, B1); PG8_BAR; PG8_SCHED;
;     ...
;         if constexpr (ALIGN_EPI) { if (wr == 0) PG8_BAR; }
	s_add_i32 s8, s57, s39
	v_lshl_add_u64 v[154:155], v[154:155], 0, s[18:19]
	s_mov_b32 m0, s8
	ds_read_b128 v[202:205], v171 offset:49152
	global_load_lds_dwordx4 v[154:155], off
	s_add_i32 m0, s8, 0x2000
	s_add_u32 s6, s6, 0x40080
	v_lshl_add_u64 v[154:155], v[234:235], 0, s[18:19]
	s_addc_u32 s7, s7, 0
	s_add_i32 s8, s69, s39
	global_load_lds_dwordx4 v[154:155], off
	v_lshl_add_u64 v[154:155], s[6:7], 0, v[130:131]
	s_mov_b32 m0, s8
	ds_read_b128 v[206:209], v171 offset:50176
	global_load_lds_dwordx4 v[154:155], off
	v_lshl_add_u64 v[154:155], s[6:7], 0, v[134:135]
	s_add_i32 m0, s8, 0x2000
	ds_read_b128 v[210:213], v171 offset:51200
	global_load_lds_dwordx4 v[154:155], off
	v_lshl_add_u64 v[154:155], v[236:237], 0, s[18:19]
	s_mov_b32 m0, s45
	ds_read_b128 v[214:217], v171 offset:52224
	global_load_lds_dwordx4 v[154:155], off
	v_lshl_add_u64 v[154:155], v[238:239], 0, s[18:19]
	s_mov_b32 m0, s50
	ds_read_b128 v[218:221], v171 offset:53248
	global_load_lds_dwordx4 v[154:155], off
	ds_read_b128 v[222:225], v171 offset:54272
	ds_read_b128 v[226:229], v171 offset:55296
	ds_read_b128 v[230:233], v171 offset:56320
	s_waitcnt vmcnt(8)
	s_waitcnt lgkmcnt(0)
	s_barrier
	s_setprio 1
	s_waitcnt lgkmcnt(0)
	v_mfma_f32_16x16x32_bf16 v[60:63], v[144:147], v[202:205], v[60:63]
	v_mfma_f32_16x16x32_bf16 v[56:59], v[178:181], v[202:205], v[56:59]
	v_mfma_f32_16x16x32_bf16 v[44:47], v[144:147], v[210:213], v[44:47]
	v_mfma_f32_16x16x32_bf16 v[40:43], v[178:181], v[210:213], v[40:43]
	v_mfma_f32_16x16x32_bf16 v[28:31], v[144:147], v[218:221], v[28:31]
	v_mfma_f32_16x16x32_bf16 v[24:27], v[178:181], v[218:221], v[24:27]
	v_mfma_f32_16x16x32_bf16 v[12:15], v[144:147], v[226:229], v[12:15]
	v_mfma_f32_16x16x32_bf16 v[8:11], v[178:181], v[226:229], v[8:11]
	v_mfma_f32_16x16x32_bf16 v[60:63], v[174:177], v[206:209], v[60:63]
	v_mfma_f32_16x16x32_bf16 v[56:59], v[182:185], v[206:209], v[56:59]
	v_mfma_f32_16x16x32_bf16 v[44:47], v[174:177], v[214:217], v[44:47]
	v_mfma_f32_16x16x32_bf16 v[40:43], v[182:185], v[214:217], v[40:43]
	v_mfma_f32_16x16x32_bf16 v[28:31], v[174:177], v[222:225], v[28:31]
	v_mfma_f32_16x16x32_bf16 v[24:27], v[182:185], v[222:225], v[24:27]
	v_mfma_f32_16x16x32_bf16 v[12:15], v[174:177], v[230:233], v[12:15]
	v_mfma_f32_16x16x32_bf16 v[8:11], v[182:185], v[230:233], v[8:11]
	s_nop 0
	s_nop 0
	v_mfma_f32_16x16x32_bf16 v[52:55], v[186:189], v[202:205], v[52:55]
	v_mfma_f32_16x16x32_bf16 v[48:51], v[194:197], v[202:205], v[48:51]
	v_mfma_f32_16x16x32_bf16 v[36:39], v[186:189], v[210:213], v[36:39]
	v_mfma_f32_16x16x32_bf16 v[32:35], v[194:197], v[210:213], v[32:35]
	v_mfma_f32_16x16x32_bf16 v[20:23], v[186:189], v[218:221], v[20:23]
	v_mfma_f32_16x16x32_bf16 v[16:19], v[194:197], v[218:221], v[16:19]
	v_mfma_f32_16x16x32_bf16 v[4:7], v[186:189], v[226:229], v[4:7]
	v_mfma_f32_16x16x32_bf16 v[0:3], v[194:197], v[226:229], v[0:3]
	v_mfma_f32_16x16x32_bf16 v[52:55], v[190:193], v[206:209], v[52:55]
	v_mfma_f32_16x16x32_bf16 v[48:51], v[198:201], v[206:209], v[48:51]
	v_mfma_f32_16x16x32_bf16 v[36:39], v[190:193], v[214:217], v[36:39]
	v_mfma_f32_16x16x32_bf16 v[32:35], v[198:201], v[214:217], v[32:35]
	v_mfma_f32_16x16x32_bf16 v[20:23], v[190:193], v[222:225], v[20:23]
	v_mfma_f32_16x16x32_bf16 v[16:19], v[198:201], v[222:225], v[16:19]
	v_mfma_f32_16x16x32_bf16 v[4:7], v[190:193], v[230:233], v[4:7]
	v_mfma_f32_16x16x32_bf16 v[0:3], v[198:201], v[230:233], v[0:3]
	s_setprio 0
	s_barrier
	s_add_i32 s56, s56, 2
	s_add_u32 s4, s4, 0x100
	s_addc_u32 s5, s5, 0
	s_add_u32 s52, s52, 0x100
	s_addc_u32 s53, s53, 0
	s_cmp_gt_u32 s56, 13
	s_cbranch_scc0 .LBB0_1247
	s_nop 0
	s_nop 0
	s_nop 0
	s_nop 0
	s_nop 0
	s_nop 0
	s_nop 0
	s_nop 0
	s_nop 0
	s_and_b64 vcc, exec, s[20:21]
	s_cbranch_vccz .LBB0_1250
	s_barrier

; #define PG8_STAGE(bufoff, gbase, voff) do { _Pragma("unroll") for (int _i = 0; _i < 2; ++_i) \
;         __builtin_amdgcn_global_load_lds((const unsigned*)((const char*)(gbase) + (voff)[_i]), (PG8_LAS unsigned*)(lds + (bufoff) + ldsw + _i * 8192), 16, 0, 0); } while (0)
; #define PG8_LDA(dst, b, h) do { _Pragma("unroll") for (int m = 0; m < 4; ++m) _Pragma("unroll") for (int k = 0; k < 2; ++k) dst[m][k] = *(const PG8_LAS bf16x8*)(lds + PG8_SA(b, h) + aoff + m * 2048 + k * 1024); } while (0)
; #define PG8_LDB(dst, b, h) do { _Pragma("unroll") for (int n = 0; n < 2; ++n) _Pragma("unroll") for (int k = 0; k < 2; ++k) dst[n][k] = *(const PG8_LAS bf16x8*)(lds + PG8_SB(b, h) + boff + n * 2048 + k * 1024); } while (0)
; #define PG8_MMA(ai, bj, At, Bt) do { __builtin_amdgcn_s_setprio(1); _Pragma("unroll") for (int m = 0; m < 4; ++m) _Pragma("unroll") for (int n = 0; n < 2; ++n) _Pragma("unroll") for (int k = 0; k < 2; ++k) \
;         acc[ai][bj][m][n] = __builtin_amdgcn_mfma_f32_16x16x32_bf16(Bt[n][k], At[m][k], acc[ai][bj][m][n], 0, 0, 0); __builtin_amdgcn_s_setprio(0); } while (0)
; #define PG8_WAIT_V(n) asm volatile("s_waitcnt vmcnt(" #n ")" ::: "memory")
; #define PG8_WAIT_L(n) asm volatile("s_waitcnt lgkmcnt(" #n ")" ::: "memory")
; template <class Epi, class Sched, bool ALIGN_EPI = false, bool SP2 = false>
; __device__ __forceinline__ void gemm_phase(PG8_LAS unsigned char* lds, const Gemm g, const Sched& S, const Epi& E) {
;     ...
;             const bool last = (t == nt - 2);
;             const char* a1 = cA + (size_t)(t + 1) * kstep;
;             const char* a2 = last ? nA : cA + (size_t)(t + 2) * kstep; const char* b2 = last ? nB : cB + (size_t)(t + 2) * kstep;
;             const char* a3 = a2 + kstep; const char* b3 = b2 + kstep;
;             if (last && has_next) S.a_ready(nxt);
;             if constexpr (SP2) {
;             PG8_LDB(B0, 0, 0); PG8_LDB(B1, 0, 1); PG8_SCHED; PG8_LDA(At, 0, 0); PG8_STAGE(PG8_SA(1, 1), a1 + hstep, voffA);
;             PG8_WAIT_V(8); PG8_WAIT_L(0); PG8_BAR; PG8_MMA(0, 0, At, B0); PG8_MMA(0, 1, At, B1); PG8_BAR; PG8_SCHED;
;             PG8_LDA(At, 0, 1); PG8_STAGE(PG8_SB(0, 0), b2, voffB); PG8_STAGE(PG8_SB(0, 1), b2 + hstep, voffB); PG8_STAGE(PG8_SA(0, 0), a2, voffA);
;             PG8_WAIT_V(8); PG8_WAIT_L(0); PG8_BAR; PG8_MMA(1, 0, At, B0); PG8_MMA(1, 1, At, B1); PG8_BAR; PG8_SCHED;
.LBB0_1271:
	s_add_u32 s30, s28, 0xfffe0080
	s_addc_u32 s31, s29, -1
	s_cmp_eq_u32 s63, 4
	s_cselect_b32 s35, s21, s31
	s_cselect_b32 s34, s56, s30
	s_cselect_b32 s31, s19, s62
	s_cselect_b32 s30, s57, s61
	v_lshl_add_u64 v[160:161], s[28:29], 0, v[144:145]
	s_add_i32 m0, s27, 0xc000
	ds_read_b128 v[156:159], v135
	global_load_lds_dwordx4 v[160:161], off
	v_lshl_add_u64 v[160:161], s[28:29], 0, v[146:147]
	s_add_i32 m0, s27, 0xe000
	ds_read_b128 v[170:173], v135 offset:1024
	global_load_lds_dwordx4 v[160:161], off
	ds_read_b128 v[174:177], v135 offset:2048
	ds_read_b128 v[178:181], v135 offset:3072
	ds_read_b128 v[182:185], v162
	ds_read_b128 v[186:189], v162 offset:1024
	ds_read_b128 v[190:193], v162 offset:2048
	ds_read_b128 v[194:197], v162 offset:3072
	ds_read_b128 v[198:201], v163
	ds_read_b128 v[202:205], v163 offset:1024
	ds_read_b128 v[206:209], v163 offset:2048
	ds_read_b128 v[210:213], v163 offset:3072
	ds_read_b128 v[214:217], v163 offset:4096
	ds_read_b128 v[218:221], v163 offset:5120
	ds_read_b128 v[222:225], v163 offset:6144
	ds_read_b128 v[226:229], v163 offset:7168
	s_waitcnt vmcnt(8)
	s_waitcnt lgkmcnt(0)
	s_barrier
	s_setprio 1
	s_waitcnt lgkmcnt(0)
	v_mfma_f32_16x16x32_bf16 v[124:127], v[156:159], v[198:201], v[124:127]
	v_mfma_f32_16x16x32_bf16 v[120:123], v[174:177], v[198:201], v[120:123]
	v_mfma_f32_16x16x32_bf16 v[108:111], v[156:159], v[206:209], v[108:111]
	v_mfma_f32_16x16x32_bf16 v[104:107], v[174:177], v[206:209], v[104:107]
	v_mfma_f32_16x16x32_bf16 v[92:95], v[156:159], v[214:217], v[92:95]
	v_mfma_f32_16x16x32_bf16 v[88:91], v[174:177], v[214:217], v[88:91]
	v_mfma_f32_16x16x32_bf16 v[76:79], v[156:159], v[222:225], v[76:79]
	v_mfma_f32_16x16x32_bf16 v[72:75], v[174:177], v[222:225], v[72:75]
	v_mfma_f32_16x16x32_bf16 v[124:127], v[170:173], v[202:205], v[124:127]
	v_mfma_f32_16x16x32_bf16 v[120:123], v[178:181], v[202:205], v[120:123]
	v_mfma_f32_16x16x32_bf16 v[108:111], v[170:173], v[210:213], v[108:111]
	v_mfma_f32_16x16x32_bf16 v[104:107], v[178:181], v[210:213], v[104:107]
	v_mfma_f32_16x16x32_bf16 v[92:95], v[170:173], v[218:221], v[92:95]
	v_mfma_f32_16x16x32_bf16 v[88:91], v[178:181], v[218:221], v[88:91]
	v_mfma_f32_16x16x32_bf16 v[76:79], v[170:173], v[226:229], v[76:79]
	v_mfma_f32_16x16x32_bf16 v[72:75], v[178:181], v[226:229], v[72:75]
	s_nop 0
	s_nop 0
	v_mfma_f32_16x16x32_bf16 v[116:119], v[182:185], v[198:201], v[116:119]
	v_mfma_f32_16x16x32_bf16 v[112:115], v[190:193], v[198:201], v[112:115]
	v_mfma_f32_16x16x32_bf16 v[100:103], v[182:185], v[206:209], v[100:103]
	v_mfma_f32_16x16x32_bf16 v[96:99], v[190:193], v[206:209], v[96:99]
	v_mfma_f32_16x16x32_bf16 v[84:87], v[182:185], v[214:217], v[84:87]
	v_mfma_f32_16x16x32_bf16 v[80:83], v[190:193], v[214:217], v[80:83]
	v_mfma_f32_16x16x32_bf16 v[68:71], v[182:185], v[222:225], v[68:71]
	v_mfma_f32_16x16x32_bf16 v[64:67], v[190:193], v[222:225], v[64:67]
	v_mfma_f32_16x16x32_bf16 v[116:119], v[186:189], v[202:205], v[116:119]
	v_mfma_f32_16x16x32_bf16 v[112:115], v[194:197], v[202:205], v[112:115]
	v_mfma_f32_16x16x32_bf16 v[100:103], v[186:189], v[210:213], v[100:103]
	v_mfma_f32_16x16x32_bf16 v[96:99], v[194:197], v[210:213], v[96:99]
	v_mfma_f32_16x16x32_bf16 v[84:87], v[186:189], v[218:221], v[84:87]
	v_mfma_f32_16x16x32_bf16 v[80:83], v[194:197], v[218:221], v[80:83]
	v_mfma_f32_16x16x32_bf16 v[68:71], v[186:189], v[226:229], v[68:71]
	v_mfma_f32_16x16x32_bf16 v[64:67], v[194:197], v[226:229], v[64:67]
	s_setprio 0
	s_barrier
	s_add_i32 s68, s45, s37
	v_lshl_add_u64 v[160:161], s[30:31], 0, v[138:139]
	s_mov_b32 m0, s68
	v_lshl_add_u64 v[230:231], s[30:31], 0, v[142:143]
	global_load_lds_dwordx4 v[160:161], off
	s_add_i32 m0, s68, 0x2000
	s_add_u32 s68, s30, 0x20000
	s_addc_u32 s69, s31, 0
	s_add_i32 s70, s50, s37
	global_load_lds_dwordx4 v[230:231], off
	v_lshl_add_u64 v[232:233], s[68:69], 0, v[138:139]
	s_mov_b32 m0, s70
	v_lshl_add_u64 v[234:235], s[34:35], 0, v[140:141]
	global_load_lds_dwordx4 v[232:233], off
	v_lshl_add_u64 v[232:233], s[68:69], 0, v[142:143]
	s_add_i32 m0, s70, 0x2000
	ds_read_b128 v[198:201], v163 offset:16384
	global_load_lds_dwordx4 v[232:233], off
	v_lshl_add_u64 v[232:233], s[34:35], 0, v[136:137]
	s_mov_b32 m0, s27
	ds_read_b128 v[202:205], v163 offset:17408
	global_load_lds_dwordx4 v[232:233], off
	s_mov_b32 m0, s38
	ds_read_b128 v[206:209], v163 offset:18432
	global_load_lds_dwordx4 v[234:235], off
	ds_read_b128 v[210:213], v163 offset:19456
	ds_read_b128 v[214:217], v163 offset:20480
	ds_read_b128 v[218:221], v163 offset:21504
	ds_read_b128 v[222:225], v163 offset:22528
	ds_read_b128 v[226:229], v163 offset:23552
	s_waitcnt vmcnt(8)
	s_waitcnt lgkmcnt(0)
	s_barrier
; #define PG8_STAGE(bufoff, gbase, voff) do { _Pragma("unroll") for (int _i = 0; _i < 2; ++_i) \
;         __builtin_amdgcn_global_load_lds((const unsigned*)((const char*)(gbase) + (voff)[_i]), (PG8_LAS unsigned*)(lds + (bufoff) + ldsw + _i * 8192), 16, 0, 0); } while (0)
; #define PG8_LDA(dst, b, h) do { _Pragma("unroll") for (int m = 0; m < 4; ++m) _Pragma("unroll") for (int k = 0; k < 2; ++k) dst[m][k] = *(const PG8_LAS bf16x8*)(lds + PG8_SA(b, h) + aoff + m * 2048 + k * 1024); } while (0)
; #define PG8_LDB(dst, b, h) do { _Pragma("unroll") for (int n = 0; n < 2; ++n) _Pragma("unroll") for (int k = 0; k < 2; ++k) dst[n][k] = *(const PG8_LAS bf16x8*)(lds + PG8_SB(b, h) + boff + n * 2048 + k * 1024); } while (0)
; #define PG8_MMA(ai, bj, At, Bt) do { __builtin_amdgcn_s_setprio(1); _Pragma("unroll") for (int m = 0; m < 4; ++m) _Pragma("unroll") for (int n = 0; n < 2; ++n) _Pragma("unroll") for (int k = 0; k < 2; ++k) \
;         acc[ai][bj][m][n] = __builtin_amdgcn_mfma_f32_16x16x32_bf16(Bt[n][k], At[m][k], acc[ai][bj][m][n], 0, 0, 0); __builtin_amdgcn_s_setprio(0); } while (0)
; #define PG8_WAIT_V(n) asm volatile("s_waitcnt vmcnt(" #n ")" ::: "memory")
; #define PG8_WAIT_L(n) asm volatile("s_waitcnt lgkmcnt(" #n ")" ::: "memory")
; #define PG8_BAR __builtin_amdgcn_s_barrier()
; #define PG8_SCHED __builtin_amdgcn_sched_barrier(0)
; template <class Epi, class Sched, bool ALIGN_EPI = false, bool SP2 = false>
; __device__ __forceinline__ void gemm_phase(PG8_LAS unsigned char* lds, const Gemm g, const Sched& S, const Epi& E) {
;     ...
;             PG8_WAIT_V(8); PG8_WAIT_L(0); PG8_BAR; PG8_MMA(1, 0, At, B0); PG8_MMA(1, 1, At, B1); PG8_BAR; PG8_SCHED;
;             PG8_LDB(B0, 1, 0); PG8_LDB(B1, 1, 1); PG8_SCHED; PG8_LDA(At, 1, 0); PG8_STAGE(PG8_SA(0, 1), a2 + hstep, voffA);
;             PG8_WAIT_V(8); PG8_WAIT_L(0); PG8_BAR; PG8_MMA(0, 0, At, B0); PG8_MMA(0, 1, At, B1); PG8_BAR; PG8_SCHED;
	s_setprio 1
	s_waitcnt lgkmcnt(0)
	v_mfma_f32_16x16x32_bf16 v[60:63], v[156:159], v[198:201], v[60:63]
	v_mfma_f32_16x16x32_bf16 v[56:59], v[174:177], v[198:201], v[56:59]
	v_mfma_f32_16x16x32_bf16 v[44:47], v[156:159], v[206:209], v[44:47]
	v_mfma_f32_16x16x32_bf16 v[40:43], v[174:177], v[206:209], v[40:43]
	v_mfma_f32_16x16x32_bf16 v[28:31], v[156:159], v[214:217], v[28:31]
	v_mfma_f32_16x16x32_bf16 v[24:27], v[174:177], v[214:217], v[24:27]
	v_mfma_f32_16x16x32_bf16 v[12:15], v[156:159], v[222:225], v[12:15]
	v_mfma_f32_16x16x32_bf16 v[8:11], v[174:177], v[222:225], v[8:11]
	v_mfma_f32_16x16x32_bf16 v[60:63], v[170:173], v[202:205], v[60:63]
	v_mfma_f32_16x16x32_bf16 v[56:59], v[178:181], v[202:205], v[56:59]
	v_mfma_f32_16x16x32_bf16 v[44:47], v[170:173], v[210:213], v[44:47]
	v_mfma_f32_16x16x32_bf16 v[40:43], v[178:181], v[210:213], v[40:43]
	v_mfma_f32_16x16x32_bf16 v[28:31], v[170:173], v[218:221], v[28:31]
	v_mfma_f32_16x16x32_bf16 v[24:27], v[178:181], v[218:221], v[24:27]
	v_mfma_f32_16x16x32_bf16 v[12:15], v[170:173], v[226:229], v[12:15]
	v_mfma_f32_16x16x32_bf16 v[8:11], v[178:181], v[226:229], v[8:11]
	s_nop 0
	s_nop 0
	v_mfma_f32_16x16x32_bf16 v[52:55], v[182:185], v[198:201], v[52:55]
	v_mfma_f32_16x16x32_bf16 v[48:51], v[190:193], v[198:201], v[48:51]
	v_mfma_f32_16x16x32_bf16 v[36:39], v[182:185], v[206:209], v[36:39]
	v_mfma_f32_16x16x32_bf16 v[32:35], v[190:193], v[206:209], v[32:35]
	v_mfma_f32_16x16x32_bf16 v[20:23], v[182:185], v[214:217], v[20:23]
	v_mfma_f32_16x16x32_bf16 v[16:19], v[190:193], v[214:217], v[16:19]
	v_mfma_f32_16x16x32_bf16 v[4:7], v[182:185], v[222:225], v[4:7]
	v_mfma_f32_16x16x32_bf16 v[0:3], v[190:193], v[222:225], v[0:3]
	v_mfma_f32_16x16x32_bf16 v[52:55], v[186:189], v[202:205], v[52:55]
	v_mfma_f32_16x16x32_bf16 v[48:51], v[194:197], v[202:205], v[48:51]
	v_mfma_f32_16x16x32_bf16 v[36:39], v[186:189], v[210:213], v[36:39]
	v_mfma_f32_16x16x32_bf16 v[32:35], v[194:197], v[210:213], v[32:35]
	v_mfma_f32_16x16x32_bf16 v[20:23], v[186:189], v[218:221], v[20:23]
	v_mfma_f32_16x16x32_bf16 v[16:19], v[194:197], v[218:221], v[16:19]
	v_mfma_f32_16x16x32_bf16 v[4:7], v[186:189], v[226:229], v[4:7]
	v_mfma_f32_16x16x32_bf16 v[0:3], v[194:197], v[226:229], v[0:3]
	s_setprio 0
	s_barrier
	s_add_i32 s68, 0, 0x18000
	s_add_i32 s69, 0, 0x1c000
	s_add_u32 s34, s34, 0x20000
	s_addc_u32 s35, s35, 0
	s_mov_b32 m0, s39
	v_lshl_add_u64 v[236:237], s[34:35], 0, v[136:137]
	global_load_lds_dwordx4 v[236:237], off
	v_lshl_add_u64 v[236:237], s[34:35], 0, v[140:141]
	s_mov_b32 m0, s40
	v_add_u32_e32 v178, s68, v131
	global_load_lds_dwordx4 v[236:237], off
	v_add_u32_e32 v194, s69, v131
	ds_read_b128 v[156:159], v178
	ds_read_b128 v[170:173], v178 offset:1024
	ds_read_b128 v[174:177], v178 offset:2048
	ds_read_b128 v[178:181], v178 offset:3072
	ds_read_b128 v[182:185], v194
	ds_read_b128 v[186:189], v194 offset:1024
	ds_read_b128 v[190:193], v194 offset:2048
	ds_read_b128 v[194:197], v194 offset:3072
	ds_read_b128 v[198:201], v163 offset:32768
	ds_read_b128 v[202:205], v163 offset:33792
	ds_read_b128 v[206:209], v163 offset:34816
	ds_read_b128 v[210:213], v163 offset:35840
	ds_read_b128 v[214:217], v163 offset:36864
	ds_read_b128 v[218:221], v163 offset:37888
	ds_read_b128 v[222:225], v163 offset:38912
	ds_read_b128 v[226:229], v163 offset:39936
	s_waitcnt vmcnt(8)
	s_waitcnt lgkmcnt(0)
	s_barrier
	s_setprio 1
	s_waitcnt lgkmcnt(0)
	v_mfma_f32_16x16x32_bf16 v[124:127], v[156:159], v[198:201], v[124:127]
	v_mfma_f32_16x16x32_bf16 v[120:123], v[174:177], v[198:201], v[120:123]
	v_mfma_f32_16x16x32_bf16 v[108:111], v[156:159], v[206:209], v[108:111]
	v_mfma_f32_16x16x32_bf16 v[104:107], v[174:177], v[206:209], v[104:107]
	v_mfma_f32_16x16x32_bf16 v[92:95], v[156:159], v[214:217], v[92:95]
	v_mfma_f32_16x16x32_bf16 v[88:91], v[174:177], v[214:217], v[88:91]
	v_mfma_f32_16x16x32_bf16 v[76:79], v[156:159], v[222:225], v[76:79]
	v_mfma_f32_16x16x32_bf16 v[72:75], v[174:177], v[222:225], v[72:75]
	v_mfma_f32_16x16x32_bf16 v[124:127], v[170:173], v[202:205], v[124:127]
	v_mfma_f32_16x16x32_bf16 v[120:123], v[178:181], v[202:205], v[120:123]
	v_mfma_f32_16x16x32_bf16 v[108:111], v[170:173], v[210:213], v[108:111]
	v_mfma_f32_16x16x32_bf16 v[104:107], v[178:181], v[210:213], v[104:107]
	v_mfma_f32_16x16x32_bf16 v[92:95], v[170:173], v[218:221], v[92:95]
	v_mfma_f32_16x16x32_bf16 v[88:91], v[178:181], v[218:221], v[88:91]
	v_mfma_f32_16x16x32_bf16 v[76:79], v[170:173], v[226:229], v[76:79]
	v_mfma_f32_16x16x32_bf16 v[72:75], v[178:181], v[226:229], v[72:75]
	s_nop 0
	s_nop 0
	v_mfma_f32_16x16x32_bf16 v[116:119], v[182:185], v[198:201], v[116:119]
	v_mfma_f32_16x16x32_bf16 v[112:115], v[190:193], v[198:201], v[112:115]
	v_mfma_f32_16x16x32_bf16 v[100:103], v[182:185], v[206:209], v[100:103]
	v_mfma_f32_16x16x32_bf16 v[96:99], v[190:193], v[206:209], v[96:99]
	v_mfma_f32_16x16x32_bf16 v[84:87], v[182:185], v[214:217], v[84:87]
	v_mfma_f32_16x16x32_bf16 v[80:83], v[190:193], v[214:217], v[80:83]
	v_mfma_f32_16x16x32_bf16 v[68:71], v[182:185], v[222:225], v[68:71]
	v_mfma_f32_16x16x32_bf16 v[64:67], v[190:193], v[222:225], v[64:67]
	v_mfma_f32_16x16x32_bf16 v[116:119], v[186:189], v[202:205], v[116:119]
	v_mfma_f32_16x16x32_bf16 v[112:115], v[194:197], v[202:205], v[112:115]
	v_mfma_f32_16x16x32_bf16 v[100:103], v[186:189], v[210:213], v[100:103]
	v_mfma_f32_16x16x32_bf16 v[96:99], v[194:197], v[210:213], v[96:99]
	v_mfma_f32_16x16x32_bf16 v[84:87], v[186:189], v[218:221], v[84:87]
	v_mfma_f32_16x16x32_bf16 v[80:83], v[194:197], v[218:221], v[80:83]
	v_mfma_f32_16x16x32_bf16 v[68:71], v[186:189], v[226:229], v[68:71]
	v_mfma_f32_16x16x32_bf16 v[64:67], v[194:197], v[226:229], v[64:67]
	s_setprio 0
	s_barrier
; #define PG8_STAGE(bufoff, gbase, voff) do { _Pragma("unroll") for (int _i = 0; _i < 2; ++_i) \
;         __builtin_amdgcn_global_load_lds((const unsigned*)((const char*)(gbase) + (voff)[_i]), (PG8_LAS unsigned*)(lds + (bufoff) + ldsw + _i * 8192), 16, 0, 0); } while (0)
; #define PG8_LDA(dst, b, h) do { _Pragma("unroll") for (int m = 0; m < 4; ++m) _Pragma("unroll") for (int k = 0; k < 2; ++k) dst[m][k] = *(const PG8_LAS bf16x8*)(lds + PG8_SA(b, h) + aoff + m * 2048 + k * 1024); } while (0)
; #define PG8_MMA(ai, bj, At, Bt) do { __builtin_amdgcn_s_setprio(1); _Pragma("unroll") for (int m = 0; m < 4; ++m) _Pragma("unroll") for (int n = 0; n < 2; ++n) _Pragma("unroll") for (int k = 0; k < 2; ++k) \
;         acc[ai][bj][m][n] = __builtin_amdgcn_mfma_f32_16x16x32_bf16(Bt[n][k], At[m][k], acc[ai][bj][m][n], 0, 0, 0); __builtin_amdgcn_s_setprio(0); } while (0)
; #define PG8_WAIT_V(n) asm volatile("s_waitcnt vmcnt(" #n ")" ::: "memory")
; #define PG8_WAIT_L(n) asm volatile("s_waitcnt lgkmcnt(" #n ")" ::: "memory")
; #define PG8_BAR __builtin_amdgcn_s_barrier()
; #define PG8_SCHED __builtin_amdgcn_sched_barrier(0)
; template <class Epi, class Sched, bool ALIGN_EPI = false, bool SP2 = false>
; __device__ __forceinline__ void gemm_phase(PG8_LAS unsigned char* lds, const Gemm g, const Sched& S, const Epi& E) {
;     ...
;             PG8_LDA(At, 1, 1); PG8_STAGE(PG8_SB(1, 0), b3, voffB); PG8_STAGE(PG8_SB(1, 1), b3 + hstep, voffB); PG8_STAGE(PG8_SA(1, 0), a3, voffA);
;             PG8_WAIT_V(8); PG8_WAIT_L(0); PG8_BAR; PG8_MMA(1, 0, At, B0); PG8_MMA(1, 1, At, B1); PG8_BAR; PG8_SCHED;
;     ...
;         if constexpr (ALIGN_EPI) { if (wr == 0) PG8_BAR; }
	s_add_i32 s34, s68, s37
	v_lshl_add_u64 v[160:161], v[160:161], 0, s[6:7]
	s_mov_b32 m0, s34
	ds_read_b128 v[198:201], v163 offset:49152
	global_load_lds_dwordx4 v[160:161], off
	s_add_i32 m0, s34, 0x2000
	s_add_u32 s30, s30, 0x20080
	v_lshl_add_u64 v[160:161], v[230:231], 0, s[6:7]
	s_addc_u32 s31, s31, 0
	s_add_i32 s34, s69, s37
	global_load_lds_dwordx4 v[160:161], off
	v_lshl_add_u64 v[160:161], s[30:31], 0, v[138:139]
	s_mov_b32 m0, s34
	ds_read_b128 v[202:205], v163 offset:50176
	global_load_lds_dwordx4 v[160:161], off
	v_lshl_add_u64 v[160:161], s[30:31], 0, v[142:143]
	s_add_i32 m0, s34, 0x2000
	ds_read_b128 v[206:209], v163 offset:51200
	global_load_lds_dwordx4 v[160:161], off
	v_lshl_add_u64 v[160:161], v[232:233], 0, s[6:7]
	s_mov_b32 m0, s42
	ds_read_b128 v[210:213], v163 offset:52224
	global_load_lds_dwordx4 v[160:161], off
	v_lshl_add_u64 v[160:161], v[234:235], 0, s[6:7]
	s_mov_b32 m0, s43
	ds_read_b128 v[214:217], v163 offset:53248
	global_load_lds_dwordx4 v[160:161], off
	ds_read_b128 v[218:221], v163 offset:54272
	ds_read_b128 v[222:225], v163 offset:55296
	ds_read_b128 v[226:229], v163 offset:56320
	s_waitcnt vmcnt(8)
	s_waitcnt lgkmcnt(0)
	s_barrier
	s_setprio 1
	s_waitcnt lgkmcnt(0)
	v_mfma_f32_16x16x32_bf16 v[60:63], v[156:159], v[198:201], v[60:63]
	v_mfma_f32_16x16x32_bf16 v[56:59], v[174:177], v[198:201], v[56:59]
	v_mfma_f32_16x16x32_bf16 v[44:47], v[156:159], v[206:209], v[44:47]
	v_mfma_f32_16x16x32_bf16 v[40:43], v[174:177], v[206:209], v[40:43]
	v_mfma_f32_16x16x32_bf16 v[28:31], v[156:159], v[214:217], v[28:31]
	v_mfma_f32_16x16x32_bf16 v[24:27], v[174:177], v[214:217], v[24:27]
	v_mfma_f32_16x16x32_bf16 v[12:15], v[156:159], v[222:225], v[12:15]
	v_mfma_f32_16x16x32_bf16 v[8:11], v[174:177], v[222:225], v[8:11]
	v_mfma_f32_16x16x32_bf16 v[60:63], v[170:173], v[202:205], v[60:63]
	v_mfma_f32_16x16x32_bf16 v[56:59], v[178:181], v[202:205], v[56:59]
	v_mfma_f32_16x16x32_bf16 v[44:47], v[170:173], v[210:213], v[44:47]
	v_mfma_f32_16x16x32_bf16 v[40:43], v[178:181], v[210:213], v[40:43]
	v_mfma_f32_16x16x32_bf16 v[28:31], v[170:173], v[218:221], v[28:31]
	v_mfma_f32_16x16x32_bf16 v[24:27], v[178:181], v[218:221], v[24:27]
	v_mfma_f32_16x16x32_bf16 v[12:15], v[170:173], v[226:229], v[12:15]
	v_mfma_f32_16x16x32_bf16 v[8:11], v[178:181], v[226:229], v[8:11]
	s_nop 0
	s_nop 0
	v_mfma_f32_16x16x32_bf16 v[52:55], v[182:185], v[198:201], v[52:55]
	v_mfma_f32_16x16x32_bf16 v[48:51], v[190:193], v[198:201], v[48:51]
	v_mfma_f32_16x16x32_bf16 v[36:39], v[182:185], v[206:209], v[36:39]
	v_mfma_f32_16x16x32_bf16 v[32:35], v[190:193], v[206:209], v[32:35]
	v_mfma_f32_16x16x32_bf16 v[20:23], v[182:185], v[214:217], v[20:23]
	v_mfma_f32_16x16x32_bf16 v[16:19], v[190:193], v[214:217], v[16:19]
	v_mfma_f32_16x16x32_bf16 v[4:7], v[182:185], v[222:225], v[4:7]
	v_mfma_f32_16x16x32_bf16 v[0:3], v[190:193], v[222:225], v[0:3]
	v_mfma_f32_16x16x32_bf16 v[52:55], v[186:189], v[202:205], v[52:55]
	v_mfma_f32_16x16x32_bf16 v[48:51], v[194:197], v[202:205], v[48:51]
	v_mfma_f32_16x16x32_bf16 v[36:39], v[186:189], v[210:213], v[36:39]
	v_mfma_f32_16x16x32_bf16 v[32:35], v[194:197], v[210:213], v[32:35]
	v_mfma_f32_16x16x32_bf16 v[20:23], v[186:189], v[218:221], v[20:23]
	v_mfma_f32_16x16x32_bf16 v[16:19], v[194:197], v[218:221], v[16:19]
	v_mfma_f32_16x16x32_bf16 v[4:7], v[186:189], v[226:229], v[4:7]
	v_mfma_f32_16x16x32_bf16 v[0:3], v[194:197], v[226:229], v[0:3]
	s_setprio 0
	s_barrier
	s_add_i32 s63, s63, 2
	s_add_u32 s28, s28, 0x100
	s_addc_u32 s29, s29, 0
	s_add_u32 s61, s61, 0x100
	s_addc_u32 s62, s62, 0
	s_cmp_gt_u32 s63, 5
	s_cbranch_scc0 .LBB0_1271
	s_nop 0
	s_nop 0
	s_nop 0
	s_nop 0
	s_nop 0
	s_nop 0
	s_nop 0
	s_nop 0
	s_nop 0
	s_and_b64 vcc, exec, s[8:9]
	s_cbranch_vccz .LBB0_1274
	s_barrier

; #define PG8_STAGE(bufoff, gbase, voff) do { _Pragma("unroll") for (int _i = 0; _i < 2; ++_i) \
;         __builtin_amdgcn_global_load_lds((const unsigned*)((const char*)(gbase) + (voff)[_i]), (PG8_LAS unsigned*)(lds + (bufoff) + ldsw + _i * 8192), 16, 0, 0); } while (0)
; #define PG8_LDA(dst, b, h) do { _Pragma("unroll") for (int m = 0; m < 4; ++m) _Pragma("unroll") for (int k = 0; k < 2; ++k) dst[m][k] = *(const PG8_LAS bf16x8*)(lds + PG8_SA(b, h) + aoff + m * 2048 + k * 1024); } while (0)
; #define PG8_LDB(dst, b, h) do { _Pragma("unroll") for (int n = 0; n < 2; ++n) _Pragma("unroll") for (int k = 0; k < 2; ++k) dst[n][k] = *(const PG8_LAS bf16x8*)(lds + PG8_SB(b, h) + boff + n * 2048 + k * 1024); } while (0)
; #define PG8_MMA(ai, bj, At, Bt) do { __builtin_amdgcn_s_setprio(1); _Pragma("unroll") for (int m = 0; m < 4; ++m) _Pragma("unroll") for (int n = 0; n < 2; ++n) _Pragma("unroll") for (int k = 0; k < 2; ++k) \
;         acc[ai][bj][m][n] = __builtin_amdgcn_mfma_f32_16x16x32_bf16(Bt[n][k], At[m][k], acc[ai][bj][m][n], 0, 0, 0); __builtin_amdgcn_s_setprio(0); } while (0)
; #define PG8_WAIT_V(n) asm volatile("s_waitcnt vmcnt(" #n ")" ::: "memory")
; #define PG8_WAIT_L(n) asm volatile("s_waitcnt lgkmcnt(" #n ")" ::: "memory")
; template <class Epi, class Sched, bool ALIGN_EPI = false, bool SP2 = false>
; __device__ __forceinline__ void gemm_phase(PG8_LAS unsigned char* lds, const Gemm g, const Sched& S, const Epi& E) {
;     ...
;             const bool last = (t == nt - 2);
;             const char* a1 = cA + (size_t)(t + 1) * kstep;
;             const char* a2 = last ? nA : cA + (size_t)(t + 2) * kstep; const char* b2 = last ? nB : cB + (size_t)(t + 2) * kstep;
;             const char* a3 = a2 + kstep; const char* b3 = b2 + kstep;
;             if (last && has_next) S.a_ready(nxt);
;             if constexpr (SP2) {
;             PG8_LDB(B0, 0, 0); PG8_LDB(B1, 0, 1); PG8_SCHED; PG8_LDA(At, 0, 0); PG8_STAGE(PG8_SA(1, 1), a1 + hstep, voffA);
;             PG8_WAIT_V(8); PG8_WAIT_L(0); PG8_BAR; PG8_MMA(0, 0, At, B0); PG8_MMA(0, 1, At, B1); PG8_BAR; PG8_SCHED;
;             PG8_LDA(At, 0, 1); PG8_STAGE(PG8_SB(0, 0), b2, voffB); PG8_STAGE(PG8_SB(0, 1), b2 + hstep, voffB); PG8_STAGE(PG8_SA(0, 0), a2, voffA);
;             PG8_WAIT_V(8); PG8_WAIT_L(0); PG8_BAR; PG8_MMA(1, 0, At, B0); PG8_MMA(1, 1, At, B1); PG8_BAR; PG8_SCHED;
.LBB0_1295:
	s_add_u32 s8, s6, 0xfffc0080
	s_addc_u32 s9, s7, -1
	s_cmp_eq_u32 s68, 12
	s_cselect_b32 s11, s12, s9
	s_cselect_b32 s10, s13, s8
	s_cselect_b32 s9, s27, s53
	s_cselect_b32 s8, s29, s52
	v_lshl_add_u64 v[162:163], s[6:7], 0, v[144:145]
	s_add_i32 m0, s40, 0xc000
	ds_read_b128 v[156:159], v143
	global_load_lds_dwordx4 v[162:163], off
	v_lshl_add_u64 v[162:163], s[6:7], 0, v[146:147]
	s_add_i32 m0, s40, 0xe000
	ds_read_b128 v[172:175], v143 offset:1024
	global_load_lds_dwordx4 v[162:163], off
	ds_read_b128 v[176:179], v143 offset:2048
	ds_read_b128 v[180:183], v143 offset:3072
	ds_read_b128 v[184:187], v161
	ds_read_b128 v[188:191], v161 offset:1024
	ds_read_b128 v[192:195], v161 offset:2048
	ds_read_b128 v[196:199], v161 offset:3072
	ds_read_b128 v[200:203], v170
	ds_read_b128 v[204:207], v170 offset:1024
	ds_read_b128 v[208:211], v170 offset:2048
	ds_read_b128 v[212:215], v170 offset:3072
	ds_read_b128 v[216:219], v170 offset:4096
	ds_read_b128 v[220:223], v170 offset:5120
	ds_read_b128 v[224:227], v170 offset:6144
	ds_read_b128 v[228:231], v170 offset:7168
	s_waitcnt vmcnt(8)
	s_waitcnt lgkmcnt(0)
	s_barrier
	s_setprio 1
	s_waitcnt lgkmcnt(0)
	v_mfma_f32_16x16x32_bf16 v[124:127], v[156:159], v[200:203], v[124:127]
	v_mfma_f32_16x16x32_bf16 v[120:123], v[176:179], v[200:203], v[120:123]
	v_mfma_f32_16x16x32_bf16 v[108:111], v[156:159], v[208:211], v[108:111]
	v_mfma_f32_16x16x32_bf16 v[104:107], v[176:179], v[208:211], v[104:107]
	v_mfma_f32_16x16x32_bf16 v[92:95], v[156:159], v[216:219], v[92:95]
	v_mfma_f32_16x16x32_bf16 v[88:91], v[176:179], v[216:219], v[88:91]
	v_mfma_f32_16x16x32_bf16 v[76:79], v[156:159], v[224:227], v[76:79]
	v_mfma_f32_16x16x32_bf16 v[72:75], v[176:179], v[224:227], v[72:75]
	v_mfma_f32_16x16x32_bf16 v[124:127], v[172:175], v[204:207], v[124:127]
	v_mfma_f32_16x16x32_bf16 v[120:123], v[180:183], v[204:207], v[120:123]
	v_mfma_f32_16x16x32_bf16 v[108:111], v[172:175], v[212:215], v[108:111]
	v_mfma_f32_16x16x32_bf16 v[104:107], v[180:183], v[212:215], v[104:107]
	v_mfma_f32_16x16x32_bf16 v[92:95], v[172:175], v[220:223], v[92:95]
	v_mfma_f32_16x16x32_bf16 v[88:91], v[180:183], v[220:223], v[88:91]
	v_mfma_f32_16x16x32_bf16 v[76:79], v[172:175], v[228:231], v[76:79]
	v_mfma_f32_16x16x32_bf16 v[72:75], v[180:183], v[228:231], v[72:75]
	s_nop 0
	s_nop 0
	v_mfma_f32_16x16x32_bf16 v[116:119], v[184:187], v[200:203], v[116:119]
	v_mfma_f32_16x16x32_bf16 v[112:115], v[192:195], v[200:203], v[112:115]
	v_mfma_f32_16x16x32_bf16 v[100:103], v[184:187], v[208:211], v[100:103]
	v_mfma_f32_16x16x32_bf16 v[96:99], v[192:195], v[208:211], v[96:99]
	v_mfma_f32_16x16x32_bf16 v[84:87], v[184:187], v[216:219], v[84:87]
	v_mfma_f32_16x16x32_bf16 v[80:83], v[192:195], v[216:219], v[80:83]
	v_mfma_f32_16x16x32_bf16 v[68:71], v[184:187], v[224:227], v[68:71]
	v_mfma_f32_16x16x32_bf16 v[64:67], v[192:195], v[224:227], v[64:67]
	v_mfma_f32_16x16x32_bf16 v[116:119], v[188:191], v[204:207], v[116:119]
	v_mfma_f32_16x16x32_bf16 v[112:115], v[196:199], v[204:207], v[112:115]
	v_mfma_f32_16x16x32_bf16 v[100:103], v[188:191], v[212:215], v[100:103]
	v_mfma_f32_16x16x32_bf16 v[96:99], v[196:199], v[212:215], v[96:99]
	v_mfma_f32_16x16x32_bf16 v[84:87], v[188:191], v[220:223], v[84:87]
	v_mfma_f32_16x16x32_bf16 v[80:83], v[196:199], v[220:223], v[80:83]
	v_mfma_f32_16x16x32_bf16 v[68:71], v[188:191], v[228:231], v[68:71]
	v_mfma_f32_16x16x32_bf16 v[64:67], v[196:199], v[228:231], v[64:67]
	s_setprio 0
	s_barrier
	s_add_i32 s69, s56, s39
	v_lshl_add_u64 v[162:163], s[8:9], 0, v[130:131]
	s_mov_b32 m0, s69
	v_lshl_add_u64 v[232:233], s[8:9], 0, v[134:135]
	global_load_lds_dwordx4 v[162:163], off
	s_add_i32 m0, s69, 0x2000
	s_add_u32 s70, s8, 0x40000
	s_addc_u32 s71, s9, 0
	s_add_i32 s69, s57, s39
	global_load_lds_dwordx4 v[232:233], off
	v_lshl_add_u64 v[234:235], s[70:71], 0, v[130:131]
	s_mov_b32 m0, s69
	v_lshl_add_u64 v[236:237], s[10:11], 0, v[132:133]
	global_load_lds_dwordx4 v[234:235], off
	v_lshl_add_u64 v[234:235], s[70:71], 0, v[134:135]
	s_add_i32 m0, s69, 0x2000
	ds_read_b128 v[200:203], v170 offset:16384
	global_load_lds_dwordx4 v[234:235], off
	v_lshl_add_u64 v[234:235], s[10:11], 0, v[128:129]
	s_mov_b32 m0, s40
	ds_read_b128 v[204:207], v170 offset:17408
	global_load_lds_dwordx4 v[234:235], off
	s_mov_b32 m0, s41
	ds_read_b128 v[208:211], v170 offset:18432
	global_load_lds_dwordx4 v[236:237], off
	ds_read_b128 v[212:215], v170 offset:19456
	ds_read_b128 v[216:219], v170 offset:20480
	ds_read_b128 v[220:223], v170 offset:21504
	ds_read_b128 v[224:227], v170 offset:22528
	ds_read_b128 v[228:231], v170 offset:23552
	s_waitcnt vmcnt(8)
	s_waitcnt lgkmcnt(0)
	s_barrier
; #define PG8_STAGE(bufoff, gbase, voff) do { _Pragma("unroll") for (int _i = 0; _i < 2; ++_i) \
;         __builtin_amdgcn_global_load_lds((const unsigned*)((const char*)(gbase) + (voff)[_i]), (PG8_LAS unsigned*)(lds + (bufoff) + ldsw + _i * 8192), 16, 0, 0); } while (0)
; #define PG8_LDA(dst, b, h) do { _Pragma("unroll") for (int m = 0; m < 4; ++m) _Pragma("unroll") for (int k = 0; k < 2; ++k) dst[m][k] = *(const PG8_LAS bf16x8*)(lds + PG8_SA(b, h) + aoff + m * 2048 + k * 1024); } while (0)
; #define PG8_LDB(dst, b, h) do { _Pragma("unroll") for (int n = 0; n < 2; ++n) _Pragma("unroll") for (int k = 0; k < 2; ++k) dst[n][k] = *(const PG8_LAS bf16x8*)(lds + PG8_SB(b, h) + boff + n * 2048 + k * 1024); } while (0)
; #define PG8_MMA(ai, bj, At, Bt) do { __builtin_amdgcn_s_setprio(1); _Pragma("unroll") for (int m = 0; m < 4; ++m) _Pragma("unroll") for (int n = 0; n < 2; ++n) _Pragma("unroll") for (int k = 0; k < 2; ++k) \
;         acc[ai][bj][m][n] = __builtin_amdgcn_mfma_f32_16x16x32_bf16(Bt[n][k], At[m][k], acc[ai][bj][m][n], 0, 0, 0); __builtin_amdgcn_s_setprio(0); } while (0)
; #define PG8_WAIT_V(n) asm volatile("s_waitcnt vmcnt(" #n ")" ::: "memory")
; #define PG8_WAIT_L(n) asm volatile("s_waitcnt lgkmcnt(" #n ")" ::: "memory")
; #define PG8_BAR __builtin_amdgcn_s_barrier()
; #define PG8_SCHED __builtin_amdgcn_sched_barrier(0)
; template <class Epi, class Sched, bool ALIGN_EPI = false, bool SP2 = false>
; __device__ __forceinline__ void gemm_phase(PG8_LAS unsigned char* lds, const Gemm g, const Sched& S, const Epi& E) {
;     ...
;             PG8_WAIT_V(8); PG8_WAIT_L(0); PG8_BAR; PG8_MMA(1, 0, At, B0); PG8_MMA(1, 1, At, B1); PG8_BAR; PG8_SCHED;
;             PG8_LDB(B0, 1, 0); PG8_LDB(B1, 1, 1); PG8_SCHED; PG8_LDA(At, 1, 0); PG8_STAGE(PG8_SA(0, 1), a2 + hstep, voffA);
;             PG8_WAIT_V(8); PG8_WAIT_L(0); PG8_BAR; PG8_MMA(0, 0, At, B0); PG8_MMA(0, 1, At, B1); PG8_BAR; PG8_SCHED;
	s_setprio 1
	s_waitcnt lgkmcnt(0)
	v_mfma_f32_16x16x32_bf16 v[60:63], v[156:159], v[200:203], v[60:63]
	v_mfma_f32_16x16x32_bf16 v[56:59], v[176:179], v[200:203], v[56:59]
	v_mfma_f32_16x16x32_bf16 v[44:47], v[156:159], v[208:211], v[44:47]
	v_mfma_f32_16x16x32_bf16 v[40:43], v[176:179], v[208:211], v[40:43]
	v_mfma_f32_16x16x32_bf16 v[28:31], v[156:159], v[216:219], v[28:31]
	v_mfma_f32_16x16x32_bf16 v[24:27], v[176:179], v[216:219], v[24:27]
	v_mfma_f32_16x16x32_bf16 v[12:15], v[156:159], v[224:227], v[12:15]
	v_mfma_f32_16x16x32_bf16 v[8:11], v[176:179], v[224:227], v[8:11]
	v_mfma_f32_16x16x32_bf16 v[60:63], v[172:175], v[204:207], v[60:63]
	v_mfma_f32_16x16x32_bf16 v[56:59], v[180:183], v[204:207], v[56:59]
	v_mfma_f32_16x16x32_bf16 v[44:47], v[172:175], v[212:215], v[44:47]
	v_mfma_f32_16x16x32_bf16 v[40:43], v[180:183], v[212:215], v[40:43]
	v_mfma_f32_16x16x32_bf16 v[28:31], v[172:175], v[220:223], v[28:31]
	v_mfma_f32_16x16x32_bf16 v[24:27], v[180:183], v[220:223], v[24:27]
	v_mfma_f32_16x16x32_bf16 v[12:15], v[172:175], v[228:231], v[12:15]
	v_mfma_f32_16x16x32_bf16 v[8:11], v[180:183], v[228:231], v[8:11]
	s_nop 0
	s_nop 0
	v_mfma_f32_16x16x32_bf16 v[52:55], v[184:187], v[200:203], v[52:55]
	v_mfma_f32_16x16x32_bf16 v[48:51], v[192:195], v[200:203], v[48:51]
	v_mfma_f32_16x16x32_bf16 v[36:39], v[184:187], v[208:211], v[36:39]
	v_mfma_f32_16x16x32_bf16 v[32:35], v[192:195], v[208:211], v[32:35]
	v_mfma_f32_16x16x32_bf16 v[20:23], v[184:187], v[216:219], v[20:23]
	v_mfma_f32_16x16x32_bf16 v[16:19], v[192:195], v[216:219], v[16:19]
	v_mfma_f32_16x16x32_bf16 v[4:7], v[184:187], v[224:227], v[4:7]
	v_mfma_f32_16x16x32_bf16 v[0:3], v[192:195], v[224:227], v[0:3]
	v_mfma_f32_16x16x32_bf16 v[52:55], v[188:191], v[204:207], v[52:55]
	v_mfma_f32_16x16x32_bf16 v[48:51], v[196:199], v[204:207], v[48:51]
	v_mfma_f32_16x16x32_bf16 v[36:39], v[188:191], v[212:215], v[36:39]
	v_mfma_f32_16x16x32_bf16 v[32:35], v[196:199], v[212:215], v[32:35]
	v_mfma_f32_16x16x32_bf16 v[20:23], v[188:191], v[220:223], v[20:23]
	v_mfma_f32_16x16x32_bf16 v[16:19], v[196:199], v[220:223], v[16:19]
	v_mfma_f32_16x16x32_bf16 v[4:7], v[188:191], v[228:231], v[4:7]
	v_mfma_f32_16x16x32_bf16 v[0:3], v[196:199], v[228:231], v[0:3]
	s_setprio 0
	s_barrier
	s_add_i32 s69, 0, 0x18000
	s_add_i32 s70, 0, 0x1c000
	s_add_u32 s10, s10, 0x40000
	s_addc_u32 s11, s11, 0
	s_mov_b32 m0, s42
	v_lshl_add_u64 v[238:239], s[10:11], 0, v[128:129]
	global_load_lds_dwordx4 v[238:239], off
	v_lshl_add_u64 v[238:239], s[10:11], 0, v[132:133]
	s_mov_b32 m0, s43
	v_add_u32_e32 v160, s69, v139
	global_load_lds_dwordx4 v[238:239], off
	ds_read_b128 v[156:159], v160
	ds_read_b128 v[172:175], v160 offset:1024
	ds_read_b128 v[176:179], v160 offset:2048
	ds_read_b128 v[180:183], v160 offset:3072
	v_add_u32_e32 v160, s70, v139
	ds_read_b128 v[184:187], v160
	ds_read_b128 v[188:191], v160 offset:1024
	ds_read_b128 v[192:195], v160 offset:2048
	ds_read_b128 v[196:199], v160 offset:3072
	ds_read_b128 v[200:203], v170 offset:32768
	ds_read_b128 v[204:207], v170 offset:33792
	ds_read_b128 v[208:211], v170 offset:34816
	ds_read_b128 v[212:215], v170 offset:35840
	ds_read_b128 v[216:219], v170 offset:36864
	ds_read_b128 v[220:223], v170 offset:37888
	ds_read_b128 v[224:227], v170 offset:38912
	ds_read_b128 v[228:231], v170 offset:39936
	s_waitcnt vmcnt(8)
	s_waitcnt lgkmcnt(0)
	s_barrier
	s_setprio 1
	s_waitcnt lgkmcnt(0)
	v_mfma_f32_16x16x32_bf16 v[124:127], v[156:159], v[200:203], v[124:127]
	v_mfma_f32_16x16x32_bf16 v[120:123], v[176:179], v[200:203], v[120:123]
	v_mfma_f32_16x16x32_bf16 v[108:111], v[156:159], v[208:211], v[108:111]
	v_mfma_f32_16x16x32_bf16 v[104:107], v[176:179], v[208:211], v[104:107]
	v_mfma_f32_16x16x32_bf16 v[92:95], v[156:159], v[216:219], v[92:95]
	v_mfma_f32_16x16x32_bf16 v[88:91], v[176:179], v[216:219], v[88:91]
	v_mfma_f32_16x16x32_bf16 v[76:79], v[156:159], v[224:227], v[76:79]
	v_mfma_f32_16x16x32_bf16 v[72:75], v[176:179], v[224:227], v[72:75]
	v_mfma_f32_16x16x32_bf16 v[124:127], v[172:175], v[204:207], v[124:127]
	v_mfma_f32_16x16x32_bf16 v[120:123], v[180:183], v[204:207], v[120:123]
	v_mfma_f32_16x16x32_bf16 v[108:111], v[172:175], v[212:215], v[108:111]
	v_mfma_f32_16x16x32_bf16 v[104:107], v[180:183], v[212:215], v[104:107]
	v_mfma_f32_16x16x32_bf16 v[92:95], v[172:175], v[220:223], v[92:95]
	v_mfma_f32_16x16x32_bf16 v[88:91], v[180:183], v[220:223], v[88:91]
	v_mfma_f32_16x16x32_bf16 v[76:79], v[172:175], v[228:231], v[76:79]
	v_mfma_f32_16x16x32_bf16 v[72:75], v[180:183], v[228:231], v[72:75]
	s_nop 0
	s_nop 0
	v_mfma_f32_16x16x32_bf16 v[116:119], v[184:187], v[200:203], v[116:119]
	v_mfma_f32_16x16x32_bf16 v[112:115], v[192:195], v[200:203], v[112:115]
	v_mfma_f32_16x16x32_bf16 v[100:103], v[184:187], v[208:211], v[100:103]
	v_mfma_f32_16x16x32_bf16 v[96:99], v[192:195], v[208:211], v[96:99]
	v_mfma_f32_16x16x32_bf16 v[84:87], v[184:187], v[216:219], v[84:87]
	v_mfma_f32_16x16x32_bf16 v[80:83], v[192:195], v[216:219], v[80:83]
	v_mfma_f32_16x16x32_bf16 v[68:71], v[184:187], v[224:227], v[68:71]
	v_mfma_f32_16x16x32_bf16 v[64:67], v[192:195], v[224:227], v[64:67]
	v_mfma_f32_16x16x32_bf16 v[116:119], v[188:191], v[204:207], v[116:119]
	v_mfma_f32_16x16x32_bf16 v[112:115], v[196:199], v[204:207], v[112:115]
	v_mfma_f32_16x16x32_bf16 v[100:103], v[188:191], v[212:215], v[100:103]
	v_mfma_f32_16x16x32_bf16 v[96:99], v[196:199], v[212:215], v[96:99]
	v_mfma_f32_16x16x32_bf16 v[84:87], v[188:191], v[220:223], v[84:87]
	v_mfma_f32_16x16x32_bf16 v[80:83], v[196:199], v[220:223], v[80:83]
	v_mfma_f32_16x16x32_bf16 v[68:71], v[188:191], v[228:231], v[68:71]
	v_mfma_f32_16x16x32_bf16 v[64:67], v[196:199], v[228:231], v[64:67]
	s_setprio 0
	s_barrier
; #define PG8_STAGE(bufoff, gbase, voff) do { _Pragma("unroll") for (int _i = 0; _i < 2; ++_i) \
;         __builtin_amdgcn_global_load_lds((const unsigned*)((const char*)(gbase) + (voff)[_i]), (PG8_LAS unsigned*)(lds + (bufoff) + ldsw + _i * 8192), 16, 0, 0); } while (0)
; #define PG8_LDA(dst, b, h) do { _Pragma("unroll") for (int m = 0; m < 4; ++m) _Pragma("unroll") for (int k = 0; k < 2; ++k) dst[m][k] = *(const PG8_LAS bf16x8*)(lds + PG8_SA(b, h) + aoff + m * 2048 + k * 1024); } while (0)
; #define PG8_MMA(ai, bj, At, Bt) do { __builtin_amdgcn_s_setprio(1); _Pragma("unroll") for (int m = 0; m < 4; ++m) _Pragma("unroll") for (int n = 0; n < 2; ++n) _Pragma("unroll") for (int k = 0; k < 2; ++k) \
;         acc[ai][bj][m][n] = __builtin_amdgcn_mfma_f32_16x16x32_bf16(Bt[n][k], At[m][k], acc[ai][bj][m][n], 0, 0, 0); __builtin_amdgcn_s_setprio(0); } while (0)
; #define PG8_WAIT_V(n) asm volatile("s_waitcnt vmcnt(" #n ")" ::: "memory")
; #define PG8_WAIT_L(n) asm volatile("s_waitcnt lgkmcnt(" #n ")" ::: "memory")
; #define PG8_BAR __builtin_amdgcn_s_barrier()
; #define PG8_SCHED __builtin_amdgcn_sched_barrier(0)
; template <class Epi, class Sched, bool ALIGN_EPI = false, bool SP2 = false>
; __device__ __forceinline__ void gemm_phase(PG8_LAS unsigned char* lds, const Gemm g, const Sched& S, const Epi& E) {
;     ...
;             PG8_LDA(At, 1, 1); PG8_STAGE(PG8_SB(1, 0), b3, voffB); PG8_STAGE(PG8_SB(1, 1), b3 + hstep, voffB); PG8_STAGE(PG8_SA(1, 0), a3, voffA);
;             PG8_WAIT_V(8); PG8_WAIT_L(0); PG8_BAR; PG8_MMA(1, 0, At, B0); PG8_MMA(1, 1, At, B1); PG8_BAR; PG8_SCHED;
;     ...
;         if constexpr (ALIGN_EPI) { if (wr == 0) PG8_BAR; }
	s_add_i32 s10, s69, s39
	v_lshl_add_u64 v[162:163], v[162:163], 0, s[18:19]
	s_mov_b32 m0, s10
	ds_read_b128 v[200:203], v170 offset:49152
	global_load_lds_dwordx4 v[162:163], off
	s_add_i32 m0, s10, 0x2000
	s_add_u32 s8, s8, 0x40080
	v_lshl_add_u64 v[162:163], v[232:233], 0, s[18:19]
	s_addc_u32 s9, s9, 0
	s_add_i32 s10, s70, s39
	global_load_lds_dwordx4 v[162:163], off
	v_lshl_add_u64 v[162:163], s[8:9], 0, v[130:131]
	s_mov_b32 m0, s10
	ds_read_b128 v[204:207], v170 offset:50176
	global_load_lds_dwordx4 v[162:163], off
	v_lshl_add_u64 v[162:163], s[8:9], 0, v[134:135]
	s_add_i32 m0, s10, 0x2000
	ds_read_b128 v[208:211], v170 offset:51200
	global_load_lds_dwordx4 v[162:163], off
	v_lshl_add_u64 v[162:163], v[234:235], 0, s[18:19]
	s_mov_b32 m0, s45
	ds_read_b128 v[212:215], v170 offset:52224
	global_load_lds_dwordx4 v[162:163], off
	v_lshl_add_u64 v[162:163], v[236:237], 0, s[18:19]
	s_mov_b32 m0, s50
	ds_read_b128 v[216:219], v170 offset:53248
	global_load_lds_dwordx4 v[162:163], off
	ds_read_b128 v[220:223], v170 offset:54272
	ds_read_b128 v[224:227], v170 offset:55296
	ds_read_b128 v[228:231], v170 offset:56320
	s_waitcnt vmcnt(8)
	s_waitcnt lgkmcnt(0)
	s_barrier
	s_setprio 1
	s_waitcnt lgkmcnt(0)
	v_mfma_f32_16x16x32_bf16 v[60:63], v[156:159], v[200:203], v[60:63]
	v_mfma_f32_16x16x32_bf16 v[56:59], v[176:179], v[200:203], v[56:59]
	v_mfma_f32_16x16x32_bf16 v[44:47], v[156:159], v[208:211], v[44:47]
	v_mfma_f32_16x16x32_bf16 v[40:43], v[176:179], v[208:211], v[40:43]
	v_mfma_f32_16x16x32_bf16 v[28:31], v[156:159], v[216:219], v[28:31]
	v_mfma_f32_16x16x32_bf16 v[24:27], v[176:179], v[216:219], v[24:27]
	v_mfma_f32_16x16x32_bf16 v[12:15], v[156:159], v[224:227], v[12:15]
	v_mfma_f32_16x16x32_bf16 v[8:11], v[176:179], v[224:227], v[8:11]
	v_mfma_f32_16x16x32_bf16 v[60:63], v[172:175], v[204:207], v[60:63]
	v_mfma_f32_16x16x32_bf16 v[56:59], v[180:183], v[204:207], v[56:59]
	v_mfma_f32_16x16x32_bf16 v[44:47], v[172:175], v[212:215], v[44:47]
	v_mfma_f32_16x16x32_bf16 v[40:43], v[180:183], v[212:215], v[40:43]
	v_mfma_f32_16x16x32_bf16 v[28:31], v[172:175], v[220:223], v[28:31]
	v_mfma_f32_16x16x32_bf16 v[24:27], v[180:183], v[220:223], v[24:27]
	v_mfma_f32_16x16x32_bf16 v[12:15], v[172:175], v[228:231], v[12:15]
	v_mfma_f32_16x16x32_bf16 v[8:11], v[180:183], v[228:231], v[8:11]
	s_nop 0
	s_nop 0
	v_mfma_f32_16x16x32_bf16 v[52:55], v[184:187], v[200:203], v[52:55]
	v_mfma_f32_16x16x32_bf16 v[48:51], v[192:195], v[200:203], v[48:51]
	v_mfma_f32_16x16x32_bf16 v[36:39], v[184:187], v[208:211], v[36:39]
	v_mfma_f32_16x16x32_bf16 v[32:35], v[192:195], v[208:211], v[32:35]
	v_mfma_f32_16x16x32_bf16 v[20:23], v[184:187], v[216:219], v[20:23]
	v_mfma_f32_16x16x32_bf16 v[16:19], v[192:195], v[216:219], v[16:19]
	v_mfma_f32_16x16x32_bf16 v[4:7], v[184:187], v[224:227], v[4:7]
	v_mfma_f32_16x16x32_bf16 v[0:3], v[192:195], v[224:227], v[0:3]
	v_mfma_f32_16x16x32_bf16 v[52:55], v[188:191], v[204:207], v[52:55]
	v_mfma_f32_16x16x32_bf16 v[48:51], v[196:199], v[204:207], v[48:51]
	v_mfma_f32_16x16x32_bf16 v[36:39], v[188:191], v[212:215], v[36:39]
	v_mfma_f32_16x16x32_bf16 v[32:35], v[196:199], v[212:215], v[32:35]
	v_mfma_f32_16x16x32_bf16 v[20:23], v[188:191], v[220:223], v[20:23]
	v_mfma_f32_16x16x32_bf16 v[16:19], v[196:199], v[220:223], v[16:19]
	v_mfma_f32_16x16x32_bf16 v[4:7], v[188:191], v[228:231], v[4:7]
	v_mfma_f32_16x16x32_bf16 v[0:3], v[196:199], v[228:231], v[0:3]
	s_setprio 0
	s_barrier
	s_add_i32 s68, s68, 2
	s_add_u32 s6, s6, 0x100
	s_addc_u32 s7, s7, 0
	s_add_u32 s52, s52, 0x100
	s_addc_u32 s53, s53, 0
	s_cmp_gt_u32 s68, 13
	s_cbranch_scc0 .LBB0_1295
	s_nop 0
	s_nop 0
	s_nop 0
	s_nop 0
	s_nop 0
	s_nop 0
	s_nop 0
	s_nop 0
	s_nop 0
	s_and_b64 vcc, exec, s[20:21]
	s_cbranch_vccz .LBB0_1298
	s_barrier

; #define PG8_STAGE(bufoff, gbase, voff) do { _Pragma("unroll") for (int _i = 0; _i < 2; ++_i) \
;         __builtin_amdgcn_global_load_lds((const unsigned*)((const char*)(gbase) + (voff)[_i]), (PG8_LAS unsigned*)(lds + (bufoff) + ldsw + _i * 8192), 16, 0, 0); } while (0)
; #define PG8_LDA(dst, b, h) do { _Pragma("unroll") for (int m = 0; m < 4; ++m) _Pragma("unroll") for (int k = 0; k < 2; ++k) dst[m][k] = *(const PG8_LAS bf16x8*)(lds + PG8_SA(b, h) + aoff + m * 2048 + k * 1024); } while (0)
; #define PG8_LDB(dst, b, h) do { _Pragma("unroll") for (int n = 0; n < 2; ++n) _Pragma("unroll") for (int k = 0; k < 2; ++k) dst[n][k] = *(const PG8_LAS bf16x8*)(lds + PG8_SB(b, h) + boff + n * 2048 + k * 1024); } while (0)
; #define PG8_MMA(ai, bj, At, Bt) do { __builtin_amdgcn_s_setprio(1); _Pragma("unroll") for (int m = 0; m < 4; ++m) _Pragma("unroll") for (int n = 0; n < 2; ++n) _Pragma("unroll") for (int k = 0; k < 2; ++k) \
;         acc[ai][bj][m][n] = __builtin_amdgcn_mfma_f32_16x16x32_bf16(Bt[n][k], At[m][k], acc[ai][bj][m][n], 0, 0, 0); __builtin_amdgcn_s_setprio(0); } while (0)
; #define PG8_WAIT_V(n) asm volatile("s_waitcnt vmcnt(" #n ")" ::: "memory")
; #define PG8_WAIT_L(n) asm volatile("s_waitcnt lgkmcnt(" #n ")" ::: "memory")
; template <class Epi, class Sched, bool ALIGN_EPI = false, bool SP2 = false>
; __device__ __forceinline__ void gemm_phase(PG8_LAS unsigned char* lds, const Gemm g, const Sched& S, const Epi& E) {
;     ...
;             const bool last = (t == nt - 2);
;             const char* a1 = cA + (size_t)(t + 1) * kstep;
;             const char* a2 = last ? nA : cA + (size_t)(t + 2) * kstep; const char* b2 = last ? nB : cB + (size_t)(t + 2) * kstep;
;             const char* a3 = a2 + kstep; const char* b3 = b2 + kstep;
;             if (last && has_next) S.a_ready(nxt);
;             if constexpr (SP2) {
;             PG8_LDB(B0, 0, 0); PG8_LDB(B1, 0, 1); PG8_SCHED; PG8_LDA(At, 0, 0); PG8_STAGE(PG8_SA(1, 1), a1 + hstep, voffA);
;             PG8_WAIT_V(8); PG8_WAIT_L(0); PG8_BAR; PG8_MMA(0, 0, At, B0); PG8_MMA(0, 1, At, B1); PG8_BAR; PG8_SCHED;
;             PG8_LDA(At, 0, 1); PG8_STAGE(PG8_SB(0, 0), b2, voffB); PG8_STAGE(PG8_SB(0, 1), b2 + hstep, voffB); PG8_STAGE(PG8_SA(0, 0), a2, voffA);
;             PG8_WAIT_V(8); PG8_WAIT_L(0); PG8_BAR; PG8_MMA(1, 0, At, B0); PG8_MMA(1, 1, At, B1); PG8_BAR; PG8_SCHED;
.LBB0_1319:
	s_add_u32 s34, s30, 0xfffe0080
	s_addc_u32 s35, s31, -1
	s_cmp_eq_u32 s69, 4
	s_cselect_b32 s37, s23, s35
	s_cselect_b32 s36, s53, s34
	s_cselect_b32 s35, s21, s68
	s_cselect_b32 s34, s62, s63
	v_lshl_add_u64 v[216:217], s[30:31], 0, v[128:129]
	s_add_i32 m0, s29, 0xc000
	ds_read_b128 v[144:147], v149
	global_load_lds_dwordx4 v[216:217], off
	v_lshl_add_u64 v[216:217], s[30:31], 0, v[130:131]
	s_add_i32 m0, s29, 0xe000
	ds_read_b128 v[152:155], v149 offset:1024
	global_load_lds_dwordx4 v[216:217], off
	ds_read_b128 v[160:163], v149 offset:2048
	ds_read_b128 v[164:167], v149 offset:3072
	ds_read_b128 v[168:171], v151
	ds_read_b128 v[172:175], v151 offset:1024
	ds_read_b128 v[176:179], v151 offset:2048
	ds_read_b128 v[180:183], v151 offset:3072
	ds_read_b128 v[184:187], v159
	ds_read_b128 v[188:191], v159 offset:1024
	ds_read_b128 v[192:195], v159 offset:2048
	ds_read_b128 v[196:199], v159 offset:3072
	ds_read_b128 v[200:203], v159 offset:4096
	ds_read_b128 v[204:207], v159 offset:5120
	ds_read_b128 v[208:211], v159 offset:6144
	ds_read_b128 v[212:215], v159 offset:7168
	s_waitcnt vmcnt(8)
	s_waitcnt lgkmcnt(0)
	s_barrier
	s_setprio 1
	s_waitcnt lgkmcnt(0)
	v_mfma_f32_16x16x32_bf16 v[124:127], v[144:147], v[184:187], v[124:127]
	v_mfma_f32_16x16x32_bf16 v[120:123], v[160:163], v[184:187], v[120:123]
	v_mfma_f32_16x16x32_bf16 v[108:111], v[144:147], v[192:195], v[108:111]
	v_mfma_f32_16x16x32_bf16 v[104:107], v[160:163], v[192:195], v[104:107]
	v_mfma_f32_16x16x32_bf16 v[92:95], v[144:147], v[200:203], v[92:95]
	v_mfma_f32_16x16x32_bf16 v[88:91], v[160:163], v[200:203], v[88:91]
	v_mfma_f32_16x16x32_bf16 v[76:79], v[144:147], v[208:211], v[76:79]
	v_mfma_f32_16x16x32_bf16 v[72:75], v[160:163], v[208:211], v[72:75]
	v_mfma_f32_16x16x32_bf16 v[124:127], v[152:155], v[188:191], v[124:127]
	v_mfma_f32_16x16x32_bf16 v[120:123], v[164:167], v[188:191], v[120:123]
	v_mfma_f32_16x16x32_bf16 v[108:111], v[152:155], v[196:199], v[108:111]
	v_mfma_f32_16x16x32_bf16 v[104:107], v[164:167], v[196:199], v[104:107]
	v_mfma_f32_16x16x32_bf16 v[92:95], v[152:155], v[204:207], v[92:95]
	v_mfma_f32_16x16x32_bf16 v[88:91], v[164:167], v[204:207], v[88:91]
	v_mfma_f32_16x16x32_bf16 v[76:79], v[152:155], v[212:215], v[76:79]
	v_mfma_f32_16x16x32_bf16 v[72:75], v[164:167], v[212:215], v[72:75]
	s_nop 0
	s_nop 0
	v_mfma_f32_16x16x32_bf16 v[116:119], v[168:171], v[184:187], v[116:119]
	v_mfma_f32_16x16x32_bf16 v[112:115], v[176:179], v[184:187], v[112:115]
	v_mfma_f32_16x16x32_bf16 v[100:103], v[168:171], v[192:195], v[100:103]
	v_mfma_f32_16x16x32_bf16 v[96:99], v[176:179], v[192:195], v[96:99]
	v_mfma_f32_16x16x32_bf16 v[84:87], v[168:171], v[200:203], v[84:87]
	v_mfma_f32_16x16x32_bf16 v[80:83], v[176:179], v[200:203], v[80:83]
	v_mfma_f32_16x16x32_bf16 v[68:71], v[168:171], v[208:211], v[68:71]
	v_mfma_f32_16x16x32_bf16 v[64:67], v[176:179], v[208:211], v[64:67]
	v_mfma_f32_16x16x32_bf16 v[116:119], v[172:175], v[188:191], v[116:119]
	v_mfma_f32_16x16x32_bf16 v[112:115], v[180:183], v[188:191], v[112:115]
	v_mfma_f32_16x16x32_bf16 v[100:103], v[172:175], v[196:199], v[100:103]
	v_mfma_f32_16x16x32_bf16 v[96:99], v[180:183], v[196:199], v[96:99]
	v_mfma_f32_16x16x32_bf16 v[84:87], v[172:175], v[204:207], v[84:87]
	v_mfma_f32_16x16x32_bf16 v[80:83], v[180:183], v[204:207], v[80:83]
	v_mfma_f32_16x16x32_bf16 v[68:71], v[172:175], v[212:215], v[68:71]
	v_mfma_f32_16x16x32_bf16 v[64:67], v[180:183], v[212:215], v[64:67]
	s_setprio 0
	s_barrier
	s_add_i32 s70, s51, s39
	v_lshl_add_u64 v[216:217], s[34:35], 0, v[138:139]
	s_mov_b32 m0, s70
	v_lshl_add_u64 v[218:219], s[34:35], 0, v[142:143]
	global_load_lds_dwordx4 v[216:217], off
	s_add_i32 m0, s70, 0x2000
	s_add_u32 s70, s34, 0x20000
	s_addc_u32 s71, s35, 0
	s_add_i32 s72, s56, s39
	global_load_lds_dwordx4 v[218:219], off
	v_lshl_add_u64 v[220:221], s[70:71], 0, v[138:139]
	s_mov_b32 m0, s72
	v_lshl_add_u64 v[222:223], s[36:37], 0, v[140:141]
	global_load_lds_dwordx4 v[220:221], off
	v_lshl_add_u64 v[220:221], s[70:71], 0, v[142:143]
	s_add_i32 m0, s72, 0x2000
	ds_read_b128 v[184:187], v159 offset:16384
	global_load_lds_dwordx4 v[220:221], off
	v_lshl_add_u64 v[220:221], s[36:37], 0, v[136:137]
	s_mov_b32 m0, s29
	ds_read_b128 v[188:191], v159 offset:17408
	global_load_lds_dwordx4 v[220:221], off
	s_mov_b32 m0, s40
	ds_read_b128 v[192:195], v159 offset:18432
	global_load_lds_dwordx4 v[222:223], off
	ds_read_b128 v[196:199], v159 offset:19456
	ds_read_b128 v[200:203], v159 offset:20480
	ds_read_b128 v[204:207], v159 offset:21504
	ds_read_b128 v[208:211], v159 offset:22528
	ds_read_b128 v[212:215], v159 offset:23552
	s_waitcnt vmcnt(8)
	s_waitcnt lgkmcnt(0)
	s_barrier
; #define PG8_STAGE(bufoff, gbase, voff) do { _Pragma("unroll") for (int _i = 0; _i < 2; ++_i) \
;         __builtin_amdgcn_global_load_lds((const unsigned*)((const char*)(gbase) + (voff)[_i]), (PG8_LAS unsigned*)(lds + (bufoff) + ldsw + _i * 8192), 16, 0, 0); } while (0)
; #define PG8_LDA(dst, b, h) do { _Pragma("unroll") for (int m = 0; m < 4; ++m) _Pragma("unroll") for (int k = 0; k < 2; ++k) dst[m][k] = *(const PG8_LAS bf16x8*)(lds + PG8_SA(b, h) + aoff + m * 2048 + k * 1024); } while (0)
; #define PG8_LDB(dst, b, h) do { _Pragma("unroll") for (int n = 0; n < 2; ++n) _Pragma("unroll") for (int k = 0; k < 2; ++k) dst[n][k] = *(const PG8_LAS bf16x8*)(lds + PG8_SB(b, h) + boff + n * 2048 + k * 1024); } while (0)
; #define PG8_MMA(ai, bj, At, Bt) do { __builtin_amdgcn_s_setprio(1); _Pragma("unroll") for (int m = 0; m < 4; ++m) _Pragma("unroll") for (int n = 0; n < 2; ++n) _Pragma("unroll") for (int k = 0; k < 2; ++k) \
;         acc[ai][bj][m][n] = __builtin_amdgcn_mfma_f32_16x16x32_bf16(Bt[n][k], At[m][k], acc[ai][bj][m][n], 0, 0, 0); __builtin_amdgcn_s_setprio(0); } while (0)
; #define PG8_WAIT_V(n) asm volatile("s_waitcnt vmcnt(" #n ")" ::: "memory")
; #define PG8_WAIT_L(n) asm volatile("s_waitcnt lgkmcnt(" #n ")" ::: "memory")
; #define PG8_BAR __builtin_amdgcn_s_barrier()
; #define PG8_SCHED __builtin_amdgcn_sched_barrier(0)
; template <class Epi, class Sched, bool ALIGN_EPI = false, bool SP2 = false>
; __device__ __forceinline__ void gemm_phase(PG8_LAS unsigned char* lds, const Gemm g, const Sched& S, const Epi& E) {
;     ...
;             PG8_WAIT_V(8); PG8_WAIT_L(0); PG8_BAR; PG8_MMA(1, 0, At, B0); PG8_MMA(1, 1, At, B1); PG8_BAR; PG8_SCHED;
;             PG8_LDB(B0, 1, 0); PG8_LDB(B1, 1, 1); PG8_SCHED; PG8_LDA(At, 1, 0); PG8_STAGE(PG8_SA(0, 1), a2 + hstep, voffA);
;             PG8_WAIT_V(8); PG8_WAIT_L(0); PG8_BAR; PG8_MMA(0, 0, At, B0); PG8_MMA(0, 1, At, B1); PG8_BAR; PG8_SCHED;
	s_setprio 1
	s_waitcnt lgkmcnt(0)
	v_mfma_f32_16x16x32_bf16 v[60:63], v[144:147], v[184:187], v[60:63]
	v_mfma_f32_16x16x32_bf16 v[56:59], v[160:163], v[184:187], v[56:59]
	v_mfma_f32_16x16x32_bf16 v[44:47], v[144:147], v[192:195], v[44:47]
	v_mfma_f32_16x16x32_bf16 v[40:43], v[160:163], v[192:195], v[40:43]
	v_mfma_f32_16x16x32_bf16 v[28:31], v[144:147], v[200:203], v[28:31]
	v_mfma_f32_16x16x32_bf16 v[24:27], v[160:163], v[200:203], v[24:27]
	v_mfma_f32_16x16x32_bf16 v[12:15], v[144:147], v[208:211], v[12:15]
	v_mfma_f32_16x16x32_bf16 v[8:11], v[160:163], v[208:211], v[8:11]
	v_mfma_f32_16x16x32_bf16 v[60:63], v[152:155], v[188:191], v[60:63]
	v_mfma_f32_16x16x32_bf16 v[56:59], v[164:167], v[188:191], v[56:59]
	v_mfma_f32_16x16x32_bf16 v[44:47], v[152:155], v[196:199], v[44:47]
	v_mfma_f32_16x16x32_bf16 v[40:43], v[164:167], v[196:199], v[40:43]
	v_mfma_f32_16x16x32_bf16 v[28:31], v[152:155], v[204:207], v[28:31]
	v_mfma_f32_16x16x32_bf16 v[24:27], v[164:167], v[204:207], v[24:27]
	v_mfma_f32_16x16x32_bf16 v[12:15], v[152:155], v[212:215], v[12:15]
	v_mfma_f32_16x16x32_bf16 v[8:11], v[164:167], v[212:215], v[8:11]
	s_nop 0
	s_nop 0
	v_mfma_f32_16x16x32_bf16 v[52:55], v[168:171], v[184:187], v[52:55]
	v_mfma_f32_16x16x32_bf16 v[48:51], v[176:179], v[184:187], v[48:51]
	v_mfma_f32_16x16x32_bf16 v[36:39], v[168:171], v[192:195], v[36:39]
	v_mfma_f32_16x16x32_bf16 v[32:35], v[176:179], v[192:195], v[32:35]
	v_mfma_f32_16x16x32_bf16 v[20:23], v[168:171], v[200:203], v[20:23]
	v_mfma_f32_16x16x32_bf16 v[16:19], v[176:179], v[200:203], v[16:19]
	v_mfma_f32_16x16x32_bf16 v[4:7], v[168:171], v[208:211], v[4:7]
	v_mfma_f32_16x16x32_bf16 v[0:3], v[176:179], v[208:211], v[0:3]
	v_mfma_f32_16x16x32_bf16 v[52:55], v[172:175], v[188:191], v[52:55]
	v_mfma_f32_16x16x32_bf16 v[48:51], v[180:183], v[188:191], v[48:51]
	v_mfma_f32_16x16x32_bf16 v[36:39], v[172:175], v[196:199], v[36:39]
	v_mfma_f32_16x16x32_bf16 v[32:35], v[180:183], v[196:199], v[32:35]
	v_mfma_f32_16x16x32_bf16 v[20:23], v[172:175], v[204:207], v[20:23]
	v_mfma_f32_16x16x32_bf16 v[16:19], v[180:183], v[204:207], v[16:19]
	v_mfma_f32_16x16x32_bf16 v[4:7], v[172:175], v[212:215], v[4:7]
	v_mfma_f32_16x16x32_bf16 v[0:3], v[180:183], v[212:215], v[0:3]
	s_setprio 0
	s_barrier
	s_add_i32 s70, 0, 0x18000
	s_add_i32 s71, 0, 0x1c000
	s_add_u32 s36, s36, 0x20000
	s_addc_u32 s37, s37, 0
	s_mov_b32 m0, s41
	v_lshl_add_u64 v[224:225], s[36:37], 0, v[136:137]
	global_load_lds_dwordx4 v[224:225], off
	v_lshl_add_u64 v[224:225], s[36:37], 0, v[140:141]
	s_mov_b32 m0, s42
	v_add_u32_e32 v164, s70, v157
	global_load_lds_dwordx4 v[224:225], off
	v_add_u32_e32 v180, s71, v157
	ds_read_b128 v[144:147], v164
	ds_read_b128 v[152:155], v164 offset:1024
	ds_read_b128 v[160:163], v164 offset:2048
	ds_read_b128 v[164:167], v164 offset:3072
	ds_read_b128 v[168:171], v180
	ds_read_b128 v[172:175], v180 offset:1024
	ds_read_b128 v[176:179], v180 offset:2048
	ds_read_b128 v[180:183], v180 offset:3072
	ds_read_b128 v[184:187], v159 offset:32768
	ds_read_b128 v[188:191], v159 offset:33792
	ds_read_b128 v[192:195], v159 offset:34816
	ds_read_b128 v[196:199], v159 offset:35840
	ds_read_b128 v[200:203], v159 offset:36864
	ds_read_b128 v[204:207], v159 offset:37888
	ds_read_b128 v[208:211], v159 offset:38912
	ds_read_b128 v[212:215], v159 offset:39936
	s_waitcnt vmcnt(8)
	s_waitcnt lgkmcnt(0)
	s_barrier
	s_setprio 1
	s_waitcnt lgkmcnt(0)
	v_mfma_f32_16x16x32_bf16 v[124:127], v[144:147], v[184:187], v[124:127]
	v_mfma_f32_16x16x32_bf16 v[120:123], v[160:163], v[184:187], v[120:123]
	v_mfma_f32_16x16x32_bf16 v[108:111], v[144:147], v[192:195], v[108:111]
	v_mfma_f32_16x16x32_bf16 v[104:107], v[160:163], v[192:195], v[104:107]
	v_mfma_f32_16x16x32_bf16 v[92:95], v[144:147], v[200:203], v[92:95]
	v_mfma_f32_16x16x32_bf16 v[88:91], v[160:163], v[200:203], v[88:91]
	v_mfma_f32_16x16x32_bf16 v[76:79], v[144:147], v[208:211], v[76:79]
	v_mfma_f32_16x16x32_bf16 v[72:75], v[160:163], v[208:211], v[72:75]
	v_mfma_f32_16x16x32_bf16 v[124:127], v[152:155], v[188:191], v[124:127]
	v_mfma_f32_16x16x32_bf16 v[120:123], v[164:167], v[188:191], v[120:123]
	v_mfma_f32_16x16x32_bf16 v[108:111], v[152:155], v[196:199], v[108:111]
	v_mfma_f32_16x16x32_bf16 v[104:107], v[164:167], v[196:199], v[104:107]
	v_mfma_f32_16x16x32_bf16 v[92:95], v[152:155], v[204:207], v[92:95]
	v_mfma_f32_16x16x32_bf16 v[88:91], v[164:167], v[204:207], v[88:91]
	v_mfma_f32_16x16x32_bf16 v[76:79], v[152:155], v[212:215], v[76:79]
	v_mfma_f32_16x16x32_bf16 v[72:75], v[164:167], v[212:215], v[72:75]
	s_nop 0
	s_nop 0
	v_mfma_f32_16x16x32_bf16 v[116:119], v[168:171], v[184:187], v[116:119]
	v_mfma_f32_16x16x32_bf16 v[112:115], v[176:179], v[184:187], v[112:115]
	v_mfma_f32_16x16x32_bf16 v[100:103], v[168:171], v[192:195], v[100:103]
	v_mfma_f32_16x16x32_bf16 v[96:99], v[176:179], v[192:195], v[96:99]
	v_mfma_f32_16x16x32_bf16 v[84:87], v[168:171], v[200:203], v[84:87]
	v_mfma_f32_16x16x32_bf16 v[80:83], v[176:179], v[200:203], v[80:83]
	v_mfma_f32_16x16x32_bf16 v[68:71], v[168:171], v[208:211], v[68:71]
	v_mfma_f32_16x16x32_bf16 v[64:67], v[176:179], v[208:211], v[64:67]
	v_mfma_f32_16x16x32_bf16 v[116:119], v[172:175], v[188:191], v[116:119]
	v_mfma_f32_16x16x32_bf16 v[112:115], v[180:183], v[188:191], v[112:115]
	v_mfma_f32_16x16x32_bf16 v[100:103], v[172:175], v[196:199], v[100:103]
	v_mfma_f32_16x16x32_bf16 v[96:99], v[180:183], v[196:199], v[96:99]
	v_mfma_f32_16x16x32_bf16 v[84:87], v[172:175], v[204:207], v[84:87]
	v_mfma_f32_16x16x32_bf16 v[80:83], v[180:183], v[204:207], v[80:83]
	v_mfma_f32_16x16x32_bf16 v[68:71], v[172:175], v[212:215], v[68:71]
	v_mfma_f32_16x16x32_bf16 v[64:67], v[180:183], v[212:215], v[64:67]
	s_setprio 0
	s_barrier
; #define PG8_STAGE(bufoff, gbase, voff) do { _Pragma("unroll") for (int _i = 0; _i < 2; ++_i) \
;         __builtin_amdgcn_global_load_lds((const unsigned*)((const char*)(gbase) + (voff)[_i]), (PG8_LAS unsigned*)(lds + (bufoff) + ldsw + _i * 8192), 16, 0, 0); } while (0)
; #define PG8_LDA(dst, b, h) do { _Pragma("unroll") for (int m = 0; m < 4; ++m) _Pragma("unroll") for (int k = 0; k < 2; ++k) dst[m][k] = *(const PG8_LAS bf16x8*)(lds + PG8_SA(b, h) + aoff + m * 2048 + k * 1024); } while (0)
; #define PG8_MMA(ai, bj, At, Bt) do { __builtin_amdgcn_s_setprio(1); _Pragma("unroll") for (int m = 0; m < 4; ++m) _Pragma("unroll") for (int n = 0; n < 2; ++n) _Pragma("unroll") for (int k = 0; k < 2; ++k) \
;         acc[ai][bj][m][n] = __builtin_amdgcn_mfma_f32_16x16x32_bf16(Bt[n][k], At[m][k], acc[ai][bj][m][n], 0, 0, 0); __builtin_amdgcn_s_setprio(0); } while (0)
; #define PG8_WAIT_V(n) asm volatile("s_waitcnt vmcnt(" #n ")" ::: "memory")
; #define PG8_WAIT_L(n) asm volatile("s_waitcnt lgkmcnt(" #n ")" ::: "memory")
; #define PG8_BAR __builtin_amdgcn_s_barrier()
; #define PG8_SCHED __builtin_amdgcn_sched_barrier(0)
; template <class Epi, class Sched, bool ALIGN_EPI = false, bool SP2 = false>
; __device__ __forceinline__ void gemm_phase(PG8_LAS unsigned char* lds, const Gemm g, const Sched& S, const Epi& E) {
;     ...
;             PG8_LDA(At, 1, 1); PG8_STAGE(PG8_SB(1, 0), b3, voffB); PG8_STAGE(PG8_SB(1, 1), b3 + hstep, voffB); PG8_STAGE(PG8_SA(1, 0), a3, voffA);
;             PG8_WAIT_V(8); PG8_WAIT_L(0); PG8_BAR; PG8_MMA(1, 0, At, B0); PG8_MMA(1, 1, At, B1); PG8_BAR; PG8_SCHED;
;     ...
;         if constexpr (ALIGN_EPI) { if (wr == 0) PG8_BAR; }
	s_add_i32 s36, s70, s39
	v_lshl_add_u64 v[216:217], v[216:217], 0, s[4:5]
	s_mov_b32 m0, s36
	ds_read_b128 v[184:187], v159 offset:49152
	global_load_lds_dwordx4 v[216:217], off
	s_add_i32 m0, s36, 0x2000
	s_add_u32 s34, s34, 0x20080
	v_lshl_add_u64 v[216:217], v[218:219], 0, s[4:5]
	s_addc_u32 s35, s35, 0
	s_add_i32 s36, s71, s39
	global_load_lds_dwordx4 v[216:217], off
	v_lshl_add_u64 v[216:217], s[34:35], 0, v[138:139]
	s_mov_b32 m0, s36
	ds_read_b128 v[188:191], v159 offset:50176
	global_load_lds_dwordx4 v[216:217], off
	v_lshl_add_u64 v[216:217], s[34:35], 0, v[142:143]
	s_add_i32 m0, s36, 0x2000
	ds_read_b128 v[192:195], v159 offset:51200
	global_load_lds_dwordx4 v[216:217], off
	v_lshl_add_u64 v[216:217], v[220:221], 0, s[4:5]
	s_mov_b32 m0, s44
	ds_read_b128 v[196:199], v159 offset:52224
	global_load_lds_dwordx4 v[216:217], off
	v_lshl_add_u64 v[216:217], v[222:223], 0, s[4:5]
	s_mov_b32 m0, s45
	ds_read_b128 v[200:203], v159 offset:53248
	global_load_lds_dwordx4 v[216:217], off
	ds_read_b128 v[204:207], v159 offset:54272
	ds_read_b128 v[208:211], v159 offset:55296
	ds_read_b128 v[212:215], v159 offset:56320
	s_waitcnt vmcnt(8)
	s_waitcnt lgkmcnt(0)
	s_barrier
	s_setprio 1
	s_waitcnt lgkmcnt(0)
	v_mfma_f32_16x16x32_bf16 v[60:63], v[144:147], v[184:187], v[60:63]
	v_mfma_f32_16x16x32_bf16 v[56:59], v[160:163], v[184:187], v[56:59]
	v_mfma_f32_16x16x32_bf16 v[44:47], v[144:147], v[192:195], v[44:47]
	v_mfma_f32_16x16x32_bf16 v[40:43], v[160:163], v[192:195], v[40:43]
	v_mfma_f32_16x16x32_bf16 v[28:31], v[144:147], v[200:203], v[28:31]
	v_mfma_f32_16x16x32_bf16 v[24:27], v[160:163], v[200:203], v[24:27]
	v_mfma_f32_16x16x32_bf16 v[12:15], v[144:147], v[208:211], v[12:15]
	v_mfma_f32_16x16x32_bf16 v[8:11], v[160:163], v[208:211], v[8:11]
	v_mfma_f32_16x16x32_bf16 v[60:63], v[152:155], v[188:191], v[60:63]
	v_mfma_f32_16x16x32_bf16 v[56:59], v[164:167], v[188:191], v[56:59]
	v_mfma_f32_16x16x32_bf16 v[44:47], v[152:155], v[196:199], v[44:47]
	v_mfma_f32_16x16x32_bf16 v[40:43], v[164:167], v[196:199], v[40:43]
	v_mfma_f32_16x16x32_bf16 v[28:31], v[152:155], v[204:207], v[28:31]
	v_mfma_f32_16x16x32_bf16 v[24:27], v[164:167], v[204:207], v[24:27]
	v_mfma_f32_16x16x32_bf16 v[12:15], v[152:155], v[212:215], v[12:15]
	v_mfma_f32_16x16x32_bf16 v[8:11], v[164:167], v[212:215], v[8:11]
	s_nop 0
	s_nop 0
	v_mfma_f32_16x16x32_bf16 v[52:55], v[168:171], v[184:187], v[52:55]
	v_mfma_f32_16x16x32_bf16 v[48:51], v[176:179], v[184:187], v[48:51]
	v_mfma_f32_16x16x32_bf16 v[36:39], v[168:171], v[192:195], v[36:39]
	v_mfma_f32_16x16x32_bf16 v[32:35], v[176:179], v[192:195], v[32:35]
	v_mfma_f32_16x16x32_bf16 v[20:23], v[168:171], v[200:203], v[20:23]
	v_mfma_f32_16x16x32_bf16 v[16:19], v[176:179], v[200:203], v[16:19]
	v_mfma_f32_16x16x32_bf16 v[4:7], v[168:171], v[208:211], v[4:7]
	v_mfma_f32_16x16x32_bf16 v[0:3], v[176:179], v[208:211], v[0:3]
	v_mfma_f32_16x16x32_bf16 v[52:55], v[172:175], v[188:191], v[52:55]
	v_mfma_f32_16x16x32_bf16 v[48:51], v[180:183], v[188:191], v[48:51]
	v_mfma_f32_16x16x32_bf16 v[36:39], v[172:175], v[196:199], v[36:39]
	v_mfma_f32_16x16x32_bf16 v[32:35], v[180:183], v[196:199], v[32:35]
	v_mfma_f32_16x16x32_bf16 v[20:23], v[172:175], v[204:207], v[20:23]
	v_mfma_f32_16x16x32_bf16 v[16:19], v[180:183], v[204:207], v[16:19]
	v_mfma_f32_16x16x32_bf16 v[4:7], v[172:175], v[212:215], v[4:7]
	v_mfma_f32_16x16x32_bf16 v[0:3], v[180:183], v[212:215], v[0:3]
	s_setprio 0
	s_barrier
	s_add_i32 s69, s69, 2
	s_add_u32 s30, s30, 0x100
	s_addc_u32 s31, s31, 0
	s_add_u32 s63, s63, 0x100
	s_addc_u32 s68, s68, 0
	s_cmp_gt_u32 s69, 5
	s_cbranch_scc0 .LBB0_1319
	s_nop 0
	s_nop 0
	s_nop 0
	s_nop 0
	s_nop 0
	s_nop 0
	s_nop 0
	s_nop 0
	s_nop 0
	s_and_b64 vcc, exec, s[6:7]
	s_cbranch_vccz .LBB0_1322
	s_barrier

; #define PG8_STAGE(bufoff, gbase, voff) do { _Pragma("unroll") for (int _i = 0; _i < 2; ++_i) \
;         __builtin_amdgcn_global_load_lds((const unsigned*)((const char*)(gbase) + (voff)[_i]), (PG8_LAS unsigned*)(lds + (bufoff) + ldsw + _i * 8192), 16, 0, 0); } while (0)
; #define PG8_LDA(dst, b, h) do { _Pragma("unroll") for (int m = 0; m < 4; ++m) _Pragma("unroll") for (int k = 0; k < 2; ++k) dst[m][k] = *(const PG8_LAS bf16x8*)(lds + PG8_SA(b, h) + aoff + m * 2048 + k * 1024); } while (0)
; #define PG8_LDB(dst, b, h) do { _Pragma("unroll") for (int n = 0; n < 2; ++n) _Pragma("unroll") for (int k = 0; k < 2; ++k) dst[n][k] = *(const PG8_LAS bf16x8*)(lds + PG8_SB(b, h) + boff + n * 2048 + k * 1024); } while (0)
; #define PG8_MMA(ai, bj, At, Bt) do { __builtin_amdgcn_s_setprio(1); _Pragma("unroll") for (int m = 0; m < 4; ++m) _Pragma("unroll") for (int n = 0; n < 2; ++n) _Pragma("unroll") for (int k = 0; k < 2; ++k) \
;         acc[ai][bj][m][n] = __builtin_amdgcn_mfma_f32_16x16x32_bf16(Bt[n][k], At[m][k], acc[ai][bj][m][n], 0, 0, 0); __builtin_amdgcn_s_setprio(0); } while (0)
; #define PG8_WAIT_V(n) asm volatile("s_waitcnt vmcnt(" #n ")" ::: "memory")
; #define PG8_WAIT_L(n) asm volatile("s_waitcnt lgkmcnt(" #n ")" ::: "memory")
; template <class Epi, class Sched, bool ALIGN_EPI = false, bool SP2 = false>
; __device__ __forceinline__ void gemm_phase(PG8_LAS unsigned char* lds, const Gemm g, const Sched& S, const Epi& E) {
;     ...
;             const bool last = (t == nt - 2);
;             const char* a1 = cA + (size_t)(t + 1) * kstep;
;             const char* a2 = last ? nA : cA + (size_t)(t + 2) * kstep; const char* b2 = last ? nB : cB + (size_t)(t + 2) * kstep;
;             const char* a3 = a2 + kstep; const char* b3 = b2 + kstep;
;             if (last && has_next) S.a_ready(nxt);
;             if constexpr (SP2) {
;             PG8_LDB(B0, 0, 0); PG8_LDB(B1, 0, 1); PG8_SCHED; PG8_LDA(At, 0, 0); PG8_STAGE(PG8_SA(1, 1), a1 + hstep, voffA);
;             PG8_WAIT_V(8); PG8_WAIT_L(0); PG8_BAR; PG8_MMA(0, 0, At, B0); PG8_MMA(0, 1, At, B1); PG8_BAR; PG8_SCHED;
;             PG8_LDA(At, 0, 1); PG8_STAGE(PG8_SB(0, 0), b2, voffB); PG8_STAGE(PG8_SB(0, 1), b2 + hstep, voffB); PG8_STAGE(PG8_SA(0, 0), a2, voffA);
;             PG8_WAIT_V(8); PG8_WAIT_L(0); PG8_BAR; PG8_MMA(1, 0, At, B0); PG8_MMA(1, 1, At, B1); PG8_BAR; PG8_SCHED;
.LBB0_1400:
	s_add_u32 s26, s24, 0xfffc0080
	s_addc_u32 s27, s25, -1
	s_cmp_eq_u32 s60, 12
	s_cselect_b32 s29, s15, s27
	s_cselect_b32 s28, s21, s26
	s_cselect_b32 s27, s13, s59
	s_cselect_b32 s26, s57, s58
	v_lshl_add_u64 v[214:215], s[24:25], 0, v[132:133]
	s_add_i32 m0, s23, 0xc000
	ds_read_b128 v[140:143], v147
	global_load_lds_dwordx4 v[214:215], off
	v_lshl_add_u64 v[214:215], s[24:25], 0, v[134:135]
	s_add_i32 m0, s23, 0xe000
	ds_read_b128 v[154:157], v147 offset:1024
	global_load_lds_dwordx4 v[214:215], off
	ds_read_b128 v[158:161], v147 offset:2048
	ds_read_b128 v[162:165], v147 offset:3072
	ds_read_b128 v[166:169], v149
	ds_read_b128 v[170:173], v149 offset:1024
	ds_read_b128 v[174:177], v149 offset:2048
	ds_read_b128 v[178:181], v149 offset:3072
	ds_read_b128 v[182:185], v151
	ds_read_b128 v[186:189], v151 offset:1024
	ds_read_b128 v[190:193], v151 offset:2048
	ds_read_b128 v[194:197], v151 offset:3072
	ds_read_b128 v[198:201], v151 offset:4096
	ds_read_b128 v[202:205], v151 offset:5120
	ds_read_b128 v[206:209], v151 offset:6144
	ds_read_b128 v[210:213], v151 offset:7168
	s_waitcnt vmcnt(8)
	s_waitcnt lgkmcnt(0)
	s_barrier
	s_setprio 1
	s_waitcnt lgkmcnt(0)
	v_mfma_f32_16x16x32_bf16 v[124:127], v[140:143], v[182:185], v[124:127]
	v_mfma_f32_16x16x32_bf16 v[120:123], v[158:161], v[182:185], v[120:123]
	v_mfma_f32_16x16x32_bf16 v[108:111], v[140:143], v[190:193], v[108:111]
	v_mfma_f32_16x16x32_bf16 v[104:107], v[158:161], v[190:193], v[104:107]
	v_mfma_f32_16x16x32_bf16 v[92:95], v[140:143], v[198:201], v[92:95]
	v_mfma_f32_16x16x32_bf16 v[88:91], v[158:161], v[198:201], v[88:91]
	v_mfma_f32_16x16x32_bf16 v[76:79], v[140:143], v[206:209], v[76:79]
	v_mfma_f32_16x16x32_bf16 v[72:75], v[158:161], v[206:209], v[72:75]
	v_mfma_f32_16x16x32_bf16 v[124:127], v[154:157], v[186:189], v[124:127]
	v_mfma_f32_16x16x32_bf16 v[120:123], v[162:165], v[186:189], v[120:123]
	v_mfma_f32_16x16x32_bf16 v[108:111], v[154:157], v[194:197], v[108:111]
	v_mfma_f32_16x16x32_bf16 v[104:107], v[162:165], v[194:197], v[104:107]
	v_mfma_f32_16x16x32_bf16 v[92:95], v[154:157], v[202:205], v[92:95]
	v_mfma_f32_16x16x32_bf16 v[88:91], v[162:165], v[202:205], v[88:91]
	v_mfma_f32_16x16x32_bf16 v[76:79], v[154:157], v[210:213], v[76:79]
	v_mfma_f32_16x16x32_bf16 v[72:75], v[162:165], v[210:213], v[72:75]
	s_nop 0
	s_nop 0
	v_mfma_f32_16x16x32_bf16 v[116:119], v[166:169], v[182:185], v[116:119]
	v_mfma_f32_16x16x32_bf16 v[112:115], v[174:177], v[182:185], v[112:115]
	v_mfma_f32_16x16x32_bf16 v[100:103], v[166:169], v[190:193], v[100:103]
	v_mfma_f32_16x16x32_bf16 v[96:99], v[174:177], v[190:193], v[96:99]
	v_mfma_f32_16x16x32_bf16 v[84:87], v[166:169], v[198:201], v[84:87]
	v_mfma_f32_16x16x32_bf16 v[80:83], v[174:177], v[198:201], v[80:83]
	v_mfma_f32_16x16x32_bf16 v[68:71], v[166:169], v[206:209], v[68:71]
	v_mfma_f32_16x16x32_bf16 v[64:67], v[174:177], v[206:209], v[64:67]
	v_mfma_f32_16x16x32_bf16 v[116:119], v[170:173], v[186:189], v[116:119]
	v_mfma_f32_16x16x32_bf16 v[112:115], v[178:181], v[186:189], v[112:115]
	v_mfma_f32_16x16x32_bf16 v[100:103], v[170:173], v[194:197], v[100:103]
	v_mfma_f32_16x16x32_bf16 v[96:99], v[178:181], v[194:197], v[96:99]
	v_mfma_f32_16x16x32_bf16 v[84:87], v[170:173], v[202:205], v[84:87]
	v_mfma_f32_16x16x32_bf16 v[80:83], v[178:181], v[202:205], v[80:83]
	v_mfma_f32_16x16x32_bf16 v[68:71], v[170:173], v[210:213], v[68:71]
	v_mfma_f32_16x16x32_bf16 v[64:67], v[178:181], v[210:213], v[64:67]
	s_setprio 0
	s_barrier
	s_add_i32 s61, s42, s30
	v_lshl_add_u64 v[214:215], s[26:27], 0, v[128:129]
	s_mov_b32 m0, s61
	v_lshl_add_u64 v[216:217], s[26:27], 0, v[130:131]
	global_load_lds_dwordx4 v[214:215], off
	s_add_i32 m0, s61, 0x2000
	s_add_u32 s62, s26, 0x40000
	s_addc_u32 s63, s27, 0
	s_add_i32 s61, s43, s30
	global_load_lds_dwordx4 v[216:217], off
	v_lshl_add_u64 v[218:219], s[62:63], 0, v[128:129]
	s_mov_b32 m0, s61
	v_lshl_add_u64 v[220:221], s[28:29], 0, v[130:131]
	global_load_lds_dwordx4 v[218:219], off
	v_lshl_add_u64 v[218:219], s[62:63], 0, v[130:131]
	s_add_i32 m0, s61, 0x2000
	ds_read_b128 v[182:185], v151 offset:16384
	global_load_lds_dwordx4 v[218:219], off
	v_lshl_add_u64 v[218:219], s[28:29], 0, v[128:129]
	s_mov_b32 m0, s23
	ds_read_b128 v[186:189], v151 offset:17408
	global_load_lds_dwordx4 v[218:219], off
	s_mov_b32 m0, s31
	ds_read_b128 v[190:193], v151 offset:18432
	global_load_lds_dwordx4 v[220:221], off
	ds_read_b128 v[194:197], v151 offset:19456
	ds_read_b128 v[198:201], v151 offset:20480
	ds_read_b128 v[202:205], v151 offset:21504
	ds_read_b128 v[206:209], v151 offset:22528
	ds_read_b128 v[210:213], v151 offset:23552
	s_waitcnt vmcnt(8)
	s_waitcnt lgkmcnt(0)
	s_barrier
; #define PG8_STAGE(bufoff, gbase, voff) do { _Pragma("unroll") for (int _i = 0; _i < 2; ++_i) \
;         __builtin_amdgcn_global_load_lds((const unsigned*)((const char*)(gbase) + (voff)[_i]), (PG8_LAS unsigned*)(lds + (bufoff) + ldsw + _i * 8192), 16, 0, 0); } while (0)
; #define PG8_LDA(dst, b, h) do { _Pragma("unroll") for (int m = 0; m < 4; ++m) _Pragma("unroll") for (int k = 0; k < 2; ++k) dst[m][k] = *(const PG8_LAS bf16x8*)(lds + PG8_SA(b, h) + aoff + m * 2048 + k * 1024); } while (0)
; #define PG8_LDB(dst, b, h) do { _Pragma("unroll") for (int n = 0; n < 2; ++n) _Pragma("unroll") for (int k = 0; k < 2; ++k) dst[n][k] = *(const PG8_LAS bf16x8*)(lds + PG8_SB(b, h) + boff + n * 2048 + k * 1024); } while (0)
; #define PG8_MMA(ai, bj, At, Bt) do { __builtin_amdgcn_s_setprio(1); _Pragma("unroll") for (int m = 0; m < 4; ++m) _Pragma("unroll") for (int n = 0; n < 2; ++n) _Pragma("unroll") for (int k = 0; k < 2; ++k) \
;         acc[ai][bj][m][n] = __builtin_amdgcn_mfma_f32_16x16x32_bf16(Bt[n][k], At[m][k], acc[ai][bj][m][n], 0, 0, 0); __builtin_amdgcn_s_setprio(0); } while (0)
; #define PG8_WAIT_V(n) asm volatile("s_waitcnt vmcnt(" #n ")" ::: "memory")
; #define PG8_WAIT_L(n) asm volatile("s_waitcnt lgkmcnt(" #n ")" ::: "memory")
; #define PG8_BAR __builtin_amdgcn_s_barrier()
; #define PG8_SCHED __builtin_amdgcn_sched_barrier(0)
; template <class Epi, class Sched, bool ALIGN_EPI = false, bool SP2 = false>
; __device__ __forceinline__ void gemm_phase(PG8_LAS unsigned char* lds, const Gemm g, const Sched& S, const Epi& E) {
;     ...
;             PG8_WAIT_V(8); PG8_WAIT_L(0); PG8_BAR; PG8_MMA(1, 0, At, B0); PG8_MMA(1, 1, At, B1); PG8_BAR; PG8_SCHED;
;             PG8_LDB(B0, 1, 0); PG8_LDB(B1, 1, 1); PG8_SCHED; PG8_LDA(At, 1, 0); PG8_STAGE(PG8_SA(0, 1), a2 + hstep, voffA);
;             PG8_WAIT_V(8); PG8_WAIT_L(0); PG8_BAR; PG8_MMA(0, 0, At, B0); PG8_MMA(0, 1, At, B1); PG8_BAR; PG8_SCHED;
	s_setprio 1
	s_waitcnt lgkmcnt(0)
	v_mfma_f32_16x16x32_bf16 v[60:63], v[140:143], v[182:185], v[60:63]
	v_mfma_f32_16x16x32_bf16 v[56:59], v[158:161], v[182:185], v[56:59]
	v_mfma_f32_16x16x32_bf16 v[44:47], v[140:143], v[190:193], v[44:47]
	v_mfma_f32_16x16x32_bf16 v[40:43], v[158:161], v[190:193], v[40:43]
	v_mfma_f32_16x16x32_bf16 v[28:31], v[140:143], v[198:201], v[28:31]
	v_mfma_f32_16x16x32_bf16 v[24:27], v[158:161], v[198:201], v[24:27]
	v_mfma_f32_16x16x32_bf16 v[12:15], v[140:143], v[206:209], v[12:15]
	v_mfma_f32_16x16x32_bf16 v[8:11], v[158:161], v[206:209], v[8:11]
	v_mfma_f32_16x16x32_bf16 v[60:63], v[154:157], v[186:189], v[60:63]
	v_mfma_f32_16x16x32_bf16 v[56:59], v[162:165], v[186:189], v[56:59]
	v_mfma_f32_16x16x32_bf16 v[44:47], v[154:157], v[194:197], v[44:47]
	v_mfma_f32_16x16x32_bf16 v[40:43], v[162:165], v[194:197], v[40:43]
	v_mfma_f32_16x16x32_bf16 v[28:31], v[154:157], v[202:205], v[28:31]
	v_mfma_f32_16x16x32_bf16 v[24:27], v[162:165], v[202:205], v[24:27]
	v_mfma_f32_16x16x32_bf16 v[12:15], v[154:157], v[210:213], v[12:15]
	v_mfma_f32_16x16x32_bf16 v[8:11], v[162:165], v[210:213], v[8:11]
	s_nop 0
	s_nop 0
	v_mfma_f32_16x16x32_bf16 v[52:55], v[166:169], v[182:185], v[52:55]
	v_mfma_f32_16x16x32_bf16 v[48:51], v[174:177], v[182:185], v[48:51]
	v_mfma_f32_16x16x32_bf16 v[36:39], v[166:169], v[190:193], v[36:39]
	v_mfma_f32_16x16x32_bf16 v[32:35], v[174:177], v[190:193], v[32:35]
	v_mfma_f32_16x16x32_bf16 v[20:23], v[166:169], v[198:201], v[20:23]
	v_mfma_f32_16x16x32_bf16 v[16:19], v[174:177], v[198:201], v[16:19]
	v_mfma_f32_16x16x32_bf16 v[4:7], v[166:169], v[206:209], v[4:7]
	v_mfma_f32_16x16x32_bf16 v[0:3], v[174:177], v[206:209], v[0:3]
	v_mfma_f32_16x16x32_bf16 v[52:55], v[170:173], v[186:189], v[52:55]
	v_mfma_f32_16x16x32_bf16 v[48:51], v[178:181], v[186:189], v[48:51]
	v_mfma_f32_16x16x32_bf16 v[36:39], v[170:173], v[194:197], v[36:39]
	v_mfma_f32_16x16x32_bf16 v[32:35], v[178:181], v[194:197], v[32:35]
	v_mfma_f32_16x16x32_bf16 v[20:23], v[170:173], v[202:205], v[20:23]
	v_mfma_f32_16x16x32_bf16 v[16:19], v[178:181], v[202:205], v[16:19]
	v_mfma_f32_16x16x32_bf16 v[4:7], v[170:173], v[210:213], v[4:7]
	v_mfma_f32_16x16x32_bf16 v[0:3], v[178:181], v[210:213], v[0:3]
	s_setprio 0
	s_barrier
	s_add_i32 s61, 0, 0x18000
	s_add_i32 s62, 0, 0x1c000
	s_add_u32 s28, s28, 0x40000
	s_addc_u32 s29, s29, 0
	s_mov_b32 m0, s34
	v_lshl_add_u64 v[222:223], s[28:29], 0, v[128:129]
	global_load_lds_dwordx4 v[222:223], off
	v_lshl_add_u64 v[222:223], s[28:29], 0, v[130:131]
	s_mov_b32 m0, s35
	v_add_u32_e32 v153, s61, v145
	global_load_lds_dwordx4 v[222:223], off
	ds_read_b128 v[140:143], v153
	ds_read_b128 v[154:157], v153 offset:1024
	ds_read_b128 v[158:161], v153 offset:2048
	ds_read_b128 v[162:165], v153 offset:3072
	v_add_u32_e32 v153, s62, v145
	ds_read_b128 v[166:169], v153
	ds_read_b128 v[170:173], v153 offset:1024
	ds_read_b128 v[174:177], v153 offset:2048
	ds_read_b128 v[178:181], v153 offset:3072
	ds_read_b128 v[182:185], v151 offset:32768
	ds_read_b128 v[186:189], v151 offset:33792
	ds_read_b128 v[190:193], v151 offset:34816
	ds_read_b128 v[194:197], v151 offset:35840
	ds_read_b128 v[198:201], v151 offset:36864
	ds_read_b128 v[202:205], v151 offset:37888
	ds_read_b128 v[206:209], v151 offset:38912
	ds_read_b128 v[210:213], v151 offset:39936
	s_waitcnt vmcnt(8)
	s_waitcnt lgkmcnt(0)
	s_barrier
	s_setprio 1
	s_waitcnt lgkmcnt(0)
	v_mfma_f32_16x16x32_bf16 v[124:127], v[140:143], v[182:185], v[124:127]
	v_mfma_f32_16x16x32_bf16 v[120:123], v[158:161], v[182:185], v[120:123]
	v_mfma_f32_16x16x32_bf16 v[108:111], v[140:143], v[190:193], v[108:111]
	v_mfma_f32_16x16x32_bf16 v[104:107], v[158:161], v[190:193], v[104:107]
	v_mfma_f32_16x16x32_bf16 v[92:95], v[140:143], v[198:201], v[92:95]
	v_mfma_f32_16x16x32_bf16 v[88:91], v[158:161], v[198:201], v[88:91]
	v_mfma_f32_16x16x32_bf16 v[76:79], v[140:143], v[206:209], v[76:79]
	v_mfma_f32_16x16x32_bf16 v[72:75], v[158:161], v[206:209], v[72:75]
	v_mfma_f32_16x16x32_bf16 v[124:127], v[154:157], v[186:189], v[124:127]
	v_mfma_f32_16x16x32_bf16 v[120:123], v[162:165], v[186:189], v[120:123]
	v_mfma_f32_16x16x32_bf16 v[108:111], v[154:157], v[194:197], v[108:111]
	v_mfma_f32_16x16x32_bf16 v[104:107], v[162:165], v[194:197], v[104:107]
	v_mfma_f32_16x16x32_bf16 v[92:95], v[154:157], v[202:205], v[92:95]
	v_mfma_f32_16x16x32_bf16 v[88:91], v[162:165], v[202:205], v[88:91]
	v_mfma_f32_16x16x32_bf16 v[76:79], v[154:157], v[210:213], v[76:79]
	v_mfma_f32_16x16x32_bf16 v[72:75], v[162:165], v[210:213], v[72:75]
	s_nop 0
	s_nop 0
	v_mfma_f32_16x16x32_bf16 v[116:119], v[166:169], v[182:185], v[116:119]
	v_mfma_f32_16x16x32_bf16 v[112:115], v[174:177], v[182:185], v[112:115]
	v_mfma_f32_16x16x32_bf16 v[100:103], v[166:169], v[190:193], v[100:103]
	v_mfma_f32_16x16x32_bf16 v[96:99], v[174:177], v[190:193], v[96:99]
	v_mfma_f32_16x16x32_bf16 v[84:87], v[166:169], v[198:201], v[84:87]
	v_mfma_f32_16x16x32_bf16 v[80:83], v[174:177], v[198:201], v[80:83]
	v_mfma_f32_16x16x32_bf16 v[68:71], v[166:169], v[206:209], v[68:71]
	v_mfma_f32_16x16x32_bf16 v[64:67], v[174:177], v[206:209], v[64:67]
	v_mfma_f32_16x16x32_bf16 v[116:119], v[170:173], v[186:189], v[116:119]
	v_mfma_f32_16x16x32_bf16 v[112:115], v[178:181], v[186:189], v[112:115]
	v_mfma_f32_16x16x32_bf16 v[100:103], v[170:173], v[194:197], v[100:103]
	v_mfma_f32_16x16x32_bf16 v[96:99], v[178:181], v[194:197], v[96:99]
	v_mfma_f32_16x16x32_bf16 v[84:87], v[170:173], v[202:205], v[84:87]
	v_mfma_f32_16x16x32_bf16 v[80:83], v[178:181], v[202:205], v[80:83]
	v_mfma_f32_16x16x32_bf16 v[68:71], v[170:173], v[210:213], v[68:71]
	v_mfma_f32_16x16x32_bf16 v[64:67], v[178:181], v[210:213], v[64:67]
	s_setprio 0
	s_barrier
; #define PG8_STAGE(bufoff, gbase, voff) do { _Pragma("unroll") for (int _i = 0; _i < 2; ++_i) \
;         __builtin_amdgcn_global_load_lds((const unsigned*)((const char*)(gbase) + (voff)[_i]), (PG8_LAS unsigned*)(lds + (bufoff) + ldsw + _i * 8192), 16, 0, 0); } while (0)
; #define PG8_LDA(dst, b, h) do { _Pragma("unroll") for (int m = 0; m < 4; ++m) _Pragma("unroll") for (int k = 0; k < 2; ++k) dst[m][k] = *(const PG8_LAS bf16x8*)(lds + PG8_SA(b, h) + aoff + m * 2048 + k * 1024); } while (0)
; #define PG8_MMA(ai, bj, At, Bt) do { __builtin_amdgcn_s_setprio(1); _Pragma("unroll") for (int m = 0; m < 4; ++m) _Pragma("unroll") for (int n = 0; n < 2; ++n) _Pragma("unroll") for (int k = 0; k < 2; ++k) \
;         acc[ai][bj][m][n] = __builtin_amdgcn_mfma_f32_16x16x32_bf16(Bt[n][k], At[m][k], acc[ai][bj][m][n], 0, 0, 0); __builtin_amdgcn_s_setprio(0); } while (0)
; #define PG8_WAIT_V(n) asm volatile("s_waitcnt vmcnt(" #n ")" ::: "memory")
; #define PG8_WAIT_L(n) asm volatile("s_waitcnt lgkmcnt(" #n ")" ::: "memory")
; #define PG8_BAR __builtin_amdgcn_s_barrier()
; #define PG8_SCHED __builtin_amdgcn_sched_barrier(0)
; template <class Epi, class Sched, bool ALIGN_EPI = false, bool SP2 = false>
; __device__ __forceinline__ void gemm_phase(PG8_LAS unsigned char* lds, const Gemm g, const Sched& S, const Epi& E) {
;     ...
;             PG8_LDA(At, 1, 1); PG8_STAGE(PG8_SB(1, 0), b3, voffB); PG8_STAGE(PG8_SB(1, 1), b3 + hstep, voffB); PG8_STAGE(PG8_SA(1, 0), a3, voffA);
;             PG8_WAIT_V(8); PG8_WAIT_L(0); PG8_BAR; PG8_MMA(1, 0, At, B0); PG8_MMA(1, 1, At, B1); PG8_BAR; PG8_SCHED;
;     ...
;         if constexpr (ALIGN_EPI) { if (wr == 0) PG8_BAR; }
	s_add_i32 s28, s61, s30
	v_lshl_add_u64 v[214:215], v[214:215], 0, s[8:9]
	s_mov_b32 m0, s28
	ds_read_b128 v[182:185], v151 offset:49152
	global_load_lds_dwordx4 v[214:215], off
	s_add_i32 m0, s28, 0x2000
	s_add_u32 s26, s26, 0x40080
	v_lshl_add_u64 v[214:215], v[216:217], 0, s[8:9]
	s_addc_u32 s27, s27, 0
	s_add_i32 s28, s62, s30
	global_load_lds_dwordx4 v[214:215], off
	v_lshl_add_u64 v[214:215], s[26:27], 0, v[128:129]
	s_mov_b32 m0, s28
	ds_read_b128 v[186:189], v151 offset:50176
	global_load_lds_dwordx4 v[214:215], off
	v_lshl_add_u64 v[214:215], s[26:27], 0, v[130:131]
	s_add_i32 m0, s28, 0x2000
	ds_read_b128 v[190:193], v151 offset:51200
	global_load_lds_dwordx4 v[214:215], off
	v_lshl_add_u64 v[214:215], v[218:219], 0, s[8:9]
	s_mov_b32 m0, s38
	ds_read_b128 v[194:197], v151 offset:52224
	global_load_lds_dwordx4 v[214:215], off
	v_lshl_add_u64 v[214:215], v[220:221], 0, s[8:9]
	s_mov_b32 m0, s39
	ds_read_b128 v[198:201], v151 offset:53248
	global_load_lds_dwordx4 v[214:215], off
	ds_read_b128 v[202:205], v151 offset:54272
	ds_read_b128 v[206:209], v151 offset:55296
	ds_read_b128 v[210:213], v151 offset:56320
	s_waitcnt vmcnt(8)
	s_waitcnt lgkmcnt(0)
	s_barrier
	s_setprio 1
	s_waitcnt lgkmcnt(0)
	v_mfma_f32_16x16x32_bf16 v[60:63], v[140:143], v[182:185], v[60:63]
	v_mfma_f32_16x16x32_bf16 v[56:59], v[158:161], v[182:185], v[56:59]
	v_mfma_f32_16x16x32_bf16 v[44:47], v[140:143], v[190:193], v[44:47]
	v_mfma_f32_16x16x32_bf16 v[40:43], v[158:161], v[190:193], v[40:43]
	v_mfma_f32_16x16x32_bf16 v[28:31], v[140:143], v[198:201], v[28:31]
	v_mfma_f32_16x16x32_bf16 v[24:27], v[158:161], v[198:201], v[24:27]
	v_mfma_f32_16x16x32_bf16 v[12:15], v[140:143], v[206:209], v[12:15]
	v_mfma_f32_16x16x32_bf16 v[8:11], v[158:161], v[206:209], v[8:11]
	v_mfma_f32_16x16x32_bf16 v[60:63], v[154:157], v[186:189], v[60:63]
	v_mfma_f32_16x16x32_bf16 v[56:59], v[162:165], v[186:189], v[56:59]
	v_mfma_f32_16x16x32_bf16 v[44:47], v[154:157], v[194:197], v[44:47]
	v_mfma_f32_16x16x32_bf16 v[40:43], v[162:165], v[194:197], v[40:43]
	v_mfma_f32_16x16x32_bf16 v[28:31], v[154:157], v[202:205], v[28:31]
	v_mfma_f32_16x16x32_bf16 v[24:27], v[162:165], v[202:205], v[24:27]
	v_mfma_f32_16x16x32_bf16 v[12:15], v[154:157], v[210:213], v[12:15]
	v_mfma_f32_16x16x32_bf16 v[8:11], v[162:165], v[210:213], v[8:11]
	s_nop 0
	s_nop 0
	v_mfma_f32_16x16x32_bf16 v[52:55], v[166:169], v[182:185], v[52:55]
	v_mfma_f32_16x16x32_bf16 v[48:51], v[174:177], v[182:185], v[48:51]
	v_mfma_f32_16x16x32_bf16 v[36:39], v[166:169], v[190:193], v[36:39]
	v_mfma_f32_16x16x32_bf16 v[32:35], v[174:177], v[190:193], v[32:35]
	v_mfma_f32_16x16x32_bf16 v[20:23], v[166:169], v[198:201], v[20:23]
	v_mfma_f32_16x16x32_bf16 v[16:19], v[174:177], v[198:201], v[16:19]
	v_mfma_f32_16x16x32_bf16 v[4:7], v[166:169], v[206:209], v[4:7]
	v_mfma_f32_16x16x32_bf16 v[0:3], v[174:177], v[206:209], v[0:3]
	v_mfma_f32_16x16x32_bf16 v[52:55], v[170:173], v[186:189], v[52:55]
	v_mfma_f32_16x16x32_bf16 v[48:51], v[178:181], v[186:189], v[48:51]
	v_mfma_f32_16x16x32_bf16 v[36:39], v[170:173], v[194:197], v[36:39]
	v_mfma_f32_16x16x32_bf16 v[32:35], v[178:181], v[194:197], v[32:35]
	v_mfma_f32_16x16x32_bf16 v[20:23], v[170:173], v[202:205], v[20:23]
	v_mfma_f32_16x16x32_bf16 v[16:19], v[178:181], v[202:205], v[16:19]
	v_mfma_f32_16x16x32_bf16 v[4:7], v[170:173], v[210:213], v[4:7]
	v_mfma_f32_16x16x32_bf16 v[0:3], v[178:181], v[210:213], v[0:3]
	s_setprio 0
	s_barrier
	s_add_i32 s60, s60, 2
	s_add_u32 s24, s24, 0x100
	s_addc_u32 s25, s25, 0
	s_add_u32 s58, s58, 0x100
	s_addc_u32 s59, s59, 0
	s_cmp_gt_u32 s60, 13
	s_cbranch_scc0 .LBB0_1400
	s_nop 0
	s_nop 0
	s_nop 0
	s_nop 0
	s_nop 0
	s_nop 0
	s_nop 0
	s_nop 0
	s_nop 0
	s_and_b64 vcc, exec, s[10:11]
	s_cbranch_vccz .LBB0_1403
	s_barrier

; #define PG8_STAGE(bufoff, gbase, voff) do { _Pragma("unroll") for (int _i = 0; _i < 2; ++_i) \
;         __builtin_amdgcn_global_load_lds((const unsigned*)((const char*)(gbase) + (voff)[_i]), (PG8_LAS unsigned*)(lds + (bufoff) + ldsw + _i * 8192), 16, 0, 0); } while (0)
; #define PG8_LDA(dst, b, h) do { _Pragma("unroll") for (int m = 0; m < 4; ++m) _Pragma("unroll") for (int k = 0; k < 2; ++k) dst[m][k] = *(const PG8_LAS bf16x8*)(lds + PG8_SA(b, h) + aoff + m * 2048 + k * 1024); } while (0)
; #define PG8_LDB(dst, b, h) do { _Pragma("unroll") for (int n = 0; n < 2; ++n) _Pragma("unroll") for (int k = 0; k < 2; ++k) dst[n][k] = *(const PG8_LAS bf16x8*)(lds + PG8_SB(b, h) + boff + n * 2048 + k * 1024); } while (0)
; #define PG8_MMA(ai, bj, At, Bt) do { __builtin_amdgcn_s_setprio(1); _Pragma("unroll") for (int m = 0; m < 4; ++m) _Pragma("unroll") for (int n = 0; n < 2; ++n) _Pragma("unroll") for (int k = 0; k < 2; ++k) \
;         acc[ai][bj][m][n] = __builtin_amdgcn_mfma_f32_16x16x32_bf16(Bt[n][k], At[m][k], acc[ai][bj][m][n], 0, 0, 0); __builtin_amdgcn_s_setprio(0); } while (0)
; #define PG8_WAIT_V(n) asm volatile("s_waitcnt vmcnt(" #n ")" ::: "memory")
; #define PG8_WAIT_L(n) asm volatile("s_waitcnt lgkmcnt(" #n ")" ::: "memory")
; template <class Epi, class Sched, bool ALIGN_EPI = false, bool SP2 = false>
; __device__ __forceinline__ void gemm_phase(PG8_LAS unsigned char* lds, const Gemm g, const Sched& S, const Epi& E) {
;     ...
;             const bool last = (t == nt - 2);
;             const char* a1 = cA + (size_t)(t + 1) * kstep;
;             const char* a2 = last ? nA : cA + (size_t)(t + 2) * kstep; const char* b2 = last ? nB : cB + (size_t)(t + 2) * kstep;
;             const char* a3 = a2 + kstep; const char* b3 = b2 + kstep;
;             if (last && has_next) S.a_ready(nxt);
;             if constexpr (SP2) {
;             PG8_LDB(B0, 0, 0); PG8_LDB(B1, 0, 1); PG8_SCHED; PG8_LDA(At, 0, 0); PG8_STAGE(PG8_SA(1, 1), a1 + hstep, voffA);
;             PG8_WAIT_V(8); PG8_WAIT_L(0); PG8_BAR; PG8_MMA(0, 0, At, B0); PG8_MMA(0, 1, At, B1); PG8_BAR; PG8_SCHED;
;             PG8_LDA(At, 0, 1); PG8_STAGE(PG8_SB(0, 0), b2, voffB); PG8_STAGE(PG8_SB(0, 1), b2 + hstep, voffB); PG8_STAGE(PG8_SA(0, 0), a2, voffA);
;             PG8_WAIT_V(8); PG8_WAIT_L(0); PG8_BAR; PG8_MMA(1, 0, At, B0); PG8_MMA(1, 1, At, B1); PG8_BAR; PG8_SCHED;
.LBB0_1487:
	s_add_u32 s6, s4, 0xfffc0080
	s_addc_u32 s7, s5, -1
	s_cmp_eq_u32 s51, 12
	s_cselect_b32 s9, s10, s7
	s_cselect_b32 s8, s11, s6
	s_cselect_b32 s7, s21, s50
	s_cselect_b32 s6, s23, s45
	v_lshl_add_u64 v[152:153], s[4:5], 0, v[136:137]
	s_add_i32 m0, s31, 0xc000
	ds_read_b128 v[144:147], v155
	global_load_lds_dwordx4 v[152:153], off
	v_lshl_add_u64 v[152:153], s[4:5], 0, v[138:139]
	s_add_i32 m0, s31, 0xe000
	ds_read_b128 v[160:163], v155 offset:1024
	global_load_lds_dwordx4 v[152:153], off
	ds_read_b128 v[164:167], v155 offset:2048
	ds_read_b128 v[168:171], v155 offset:3072
	ds_read_b128 v[172:175], v156
	ds_read_b128 v[176:179], v156 offset:1024
	ds_read_b128 v[180:183], v156 offset:2048
	ds_read_b128 v[184:187], v156 offset:3072
	ds_read_b128 v[188:191], v157
	ds_read_b128 v[192:195], v157 offset:1024
	ds_read_b128 v[196:199], v157 offset:2048
	ds_read_b128 v[200:203], v157 offset:3072
	ds_read_b128 v[204:207], v157 offset:4096
	ds_read_b128 v[208:211], v157 offset:5120
	ds_read_b128 v[212:215], v157 offset:6144
	ds_read_b128 v[216:219], v157 offset:7168
	s_waitcnt vmcnt(8)
	s_waitcnt lgkmcnt(0)
	s_barrier
	s_setprio 1
	s_waitcnt lgkmcnt(0)
	v_mfma_f32_16x16x32_bf16 v[124:127], v[144:147], v[188:191], v[124:127]
	v_mfma_f32_16x16x32_bf16 v[116:119], v[164:167], v[188:191], v[116:119]
	v_mfma_f32_16x16x32_bf16 v[108:111], v[144:147], v[196:199], v[108:111]
	v_mfma_f32_16x16x32_bf16 v[100:103], v[164:167], v[196:199], v[100:103]
	v_mfma_f32_16x16x32_bf16 v[92:95], v[144:147], v[204:207], v[92:95]
	v_mfma_f32_16x16x32_bf16 v[84:87], v[164:167], v[204:207], v[84:87]
	v_mfma_f32_16x16x32_bf16 v[76:79], v[144:147], v[212:215], v[76:79]
	v_mfma_f32_16x16x32_bf16 v[68:71], v[164:167], v[212:215], v[68:71]
	v_mfma_f32_16x16x32_bf16 v[124:127], v[160:163], v[192:195], v[124:127]
	v_mfma_f32_16x16x32_bf16 v[116:119], v[168:171], v[192:195], v[116:119]
	v_mfma_f32_16x16x32_bf16 v[108:111], v[160:163], v[200:203], v[108:111]
	v_mfma_f32_16x16x32_bf16 v[100:103], v[168:171], v[200:203], v[100:103]
	v_mfma_f32_16x16x32_bf16 v[92:95], v[160:163], v[208:211], v[92:95]
	v_mfma_f32_16x16x32_bf16 v[84:87], v[168:171], v[208:211], v[84:87]
	v_mfma_f32_16x16x32_bf16 v[76:79], v[160:163], v[216:219], v[76:79]
	v_mfma_f32_16x16x32_bf16 v[68:71], v[168:171], v[216:219], v[68:71]
	s_nop 0
	s_nop 0
	v_mfma_f32_16x16x32_bf16 v[120:123], v[172:175], v[188:191], v[120:123]
	v_mfma_f32_16x16x32_bf16 v[112:115], v[180:183], v[188:191], v[112:115]
	v_mfma_f32_16x16x32_bf16 v[104:107], v[172:175], v[196:199], v[104:107]
	v_mfma_f32_16x16x32_bf16 v[96:99], v[180:183], v[196:199], v[96:99]
	v_mfma_f32_16x16x32_bf16 v[88:91], v[172:175], v[204:207], v[88:91]
	v_mfma_f32_16x16x32_bf16 v[80:83], v[180:183], v[204:207], v[80:83]
	v_mfma_f32_16x16x32_bf16 v[72:75], v[172:175], v[212:215], v[72:75]
	v_mfma_f32_16x16x32_bf16 v[64:67], v[180:183], v[212:215], v[64:67]
	v_mfma_f32_16x16x32_bf16 v[120:123], v[176:179], v[192:195], v[120:123]
	v_mfma_f32_16x16x32_bf16 v[112:115], v[184:187], v[192:195], v[112:115]
	v_mfma_f32_16x16x32_bf16 v[104:107], v[176:179], v[200:203], v[104:107]
	v_mfma_f32_16x16x32_bf16 v[96:99], v[184:187], v[200:203], v[96:99]
	v_mfma_f32_16x16x32_bf16 v[88:91], v[176:179], v[208:211], v[88:91]
	v_mfma_f32_16x16x32_bf16 v[80:83], v[184:187], v[208:211], v[80:83]
	v_mfma_f32_16x16x32_bf16 v[72:75], v[176:179], v[216:219], v[72:75]
	v_mfma_f32_16x16x32_bf16 v[64:67], v[184:187], v[216:219], v[64:67]
	s_setprio 0
	s_barrier
	s_add_i32 s52, s41, s28
	v_lshl_add_u64 v[152:153], s[6:7], 0, v[132:133]
	s_mov_b32 m0, s52
	v_lshl_add_u64 v[220:221], s[6:7], 0, v[128:129]
	global_load_lds_dwordx4 v[152:153], off
	s_add_i32 m0, s52, 0x2000
	s_add_u32 s52, s6, 0x40000
	s_addc_u32 s53, s7, 0
	s_add_i32 s54, s42, s28
	global_load_lds_dwordx4 v[220:221], off
	v_lshl_add_u64 v[222:223], s[52:53], 0, v[132:133]
	s_mov_b32 m0, s54
	v_lshl_add_u64 v[224:225], s[8:9], 0, v[130:131]
	global_load_lds_dwordx4 v[222:223], off
	v_lshl_add_u64 v[222:223], s[52:53], 0, v[128:129]
	s_add_i32 m0, s54, 0x2000
	ds_read_b128 v[188:191], v157 offset:16384
	global_load_lds_dwordx4 v[222:223], off
	v_lshl_add_u64 v[222:223], s[8:9], 0, v[134:135]
	s_mov_b32 m0, s31
	ds_read_b128 v[192:195], v157 offset:17408
	global_load_lds_dwordx4 v[222:223], off
	s_mov_b32 m0, s34
	ds_read_b128 v[196:199], v157 offset:18432
	global_load_lds_dwordx4 v[224:225], off
	ds_read_b128 v[200:203], v157 offset:19456
	ds_read_b128 v[204:207], v157 offset:20480
	ds_read_b128 v[208:211], v157 offset:21504
	ds_read_b128 v[212:215], v157 offset:22528
	ds_read_b128 v[216:219], v157 offset:23552
	s_waitcnt vmcnt(8)
	s_waitcnt lgkmcnt(0)
	s_barrier
; #define PG8_STAGE(bufoff, gbase, voff) do { _Pragma("unroll") for (int _i = 0; _i < 2; ++_i) \
;         __builtin_amdgcn_global_load_lds((const unsigned*)((const char*)(gbase) + (voff)[_i]), (PG8_LAS unsigned*)(lds + (bufoff) + ldsw + _i * 8192), 16, 0, 0); } while (0)
; #define PG8_LDA(dst, b, h) do { _Pragma("unroll") for (int m = 0; m < 4; ++m) _Pragma("unroll") for (int k = 0; k < 2; ++k) dst[m][k] = *(const PG8_LAS bf16x8*)(lds + PG8_SA(b, h) + aoff + m * 2048 + k * 1024); } while (0)
; #define PG8_LDB(dst, b, h) do { _Pragma("unroll") for (int n = 0; n < 2; ++n) _Pragma("unroll") for (int k = 0; k < 2; ++k) dst[n][k] = *(const PG8_LAS bf16x8*)(lds + PG8_SB(b, h) + boff + n * 2048 + k * 1024); } while (0)
; #define PG8_MMA(ai, bj, At, Bt) do { __builtin_amdgcn_s_setprio(1); _Pragma("unroll") for (int m = 0; m < 4; ++m) _Pragma("unroll") for (int n = 0; n < 2; ++n) _Pragma("unroll") for (int k = 0; k < 2; ++k) \
;         acc[ai][bj][m][n] = __builtin_amdgcn_mfma_f32_16x16x32_bf16(Bt[n][k], At[m][k], acc[ai][bj][m][n], 0, 0, 0); __builtin_amdgcn_s_setprio(0); } while (0)
; #define PG8_WAIT_V(n) asm volatile("s_waitcnt vmcnt(" #n ")" ::: "memory")
; #define PG8_WAIT_L(n) asm volatile("s_waitcnt lgkmcnt(" #n ")" ::: "memory")
; #define PG8_BAR __builtin_amdgcn_s_barrier()
; #define PG8_SCHED __builtin_amdgcn_sched_barrier(0)
; template <class Epi, class Sched, bool ALIGN_EPI = false, bool SP2 = false>
; __device__ __forceinline__ void gemm_phase(PG8_LAS unsigned char* lds, const Gemm g, const Sched& S, const Epi& E) {
;     ...
;             PG8_WAIT_V(8); PG8_WAIT_L(0); PG8_BAR; PG8_MMA(1, 0, At, B0); PG8_MMA(1, 1, At, B1); PG8_BAR; PG8_SCHED;
;             PG8_LDB(B0, 1, 0); PG8_LDB(B1, 1, 1); PG8_SCHED; PG8_LDA(At, 1, 0); PG8_STAGE(PG8_SA(0, 1), a2 + hstep, voffA);
;             PG8_WAIT_V(8); PG8_WAIT_L(0); PG8_BAR; PG8_MMA(0, 0, At, B0); PG8_MMA(0, 1, At, B1); PG8_BAR; PG8_SCHED;
	s_setprio 1
	s_waitcnt lgkmcnt(0)
	v_mfma_f32_16x16x32_bf16 v[60:63], v[144:147], v[188:191], v[60:63]
	v_mfma_f32_16x16x32_bf16 v[52:55], v[164:167], v[188:191], v[52:55]
	v_mfma_f32_16x16x32_bf16 v[44:47], v[144:147], v[196:199], v[44:47]
	v_mfma_f32_16x16x32_bf16 v[36:39], v[164:167], v[196:199], v[36:39]
	v_mfma_f32_16x16x32_bf16 v[28:31], v[144:147], v[204:207], v[28:31]
	v_mfma_f32_16x16x32_bf16 v[20:23], v[164:167], v[204:207], v[20:23]
	v_mfma_f32_16x16x32_bf16 v[12:15], v[144:147], v[212:215], v[12:15]
	v_mfma_f32_16x16x32_bf16 v[4:7], v[164:167], v[212:215], v[4:7]
	v_mfma_f32_16x16x32_bf16 v[60:63], v[160:163], v[192:195], v[60:63]
	v_mfma_f32_16x16x32_bf16 v[52:55], v[168:171], v[192:195], v[52:55]
	v_mfma_f32_16x16x32_bf16 v[44:47], v[160:163], v[200:203], v[44:47]
	v_mfma_f32_16x16x32_bf16 v[36:39], v[168:171], v[200:203], v[36:39]
	v_mfma_f32_16x16x32_bf16 v[28:31], v[160:163], v[208:211], v[28:31]
	v_mfma_f32_16x16x32_bf16 v[20:23], v[168:171], v[208:211], v[20:23]
	v_mfma_f32_16x16x32_bf16 v[12:15], v[160:163], v[216:219], v[12:15]
	v_mfma_f32_16x16x32_bf16 v[4:7], v[168:171], v[216:219], v[4:7]
	s_nop 0
	s_nop 0
	v_mfma_f32_16x16x32_bf16 v[56:59], v[172:175], v[188:191], v[56:59]
	v_mfma_f32_16x16x32_bf16 v[48:51], v[180:183], v[188:191], v[48:51]
	v_mfma_f32_16x16x32_bf16 v[40:43], v[172:175], v[196:199], v[40:43]
	v_mfma_f32_16x16x32_bf16 v[32:35], v[180:183], v[196:199], v[32:35]
	v_mfma_f32_16x16x32_bf16 v[24:27], v[172:175], v[204:207], v[24:27]
	v_mfma_f32_16x16x32_bf16 v[16:19], v[180:183], v[204:207], v[16:19]
	v_mfma_f32_16x16x32_bf16 v[8:11], v[172:175], v[212:215], v[8:11]
	v_mfma_f32_16x16x32_bf16 v[0:3], v[180:183], v[212:215], v[0:3]
	v_mfma_f32_16x16x32_bf16 v[56:59], v[176:179], v[192:195], v[56:59]
	v_mfma_f32_16x16x32_bf16 v[48:51], v[184:187], v[192:195], v[48:51]
	v_mfma_f32_16x16x32_bf16 v[40:43], v[176:179], v[200:203], v[40:43]
	v_mfma_f32_16x16x32_bf16 v[32:35], v[184:187], v[200:203], v[32:35]
	v_mfma_f32_16x16x32_bf16 v[24:27], v[176:179], v[208:211], v[24:27]
	v_mfma_f32_16x16x32_bf16 v[16:19], v[184:187], v[208:211], v[16:19]
	v_mfma_f32_16x16x32_bf16 v[8:11], v[176:179], v[216:219], v[8:11]
	v_mfma_f32_16x16x32_bf16 v[0:3], v[184:187], v[216:219], v[0:3]
	s_setprio 0
	s_barrier
	s_add_i32 s52, 0, 0x18000
	s_add_i32 s53, 0, 0x1c000
	s_add_u32 s8, s8, 0x40000
	s_addc_u32 s9, s9, 0
	s_mov_b32 m0, s35
	v_lshl_add_u64 v[226:227], s[8:9], 0, v[134:135]
	global_load_lds_dwordx4 v[226:227], off
	v_lshl_add_u64 v[226:227], s[8:9], 0, v[130:131]
	s_mov_b32 m0, s36
	v_add_u32_e32 v159, s52, v151
	global_load_lds_dwordx4 v[226:227], off
	ds_read_b128 v[144:147], v159
	ds_read_b128 v[160:163], v159 offset:1024
	ds_read_b128 v[164:167], v159 offset:2048
	ds_read_b128 v[168:171], v159 offset:3072
	v_add_u32_e32 v159, s53, v151
	ds_read_b128 v[172:175], v159
	ds_read_b128 v[176:179], v159 offset:1024
	ds_read_b128 v[180:183], v159 offset:2048
	ds_read_b128 v[184:187], v159 offset:3072
	ds_read_b128 v[188:191], v157 offset:32768
	ds_read_b128 v[192:195], v157 offset:33792
	ds_read_b128 v[196:199], v157 offset:34816
	ds_read_b128 v[200:203], v157 offset:35840
	ds_read_b128 v[204:207], v157 offset:36864
	ds_read_b128 v[208:211], v157 offset:37888
	ds_read_b128 v[212:215], v157 offset:38912
	ds_read_b128 v[216:219], v157 offset:39936
	s_waitcnt vmcnt(8)
	s_waitcnt lgkmcnt(0)
	s_barrier
	s_setprio 1
	s_waitcnt lgkmcnt(0)
	v_mfma_f32_16x16x32_bf16 v[124:127], v[144:147], v[188:191], v[124:127]
	v_mfma_f32_16x16x32_bf16 v[116:119], v[164:167], v[188:191], v[116:119]
	v_mfma_f32_16x16x32_bf16 v[108:111], v[144:147], v[196:199], v[108:111]
	v_mfma_f32_16x16x32_bf16 v[100:103], v[164:167], v[196:199], v[100:103]
	v_mfma_f32_16x16x32_bf16 v[92:95], v[144:147], v[204:207], v[92:95]
	v_mfma_f32_16x16x32_bf16 v[84:87], v[164:167], v[204:207], v[84:87]
	v_mfma_f32_16x16x32_bf16 v[76:79], v[144:147], v[212:215], v[76:79]
	v_mfma_f32_16x16x32_bf16 v[68:71], v[164:167], v[212:215], v[68:71]
	v_mfma_f32_16x16x32_bf16 v[124:127], v[160:163], v[192:195], v[124:127]
	v_mfma_f32_16x16x32_bf16 v[116:119], v[168:171], v[192:195], v[116:119]
	v_mfma_f32_16x16x32_bf16 v[108:111], v[160:163], v[200:203], v[108:111]
	v_mfma_f32_16x16x32_bf16 v[100:103], v[168:171], v[200:203], v[100:103]
	v_mfma_f32_16x16x32_bf16 v[92:95], v[160:163], v[208:211], v[92:95]
	v_mfma_f32_16x16x32_bf16 v[84:87], v[168:171], v[208:211], v[84:87]
	v_mfma_f32_16x16x32_bf16 v[76:79], v[160:163], v[216:219], v[76:79]
	v_mfma_f32_16x16x32_bf16 v[68:71], v[168:171], v[216:219], v[68:71]
	s_nop 0
	s_nop 0
	v_mfma_f32_16x16x32_bf16 v[120:123], v[172:175], v[188:191], v[120:123]
	v_mfma_f32_16x16x32_bf16 v[112:115], v[180:183], v[188:191], v[112:115]
	v_mfma_f32_16x16x32_bf16 v[104:107], v[172:175], v[196:199], v[104:107]
	v_mfma_f32_16x16x32_bf16 v[96:99], v[180:183], v[196:199], v[96:99]
	v_mfma_f32_16x16x32_bf16 v[88:91], v[172:175], v[204:207], v[88:91]
	v_mfma_f32_16x16x32_bf16 v[80:83], v[180:183], v[204:207], v[80:83]
	v_mfma_f32_16x16x32_bf16 v[72:75], v[172:175], v[212:215], v[72:75]
	v_mfma_f32_16x16x32_bf16 v[64:67], v[180:183], v[212:215], v[64:67]
	v_mfma_f32_16x16x32_bf16 v[120:123], v[176:179], v[192:195], v[120:123]
	v_mfma_f32_16x16x32_bf16 v[112:115], v[184:187], v[192:195], v[112:115]
	v_mfma_f32_16x16x32_bf16 v[104:107], v[176:179], v[200:203], v[104:107]
	v_mfma_f32_16x16x32_bf16 v[96:99], v[184:187], v[200:203], v[96:99]
	v_mfma_f32_16x16x32_bf16 v[88:91], v[176:179], v[208:211], v[88:91]
	v_mfma_f32_16x16x32_bf16 v[80:83], v[184:187], v[208:211], v[80:83]
	v_mfma_f32_16x16x32_bf16 v[72:75], v[176:179], v[216:219], v[72:75]
	v_mfma_f32_16x16x32_bf16 v[64:67], v[184:187], v[216:219], v[64:67]
	s_setprio 0
	s_barrier
; #define PG8_STAGE(bufoff, gbase, voff) do { _Pragma("unroll") for (int _i = 0; _i < 2; ++_i) \
;         __builtin_amdgcn_global_load_lds((const unsigned*)((const char*)(gbase) + (voff)[_i]), (PG8_LAS unsigned*)(lds + (bufoff) + ldsw + _i * 8192), 16, 0, 0); } while (0)
; #define PG8_LDA(dst, b, h) do { _Pragma("unroll") for (int m = 0; m < 4; ++m) _Pragma("unroll") for (int k = 0; k < 2; ++k) dst[m][k] = *(const PG8_LAS bf16x8*)(lds + PG8_SA(b, h) + aoff + m * 2048 + k * 1024); } while (0)
; #define PG8_MMA(ai, bj, At, Bt) do { __builtin_amdgcn_s_setprio(1); _Pragma("unroll") for (int m = 0; m < 4; ++m) _Pragma("unroll") for (int n = 0; n < 2; ++n) _Pragma("unroll") for (int k = 0; k < 2; ++k) \
;         acc[ai][bj][m][n] = __builtin_amdgcn_mfma_f32_16x16x32_bf16(Bt[n][k], At[m][k], acc[ai][bj][m][n], 0, 0, 0); __builtin_amdgcn_s_setprio(0); } while (0)
; #define PG8_WAIT_V(n) asm volatile("s_waitcnt vmcnt(" #n ")" ::: "memory")
; #define PG8_WAIT_L(n) asm volatile("s_waitcnt lgkmcnt(" #n ")" ::: "memory")
; #define PG8_BAR __builtin_amdgcn_s_barrier()
; #define PG8_SCHED __builtin_amdgcn_sched_barrier(0)
; template <class Epi, class Sched, bool ALIGN_EPI = false, bool SP2 = false>
; __device__ __forceinline__ void gemm_phase(PG8_LAS unsigned char* lds, const Gemm g, const Sched& S, const Epi& E) {
;     ...
;             PG8_LDA(At, 1, 1); PG8_STAGE(PG8_SB(1, 0), b3, voffB); PG8_STAGE(PG8_SB(1, 1), b3 + hstep, voffB); PG8_STAGE(PG8_SA(1, 0), a3, voffA);
;             PG8_WAIT_V(8); PG8_WAIT_L(0); PG8_BAR; PG8_MMA(1, 0, At, B0); PG8_MMA(1, 1, At, B1); PG8_BAR; PG8_SCHED;
;     ...
;         if constexpr (ALIGN_EPI) { if (wr == 0) PG8_BAR; }
	s_add_i32 s8, s52, s28
	v_lshl_add_u64 v[152:153], v[152:153], 0, s[16:17]
	s_mov_b32 m0, s8
	ds_read_b128 v[188:191], v157 offset:49152
	global_load_lds_dwordx4 v[152:153], off
	s_add_i32 m0, s8, 0x2000
	s_add_u32 s6, s6, 0x40080
	v_lshl_add_u64 v[152:153], v[220:221], 0, s[16:17]
	s_addc_u32 s7, s7, 0
	s_add_i32 s8, s53, s28
	global_load_lds_dwordx4 v[152:153], off
	v_lshl_add_u64 v[152:153], s[6:7], 0, v[132:133]
	s_mov_b32 m0, s8
	ds_read_b128 v[192:195], v157 offset:50176
	global_load_lds_dwordx4 v[152:153], off
	v_lshl_add_u64 v[152:153], s[6:7], 0, v[128:129]
	s_add_i32 m0, s8, 0x2000
	ds_read_b128 v[196:199], v157 offset:51200
	global_load_lds_dwordx4 v[152:153], off
	v_lshl_add_u64 v[152:153], v[222:223], 0, s[16:17]
	s_mov_b32 m0, s38
	ds_read_b128 v[200:203], v157 offset:52224
	global_load_lds_dwordx4 v[152:153], off
	v_lshl_add_u64 v[152:153], v[224:225], 0, s[16:17]
	s_mov_b32 m0, s39
	ds_read_b128 v[204:207], v157 offset:53248
	global_load_lds_dwordx4 v[152:153], off
	ds_read_b128 v[208:211], v157 offset:54272
	ds_read_b128 v[212:215], v157 offset:55296
	ds_read_b128 v[216:219], v157 offset:56320
	s_waitcnt vmcnt(8)
	s_waitcnt lgkmcnt(0)
	s_barrier
	s_setprio 1
	s_waitcnt lgkmcnt(0)
	v_mfma_f32_16x16x32_bf16 v[60:63], v[144:147], v[188:191], v[60:63]
	v_mfma_f32_16x16x32_bf16 v[52:55], v[164:167], v[188:191], v[52:55]
	v_mfma_f32_16x16x32_bf16 v[44:47], v[144:147], v[196:199], v[44:47]
	v_mfma_f32_16x16x32_bf16 v[36:39], v[164:167], v[196:199], v[36:39]
	v_mfma_f32_16x16x32_bf16 v[28:31], v[144:147], v[204:207], v[28:31]
	v_mfma_f32_16x16x32_bf16 v[20:23], v[164:167], v[204:207], v[20:23]
	v_mfma_f32_16x16x32_bf16 v[12:15], v[144:147], v[212:215], v[12:15]
	v_mfma_f32_16x16x32_bf16 v[4:7], v[164:167], v[212:215], v[4:7]
	v_mfma_f32_16x16x32_bf16 v[60:63], v[160:163], v[192:195], v[60:63]
	v_mfma_f32_16x16x32_bf16 v[52:55], v[168:171], v[192:195], v[52:55]
	v_mfma_f32_16x16x32_bf16 v[44:47], v[160:163], v[200:203], v[44:47]
	v_mfma_f32_16x16x32_bf16 v[36:39], v[168:171], v[200:203], v[36:39]
	v_mfma_f32_16x16x32_bf16 v[28:31], v[160:163], v[208:211], v[28:31]
	v_mfma_f32_16x16x32_bf16 v[20:23], v[168:171], v[208:211], v[20:23]
	v_mfma_f32_16x16x32_bf16 v[12:15], v[160:163], v[216:219], v[12:15]
	v_mfma_f32_16x16x32_bf16 v[4:7], v[168:171], v[216:219], v[4:7]
	s_nop 0
	s_nop 0
	v_mfma_f32_16x16x32_bf16 v[56:59], v[172:175], v[188:191], v[56:59]
	v_mfma_f32_16x16x32_bf16 v[48:51], v[180:183], v[188:191], v[48:51]
	v_mfma_f32_16x16x32_bf16 v[40:43], v[172:175], v[196:199], v[40:43]
	v_mfma_f32_16x16x32_bf16 v[32:35], v[180:183], v[196:199], v[32:35]
	v_mfma_f32_16x16x32_bf16 v[24:27], v[172:175], v[204:207], v[24:27]
	v_mfma_f32_16x16x32_bf16 v[16:19], v[180:183], v[204:207], v[16:19]
	v_mfma_f32_16x16x32_bf16 v[8:11], v[172:175], v[212:215], v[8:11]
	v_mfma_f32_16x16x32_bf16 v[0:3], v[180:183], v[212:215], v[0:3]
	v_mfma_f32_16x16x32_bf16 v[56:59], v[176:179], v[192:195], v[56:59]
	v_mfma_f32_16x16x32_bf16 v[48:51], v[184:187], v[192:195], v[48:51]
	v_mfma_f32_16x16x32_bf16 v[40:43], v[176:179], v[200:203], v[40:43]
	v_mfma_f32_16x16x32_bf16 v[32:35], v[184:187], v[200:203], v[32:35]
	v_mfma_f32_16x16x32_bf16 v[24:27], v[176:179], v[208:211], v[24:27]
	v_mfma_f32_16x16x32_bf16 v[16:19], v[184:187], v[208:211], v[16:19]
	v_mfma_f32_16x16x32_bf16 v[8:11], v[176:179], v[216:219], v[8:11]
	v_mfma_f32_16x16x32_bf16 v[0:3], v[184:187], v[216:219], v[0:3]
	s_setprio 0
	s_barrier
	s_add_i32 s51, s51, 2
	s_add_u32 s4, s4, 0x100
	s_addc_u32 s5, s5, 0
	s_add_u32 s45, s45, 0x100
	s_addc_u32 s50, s50, 0
	s_cmp_gt_u32 s51, 13
	s_cbranch_scc0 .LBB0_1487
	s_nop 0
	s_nop 0
	s_nop 0
	s_nop 0
	s_nop 0
	s_nop 0
	s_nop 0
	s_nop 0
	s_nop 0
	s_and_b64 vcc, exec, s[18:19]
	s_cbranch_vccz .LBB0_1490
	s_barrier

; #define PG8_STAGE(bufoff, gbase, voff) do { _Pragma("unroll") for (int _i = 0; _i < 2; ++_i) \
;         __builtin_amdgcn_global_load_lds((const unsigned*)((const char*)(gbase) + (voff)[_i]), (PG8_LAS unsigned*)(lds + (bufoff) + ldsw + _i * 8192), 16, 0, 0); } while (0)
; #define PG8_LDA(dst, b, h) do { _Pragma("unroll") for (int m = 0; m < 4; ++m) _Pragma("unroll") for (int k = 0; k < 2; ++k) dst[m][k] = *(const PG8_LAS bf16x8*)(lds + PG8_SA(b, h) + aoff + m * 2048 + k * 1024); } while (0)
; #define PG8_LDB(dst, b, h) do { _Pragma("unroll") for (int n = 0; n < 2; ++n) _Pragma("unroll") for (int k = 0; k < 2; ++k) dst[n][k] = *(const PG8_LAS bf16x8*)(lds + PG8_SB(b, h) + boff + n * 2048 + k * 1024); } while (0)
; #define PG8_MMA(ai, bj, At, Bt) do { __builtin_amdgcn_s_setprio(1); _Pragma("unroll") for (int m = 0; m < 4; ++m) _Pragma("unroll") for (int n = 0; n < 2; ++n) _Pragma("unroll") for (int k = 0; k < 2; ++k) \
;         acc[ai][bj][m][n] = __builtin_amdgcn_mfma_f32_16x16x32_bf16(Bt[n][k], At[m][k], acc[ai][bj][m][n], 0, 0, 0); __builtin_amdgcn_s_setprio(0); } while (0)
; #define PG8_WAIT_V(n) asm volatile("s_waitcnt vmcnt(" #n ")" ::: "memory")
; #define PG8_WAIT_L(n) asm volatile("s_waitcnt lgkmcnt(" #n ")" ::: "memory")
; template <class Epi, class Sched, bool ALIGN_EPI = false, bool SP2 = false>
; __device__ __forceinline__ void gemm_phase(PG8_LAS unsigned char* lds, const Gemm g, const Sched& S, const Epi& E) {
;     ...
;             const bool last = (t == nt - 2);
;             const char* a1 = cA + (size_t)(t + 1) * kstep;
;             const char* a2 = last ? nA : cA + (size_t)(t + 2) * kstep; const char* b2 = last ? nB : cB + (size_t)(t + 2) * kstep;
;             const char* a3 = a2 + kstep; const char* b3 = b2 + kstep;
;             if (last && has_next) S.a_ready(nxt);
;             if constexpr (SP2) {
;             PG8_LDB(B0, 0, 0); PG8_LDB(B1, 0, 1); PG8_SCHED; PG8_LDA(At, 0, 0); PG8_STAGE(PG8_SA(1, 1), a1 + hstep, voffA);
;             PG8_WAIT_V(8); PG8_WAIT_L(0); PG8_BAR; PG8_MMA(0, 0, At, B0); PG8_MMA(0, 1, At, B1); PG8_BAR; PG8_SCHED;
;             PG8_LDA(At, 0, 1); PG8_STAGE(PG8_SB(0, 0), b2, voffB); PG8_STAGE(PG8_SB(0, 1), b2 + hstep, voffB); PG8_STAGE(PG8_SA(0, 0), a2, voffA);
;             PG8_WAIT_V(8); PG8_WAIT_L(0); PG8_BAR; PG8_MMA(1, 0, At, B0); PG8_MMA(1, 1, At, B1); PG8_BAR; PG8_SCHED;
.LBB0_1572:
	s_add_u32 s22, s20, 0xfff50080
	s_addc_u32 s23, s21, -1
	s_cmp_eq_u32 s47, 40
	s_cselect_b32 s25, s1, s23
	s_cselect_b32 s24, s0, s22
	s_cselect_b32 s23, s19, s46
	s_cselect_b32 s22, s18, s45
	v_lshl_add_u64 v[214:215], s[20:21], 0, v[132:133]
	s_add_i32 m0, s27, 0xc000
	ds_read_b128 v[140:143], v189
	global_load_lds_dwordx4 v[214:215], off
	v_lshl_add_u64 v[214:215], s[20:21], 0, v[134:135]
	s_add_i32 m0, s27, 0xe000
	ds_read_b128 v[144:147], v189 offset:1024
	global_load_lds_dwordx4 v[214:215], off
	ds_read_b128 v[152:155], v189 offset:2048
	ds_read_b128 v[156:159], v189 offset:3072
	ds_read_b128 v[160:163], v190
	ds_read_b128 v[164:167], v190 offset:1024
	ds_read_b128 v[168:171], v190 offset:2048
	ds_read_b128 v[172:175], v190 offset:3072
	ds_read_b128 v[176:179], v191
	ds_read_b128 v[180:183], v191 offset:1024
	ds_read_b128 v[184:187], v191 offset:2048
	ds_read_b128 v[194:197], v191 offset:3072
	ds_read_b128 v[198:201], v191 offset:4096
	ds_read_b128 v[202:205], v191 offset:5120
	ds_read_b128 v[206:209], v191 offset:6144
	ds_read_b128 v[210:213], v191 offset:7168
	s_waitcnt vmcnt(8)
	s_waitcnt lgkmcnt(0)
	s_barrier
	s_setprio 1
	s_waitcnt lgkmcnt(0)
	v_mfma_f32_16x16x32_bf16 v[124:127], v[140:143], v[176:179], v[124:127]
	v_mfma_f32_16x16x32_bf16 v[120:123], v[152:155], v[176:179], v[120:123]
	v_mfma_f32_16x16x32_bf16 v[108:111], v[140:143], v[184:187], v[108:111]
	v_mfma_f32_16x16x32_bf16 v[104:107], v[152:155], v[184:187], v[104:107]
	v_mfma_f32_16x16x32_bf16 v[92:95], v[140:143], v[198:201], v[92:95]
	v_mfma_f32_16x16x32_bf16 v[88:91], v[152:155], v[198:201], v[88:91]
	v_mfma_f32_16x16x32_bf16 v[76:79], v[140:143], v[206:209], v[76:79]
	v_mfma_f32_16x16x32_bf16 v[72:75], v[152:155], v[206:209], v[72:75]
	v_mfma_f32_16x16x32_bf16 v[124:127], v[144:147], v[180:183], v[124:127]
	v_mfma_f32_16x16x32_bf16 v[120:123], v[156:159], v[180:183], v[120:123]
	v_mfma_f32_16x16x32_bf16 v[108:111], v[144:147], v[194:197], v[108:111]
	v_mfma_f32_16x16x32_bf16 v[104:107], v[156:159], v[194:197], v[104:107]
	v_mfma_f32_16x16x32_bf16 v[92:95], v[144:147], v[202:205], v[92:95]
	v_mfma_f32_16x16x32_bf16 v[88:91], v[156:159], v[202:205], v[88:91]
	v_mfma_f32_16x16x32_bf16 v[76:79], v[144:147], v[210:213], v[76:79]
	v_mfma_f32_16x16x32_bf16 v[72:75], v[156:159], v[210:213], v[72:75]
	s_nop 0
	s_nop 0
	v_mfma_f32_16x16x32_bf16 v[116:119], v[160:163], v[176:179], v[116:119]
	v_mfma_f32_16x16x32_bf16 v[112:115], v[168:171], v[176:179], v[112:115]
	v_mfma_f32_16x16x32_bf16 v[100:103], v[160:163], v[184:187], v[100:103]
	v_mfma_f32_16x16x32_bf16 v[96:99], v[168:171], v[184:187], v[96:99]
	v_mfma_f32_16x16x32_bf16 v[84:87], v[160:163], v[198:201], v[84:87]
	v_mfma_f32_16x16x32_bf16 v[80:83], v[168:171], v[198:201], v[80:83]
	v_mfma_f32_16x16x32_bf16 v[68:71], v[160:163], v[206:209], v[68:71]
	v_mfma_f32_16x16x32_bf16 v[64:67], v[168:171], v[206:209], v[64:67]
	v_mfma_f32_16x16x32_bf16 v[116:119], v[164:167], v[180:183], v[116:119]
	v_mfma_f32_16x16x32_bf16 v[112:115], v[172:175], v[180:183], v[112:115]
	v_mfma_f32_16x16x32_bf16 v[100:103], v[164:167], v[194:197], v[100:103]
	v_mfma_f32_16x16x32_bf16 v[96:99], v[172:175], v[194:197], v[96:99]
	v_mfma_f32_16x16x32_bf16 v[84:87], v[164:167], v[202:205], v[84:87]
	v_mfma_f32_16x16x32_bf16 v[80:83], v[172:175], v[202:205], v[80:83]
	v_mfma_f32_16x16x32_bf16 v[68:71], v[164:167], v[210:213], v[68:71]
	v_mfma_f32_16x16x32_bf16 v[64:67], v[172:175], v[210:213], v[64:67]
	s_setprio 0
	s_barrier
	s_add_i32 s50, s38, s26
	v_lshl_add_u64 v[214:215], s[22:23], 0, v[128:129]
	s_mov_b32 m0, s50
	v_lshl_add_u64 v[216:217], s[22:23], 0, v[130:131]
	global_load_lds_dwordx4 v[214:215], off
	s_add_i32 m0, s50, 0x2000
	s_add_u32 s50, s22, 0xb0000
	s_addc_u32 s51, s23, 0
	s_add_i32 s52, s39, s26
	global_load_lds_dwordx4 v[216:217], off
	v_lshl_add_u64 v[218:219], s[50:51], 0, v[128:129]
	s_mov_b32 m0, s52
	v_lshl_add_u64 v[220:221], s[24:25], 0, v[130:131]
	global_load_lds_dwordx4 v[218:219], off
	v_lshl_add_u64 v[218:219], s[50:51], 0, v[130:131]
	s_add_i32 m0, s52, 0x2000
	ds_read_b128 v[176:179], v191 offset:16384
	global_load_lds_dwordx4 v[218:219], off
	v_lshl_add_u64 v[218:219], s[24:25], 0, v[128:129]
	s_mov_b32 m0, s27
	ds_read_b128 v[180:183], v191 offset:17408
	global_load_lds_dwordx4 v[218:219], off
	s_mov_b32 m0, s28
	ds_read_b128 v[184:187], v191 offset:18432
	global_load_lds_dwordx4 v[220:221], off
	ds_read_b128 v[194:197], v191 offset:19456
	ds_read_b128 v[198:201], v191 offset:20480
	ds_read_b128 v[202:205], v191 offset:21504
	ds_read_b128 v[206:209], v191 offset:22528
	ds_read_b128 v[210:213], v191 offset:23552
	s_waitcnt vmcnt(8)
	s_waitcnt lgkmcnt(0)
	s_barrier
; #define PG8_STAGE(bufoff, gbase, voff) do { _Pragma("unroll") for (int _i = 0; _i < 2; ++_i) \
;         __builtin_amdgcn_global_load_lds((const unsigned*)((const char*)(gbase) + (voff)[_i]), (PG8_LAS unsigned*)(lds + (bufoff) + ldsw + _i * 8192), 16, 0, 0); } while (0)
; #define PG8_LDA(dst, b, h) do { _Pragma("unroll") for (int m = 0; m < 4; ++m) _Pragma("unroll") for (int k = 0; k < 2; ++k) dst[m][k] = *(const PG8_LAS bf16x8*)(lds + PG8_SA(b, h) + aoff + m * 2048 + k * 1024); } while (0)
; #define PG8_LDB(dst, b, h) do { _Pragma("unroll") for (int n = 0; n < 2; ++n) _Pragma("unroll") for (int k = 0; k < 2; ++k) dst[n][k] = *(const PG8_LAS bf16x8*)(lds + PG8_SB(b, h) + boff + n * 2048 + k * 1024); } while (0)
; #define PG8_MMA(ai, bj, At, Bt) do { __builtin_amdgcn_s_setprio(1); _Pragma("unroll") for (int m = 0; m < 4; ++m) _Pragma("unroll") for (int n = 0; n < 2; ++n) _Pragma("unroll") for (int k = 0; k < 2; ++k) \
;         acc[ai][bj][m][n] = __builtin_amdgcn_mfma_f32_16x16x32_bf16(Bt[n][k], At[m][k], acc[ai][bj][m][n], 0, 0, 0); __builtin_amdgcn_s_setprio(0); } while (0)
; #define PG8_WAIT_V(n) asm volatile("s_waitcnt vmcnt(" #n ")" ::: "memory")
; #define PG8_WAIT_L(n) asm volatile("s_waitcnt lgkmcnt(" #n ")" ::: "memory")
; #define PG8_BAR __builtin_amdgcn_s_barrier()
; #define PG8_SCHED __builtin_amdgcn_sched_barrier(0)
; template <class Epi, class Sched, bool ALIGN_EPI = false, bool SP2 = false>
; __device__ __forceinline__ void gemm_phase(PG8_LAS unsigned char* lds, const Gemm g, const Sched& S, const Epi& E) {
;     ...
;             PG8_WAIT_V(8); PG8_WAIT_L(0); PG8_BAR; PG8_MMA(1, 0, At, B0); PG8_MMA(1, 1, At, B1); PG8_BAR; PG8_SCHED;
;             PG8_LDB(B0, 1, 0); PG8_LDB(B1, 1, 1); PG8_SCHED; PG8_LDA(At, 1, 0); PG8_STAGE(PG8_SA(0, 1), a2 + hstep, voffA);
;             PG8_WAIT_V(8); PG8_WAIT_L(0); PG8_BAR; PG8_MMA(0, 0, At, B0); PG8_MMA(0, 1, At, B1); PG8_BAR; PG8_SCHED;
	s_setprio 1
	s_waitcnt lgkmcnt(0)
	v_mfma_f32_16x16x32_bf16 v[60:63], v[140:143], v[176:179], v[60:63]
	v_mfma_f32_16x16x32_bf16 v[56:59], v[152:155], v[176:179], v[56:59]
	v_mfma_f32_16x16x32_bf16 v[44:47], v[140:143], v[184:187], v[44:47]
	v_mfma_f32_16x16x32_bf16 v[40:43], v[152:155], v[184:187], v[40:43]
	v_mfma_f32_16x16x32_bf16 v[28:31], v[140:143], v[198:201], v[28:31]
	v_mfma_f32_16x16x32_bf16 v[24:27], v[152:155], v[198:201], v[24:27]
	v_mfma_f32_16x16x32_bf16 v[12:15], v[140:143], v[206:209], v[12:15]
	v_mfma_f32_16x16x32_bf16 v[8:11], v[152:155], v[206:209], v[8:11]
	v_mfma_f32_16x16x32_bf16 v[60:63], v[144:147], v[180:183], v[60:63]
	v_mfma_f32_16x16x32_bf16 v[56:59], v[156:159], v[180:183], v[56:59]
	v_mfma_f32_16x16x32_bf16 v[44:47], v[144:147], v[194:197], v[44:47]
	v_mfma_f32_16x16x32_bf16 v[40:43], v[156:159], v[194:197], v[40:43]
	v_mfma_f32_16x16x32_bf16 v[28:31], v[144:147], v[202:205], v[28:31]
	v_mfma_f32_16x16x32_bf16 v[24:27], v[156:159], v[202:205], v[24:27]
	v_mfma_f32_16x16x32_bf16 v[12:15], v[144:147], v[210:213], v[12:15]
	v_mfma_f32_16x16x32_bf16 v[8:11], v[156:159], v[210:213], v[8:11]
	s_nop 0
	s_nop 0
	v_mfma_f32_16x16x32_bf16 v[52:55], v[160:163], v[176:179], v[52:55]
	v_mfma_f32_16x16x32_bf16 v[48:51], v[168:171], v[176:179], v[48:51]
	v_mfma_f32_16x16x32_bf16 v[36:39], v[160:163], v[184:187], v[36:39]
	v_mfma_f32_16x16x32_bf16 v[32:35], v[168:171], v[184:187], v[32:35]
	v_mfma_f32_16x16x32_bf16 v[20:23], v[160:163], v[198:201], v[20:23]
	v_mfma_f32_16x16x32_bf16 v[16:19], v[168:171], v[198:201], v[16:19]
	v_mfma_f32_16x16x32_bf16 v[4:7], v[160:163], v[206:209], v[4:7]
	v_mfma_f32_16x16x32_bf16 v[0:3], v[168:171], v[206:209], v[0:3]
	v_mfma_f32_16x16x32_bf16 v[52:55], v[164:167], v[180:183], v[52:55]
	v_mfma_f32_16x16x32_bf16 v[48:51], v[172:175], v[180:183], v[48:51]
	v_mfma_f32_16x16x32_bf16 v[36:39], v[164:167], v[194:197], v[36:39]
	v_mfma_f32_16x16x32_bf16 v[32:35], v[172:175], v[194:197], v[32:35]
	v_mfma_f32_16x16x32_bf16 v[20:23], v[164:167], v[202:205], v[20:23]
	v_mfma_f32_16x16x32_bf16 v[16:19], v[172:175], v[202:205], v[16:19]
	v_mfma_f32_16x16x32_bf16 v[4:7], v[164:167], v[210:213], v[4:7]
	v_mfma_f32_16x16x32_bf16 v[0:3], v[172:175], v[210:213], v[0:3]
	s_setprio 0
	s_barrier
	s_add_i32 s50, 0, 0x18000
	s_add_i32 s51, 0, 0x1c000
	s_add_u32 s24, s24, 0xb0000
	s_addc_u32 s25, s25, 0
	s_mov_b32 m0, s29
	v_lshl_add_u64 v[222:223], s[24:25], 0, v[128:129]
	global_load_lds_dwordx4 v[222:223], off
	v_lshl_add_u64 v[222:223], s[24:25], 0, v[130:131]
	s_mov_b32 m0, s30
	v_add_u32_e32 v156, s50, v151
	global_load_lds_dwordx4 v[222:223], off
	v_add_u32_e32 v172, s51, v151
	ds_read_b128 v[140:143], v156
	ds_read_b128 v[144:147], v156 offset:1024
	ds_read_b128 v[152:155], v156 offset:2048
	ds_read_b128 v[156:159], v156 offset:3072
	ds_read_b128 v[160:163], v172
	ds_read_b128 v[164:167], v172 offset:1024
	ds_read_b128 v[168:171], v172 offset:2048
	ds_read_b128 v[172:175], v172 offset:3072
	ds_read_b128 v[176:179], v191 offset:32768
	ds_read_b128 v[180:183], v191 offset:33792
	ds_read_b128 v[184:187], v191 offset:34816
	ds_read_b128 v[194:197], v191 offset:35840
	ds_read_b128 v[198:201], v191 offset:36864
	ds_read_b128 v[202:205], v191 offset:37888
	ds_read_b128 v[206:209], v191 offset:38912
	ds_read_b128 v[210:213], v191 offset:39936
	s_waitcnt vmcnt(8)
	s_waitcnt lgkmcnt(0)
	s_barrier
	s_setprio 1
	s_waitcnt lgkmcnt(0)
	v_mfma_f32_16x16x32_bf16 v[124:127], v[140:143], v[176:179], v[124:127]
	v_mfma_f32_16x16x32_bf16 v[120:123], v[152:155], v[176:179], v[120:123]
	v_mfma_f32_16x16x32_bf16 v[108:111], v[140:143], v[184:187], v[108:111]
	v_mfma_f32_16x16x32_bf16 v[104:107], v[152:155], v[184:187], v[104:107]
	v_mfma_f32_16x16x32_bf16 v[92:95], v[140:143], v[198:201], v[92:95]
	v_mfma_f32_16x16x32_bf16 v[88:91], v[152:155], v[198:201], v[88:91]
	v_mfma_f32_16x16x32_bf16 v[76:79], v[140:143], v[206:209], v[76:79]
	v_mfma_f32_16x16x32_bf16 v[72:75], v[152:155], v[206:209], v[72:75]
	v_mfma_f32_16x16x32_bf16 v[124:127], v[144:147], v[180:183], v[124:127]
	v_mfma_f32_16x16x32_bf16 v[120:123], v[156:159], v[180:183], v[120:123]
	v_mfma_f32_16x16x32_bf16 v[108:111], v[144:147], v[194:197], v[108:111]
	v_mfma_f32_16x16x32_bf16 v[104:107], v[156:159], v[194:197], v[104:107]
	v_mfma_f32_16x16x32_bf16 v[92:95], v[144:147], v[202:205], v[92:95]
	v_mfma_f32_16x16x32_bf16 v[88:91], v[156:159], v[202:205], v[88:91]
	v_mfma_f32_16x16x32_bf16 v[76:79], v[144:147], v[210:213], v[76:79]
	v_mfma_f32_16x16x32_bf16 v[72:75], v[156:159], v[210:213], v[72:75]
	s_nop 0
	s_nop 0
	v_mfma_f32_16x16x32_bf16 v[116:119], v[160:163], v[176:179], v[116:119]
	v_mfma_f32_16x16x32_bf16 v[112:115], v[168:171], v[176:179], v[112:115]
	v_mfma_f32_16x16x32_bf16 v[100:103], v[160:163], v[184:187], v[100:103]
	v_mfma_f32_16x16x32_bf16 v[96:99], v[168:171], v[184:187], v[96:99]
	v_mfma_f32_16x16x32_bf16 v[84:87], v[160:163], v[198:201], v[84:87]
	v_mfma_f32_16x16x32_bf16 v[80:83], v[168:171], v[198:201], v[80:83]
	v_mfma_f32_16x16x32_bf16 v[68:71], v[160:163], v[206:209], v[68:71]
	v_mfma_f32_16x16x32_bf16 v[64:67], v[168:171], v[206:209], v[64:67]
	v_mfma_f32_16x16x32_bf16 v[116:119], v[164:167], v[180:183], v[116:119]
	v_mfma_f32_16x16x32_bf16 v[112:115], v[172:175], v[180:183], v[112:115]
	v_mfma_f32_16x16x32_bf16 v[100:103], v[164:167], v[194:197], v[100:103]
	v_mfma_f32_16x16x32_bf16 v[96:99], v[172:175], v[194:197], v[96:99]
	v_mfma_f32_16x16x32_bf16 v[84:87], v[164:167], v[202:205], v[84:87]
	v_mfma_f32_16x16x32_bf16 v[80:83], v[172:175], v[202:205], v[80:83]
	v_mfma_f32_16x16x32_bf16 v[68:71], v[164:167], v[210:213], v[68:71]
	v_mfma_f32_16x16x32_bf16 v[64:67], v[172:175], v[210:213], v[64:67]
	s_setprio 0
	s_barrier
; #define PG8_STAGE(bufoff, gbase, voff) do { _Pragma("unroll") for (int _i = 0; _i < 2; ++_i) \
;         __builtin_amdgcn_global_load_lds((const unsigned*)((const char*)(gbase) + (voff)[_i]), (PG8_LAS unsigned*)(lds + (bufoff) + ldsw + _i * 8192), 16, 0, 0); } while (0)
; #define PG8_LDA(dst, b, h) do { _Pragma("unroll") for (int m = 0; m < 4; ++m) _Pragma("unroll") for (int k = 0; k < 2; ++k) dst[m][k] = *(const PG8_LAS bf16x8*)(lds + PG8_SA(b, h) + aoff + m * 2048 + k * 1024); } while (0)
; #define PG8_MMA(ai, bj, At, Bt) do { __builtin_amdgcn_s_setprio(1); _Pragma("unroll") for (int m = 0; m < 4; ++m) _Pragma("unroll") for (int n = 0; n < 2; ++n) _Pragma("unroll") for (int k = 0; k < 2; ++k) \
;         acc[ai][bj][m][n] = __builtin_amdgcn_mfma_f32_16x16x32_bf16(Bt[n][k], At[m][k], acc[ai][bj][m][n], 0, 0, 0); __builtin_amdgcn_s_setprio(0); } while (0)
; #define PG8_WAIT_V(n) asm volatile("s_waitcnt vmcnt(" #n ")" ::: "memory")
; #define PG8_WAIT_L(n) asm volatile("s_waitcnt lgkmcnt(" #n ")" ::: "memory")
; #define PG8_BAR __builtin_amdgcn_s_barrier()
; #define PG8_SCHED __builtin_amdgcn_sched_barrier(0)
; template <class Epi, class Sched, bool ALIGN_EPI = false, bool SP2 = false>
; __device__ __forceinline__ void gemm_phase(PG8_LAS unsigned char* lds, const Gemm g, const Sched& S, const Epi& E) {
;     ...
;             PG8_LDA(At, 1, 1); PG8_STAGE(PG8_SB(1, 0), b3, voffB); PG8_STAGE(PG8_SB(1, 1), b3 + hstep, voffB); PG8_STAGE(PG8_SA(1, 0), a3, voffA);
;             PG8_WAIT_V(8); PG8_WAIT_L(0); PG8_BAR; PG8_MMA(1, 0, At, B0); PG8_MMA(1, 1, At, B1); PG8_BAR; PG8_SCHED;
;     ...
;         if constexpr (ALIGN_EPI) { if (wr == 0) PG8_BAR; }
	s_add_i32 s24, s50, s26
	v_lshl_add_u64 v[214:215], v[214:215], 0, s[14:15]
	s_mov_b32 m0, s24
	ds_read_b128 v[176:179], v191 offset:49152
	global_load_lds_dwordx4 v[214:215], off
	s_add_i32 m0, s24, 0x2000
	s_add_u32 s22, s22, 0xb0080
	v_lshl_add_u64 v[214:215], v[216:217], 0, s[14:15]
	s_addc_u32 s23, s23, 0
	s_add_i32 s24, s51, s26
	global_load_lds_dwordx4 v[214:215], off
	v_lshl_add_u64 v[214:215], s[22:23], 0, v[128:129]
	s_mov_b32 m0, s24
	ds_read_b128 v[180:183], v191 offset:50176
	global_load_lds_dwordx4 v[214:215], off
	v_lshl_add_u64 v[214:215], s[22:23], 0, v[130:131]
	s_add_i32 m0, s24, 0x2000
	ds_read_b128 v[184:187], v191 offset:51200
	global_load_lds_dwordx4 v[214:215], off
	v_lshl_add_u64 v[214:215], v[218:219], 0, s[14:15]
	s_mov_b32 m0, s34
	ds_read_b128 v[194:197], v191 offset:52224
	global_load_lds_dwordx4 v[214:215], off
	v_lshl_add_u64 v[214:215], v[220:221], 0, s[14:15]
	s_mov_b32 m0, s35
	ds_read_b128 v[198:201], v191 offset:53248
	global_load_lds_dwordx4 v[214:215], off
	ds_read_b128 v[202:205], v191 offset:54272
	ds_read_b128 v[206:209], v191 offset:55296
	ds_read_b128 v[210:213], v191 offset:56320
	s_waitcnt vmcnt(8)
	s_waitcnt lgkmcnt(0)
	s_barrier
	s_setprio 1
	s_waitcnt lgkmcnt(0)
	v_mfma_f32_16x16x32_bf16 v[60:63], v[140:143], v[176:179], v[60:63]
	v_mfma_f32_16x16x32_bf16 v[56:59], v[152:155], v[176:179], v[56:59]
	v_mfma_f32_16x16x32_bf16 v[44:47], v[140:143], v[184:187], v[44:47]
	v_mfma_f32_16x16x32_bf16 v[40:43], v[152:155], v[184:187], v[40:43]
	v_mfma_f32_16x16x32_bf16 v[28:31], v[140:143], v[198:201], v[28:31]
	v_mfma_f32_16x16x32_bf16 v[24:27], v[152:155], v[198:201], v[24:27]
	v_mfma_f32_16x16x32_bf16 v[12:15], v[140:143], v[206:209], v[12:15]
	v_mfma_f32_16x16x32_bf16 v[8:11], v[152:155], v[206:209], v[8:11]
	v_mfma_f32_16x16x32_bf16 v[60:63], v[144:147], v[180:183], v[60:63]
	v_mfma_f32_16x16x32_bf16 v[56:59], v[156:159], v[180:183], v[56:59]
	v_mfma_f32_16x16x32_bf16 v[44:47], v[144:147], v[194:197], v[44:47]
	v_mfma_f32_16x16x32_bf16 v[40:43], v[156:159], v[194:197], v[40:43]
	v_mfma_f32_16x16x32_bf16 v[28:31], v[144:147], v[202:205], v[28:31]
	v_mfma_f32_16x16x32_bf16 v[24:27], v[156:159], v[202:205], v[24:27]
	v_mfma_f32_16x16x32_bf16 v[12:15], v[144:147], v[210:213], v[12:15]
	v_mfma_f32_16x16x32_bf16 v[8:11], v[156:159], v[210:213], v[8:11]
	s_nop 0
	s_nop 0
	v_mfma_f32_16x16x32_bf16 v[52:55], v[160:163], v[176:179], v[52:55]
	v_mfma_f32_16x16x32_bf16 v[48:51], v[168:171], v[176:179], v[48:51]
	v_mfma_f32_16x16x32_bf16 v[36:39], v[160:163], v[184:187], v[36:39]
	v_mfma_f32_16x16x32_bf16 v[32:35], v[168:171], v[184:187], v[32:35]
	v_mfma_f32_16x16x32_bf16 v[20:23], v[160:163], v[198:201], v[20:23]
	v_mfma_f32_16x16x32_bf16 v[16:19], v[168:171], v[198:201], v[16:19]
	v_mfma_f32_16x16x32_bf16 v[4:7], v[160:163], v[206:209], v[4:7]
	v_mfma_f32_16x16x32_bf16 v[0:3], v[168:171], v[206:209], v[0:3]
	v_mfma_f32_16x16x32_bf16 v[52:55], v[164:167], v[180:183], v[52:55]
	v_mfma_f32_16x16x32_bf16 v[48:51], v[172:175], v[180:183], v[48:51]
	v_mfma_f32_16x16x32_bf16 v[36:39], v[164:167], v[194:197], v[36:39]
	v_mfma_f32_16x16x32_bf16 v[32:35], v[172:175], v[194:197], v[32:35]
	v_mfma_f32_16x16x32_bf16 v[20:23], v[164:167], v[202:205], v[20:23]
	v_mfma_f32_16x16x32_bf16 v[16:19], v[172:175], v[202:205], v[16:19]
	v_mfma_f32_16x16x32_bf16 v[4:7], v[164:167], v[210:213], v[4:7]
	v_mfma_f32_16x16x32_bf16 v[0:3], v[172:175], v[210:213], v[0:3]
	s_setprio 0
	s_barrier
	s_add_i32 s47, s47, 2
	s_add_u32 s20, s20, 0x100
	s_addc_u32 s21, s21, 0
	s_add_u32 s45, s45, 0x100
	s_addc_u32 s46, s46, 0
	s_cmp_gt_u32 s47, 41
	s_cbranch_scc0 .LBB0_1572
	s_nop 0
	s_nop 0
	s_nop 0
	s_nop 0
	s_nop 0
	s_nop 0
	s_nop 0
	s_nop 0
	s_nop 0
	s_and_b64 vcc, exec, s[16:17]
	s_cbranch_vccz .LBB0_1575
	s_barrier

; #define PG8_STAGE(bufoff, gbase, voff) do { _Pragma("unroll") for (int _i = 0; _i < 2; ++_i) \
;         __builtin_amdgcn_global_load_lds((const unsigned*)((const char*)(gbase) + (voff)[_i]), (PG8_LAS unsigned*)(lds + (bufoff) + ldsw + _i * 8192), 16, 0, 0); } while (0)
; #define PG8_LDA(dst, b, h) do { _Pragma("unroll") for (int m = 0; m < 4; ++m) _Pragma("unroll") for (int k = 0; k < 2; ++k) dst[m][k] = *(const PG8_LAS bf16x8*)(lds + PG8_SA(b, h) + aoff + m * 2048 + k * 1024); } while (0)
; #define PG8_LDB(dst, b, h) do { _Pragma("unroll") for (int n = 0; n < 2; ++n) _Pragma("unroll") for (int k = 0; k < 2; ++k) dst[n][k] = *(const PG8_LAS bf16x8*)(lds + PG8_SB(b, h) + boff + n * 2048 + k * 1024); } while (0)
; #define PG8_MMA(ai, bj, At, Bt) do { __builtin_amdgcn_s_setprio(1); _Pragma("unroll") for (int m = 0; m < 4; ++m) _Pragma("unroll") for (int n = 0; n < 2; ++n) _Pragma("unroll") for (int k = 0; k < 2; ++k) \
;         acc[ai][bj][m][n] = __builtin_amdgcn_mfma_f32_16x16x32_bf16(Bt[n][k], At[m][k], acc[ai][bj][m][n], 0, 0, 0); __builtin_amdgcn_s_setprio(0); } while (0)
; #define PG8_WAIT_V(n) asm volatile("s_waitcnt vmcnt(" #n ")" ::: "memory")
; #define PG8_WAIT_L(n) asm volatile("s_waitcnt lgkmcnt(" #n ")" ::: "memory")
; template <class Epi, class Sched, bool ALIGN_EPI = false, bool SP2 = false>
; __device__ __forceinline__ void gemm_phase(PG8_LAS unsigned char* lds, const Gemm g, const Sched& S, const Epi& E) {
;     ...
;             const bool last = (t == nt - 2);
;             const char* a1 = cA + (size_t)(t + 1) * kstep;
;             const char* a2 = last ? nA : cA + (size_t)(t + 2) * kstep; const char* b2 = last ? nB : cB + (size_t)(t + 2) * kstep;
;             const char* a3 = a2 + kstep; const char* b3 = b2 + kstep;
;             if (last && has_next) S.a_ready(nxt);
;             if constexpr (SP2) {
;             PG8_LDB(B0, 0, 0); PG8_LDB(B1, 0, 1); PG8_SCHED; PG8_LDA(At, 0, 0); PG8_STAGE(PG8_SA(1, 1), a1 + hstep, voffA);
;             PG8_WAIT_V(8); PG8_WAIT_L(0); PG8_BAR; PG8_MMA(0, 0, At, B0); PG8_MMA(0, 1, At, B1); PG8_BAR; PG8_SCHED;
;             PG8_LDA(At, 0, 1); PG8_STAGE(PG8_SB(0, 0), b2, voffB); PG8_STAGE(PG8_SB(0, 1), b2 + hstep, voffB); PG8_STAGE(PG8_SA(0, 0), a2, voffA);
;             PG8_WAIT_V(8); PG8_WAIT_L(0); PG8_BAR; PG8_MMA(1, 0, At, B0); PG8_MMA(1, 1, At, B1); PG8_BAR; PG8_SCHED;
.LBB0_1666:
	s_add_u32 s6, s4, 0xfffc0080
	s_addc_u32 s7, s5, -1
	s_cmp_eq_u32 s55, 12
	s_cselect_b32 s9, s10, s7
	s_cselect_b32 s8, s11, s6
	s_cselect_b32 s7, s25, s54
	s_cselect_b32 s6, s27, s53
	v_lshl_add_u64 v[152:153], s[4:5], 0, v[136:137]
	s_add_i32 m0, s39, 0xc000
	ds_read_b128 v[144:147], v155
	global_load_lds_dwordx4 v[152:153], off
	v_lshl_add_u64 v[152:153], s[4:5], 0, v[138:139]
	s_add_i32 m0, s39, 0xe000
	ds_read_b128 v[160:163], v155 offset:1024
	global_load_lds_dwordx4 v[152:153], off
	ds_read_b128 v[164:167], v155 offset:2048
	ds_read_b128 v[168:171], v155 offset:3072
	ds_read_b128 v[172:175], v156
	ds_read_b128 v[176:179], v156 offset:1024
	ds_read_b128 v[180:183], v156 offset:2048
	ds_read_b128 v[184:187], v156 offset:3072
	ds_read_b128 v[188:191], v157
	ds_read_b128 v[192:195], v157 offset:1024
	ds_read_b128 v[196:199], v157 offset:2048
	ds_read_b128 v[200:203], v157 offset:3072
	ds_read_b128 v[204:207], v157 offset:4096
	ds_read_b128 v[208:211], v157 offset:5120
	ds_read_b128 v[212:215], v157 offset:6144
	ds_read_b128 v[216:219], v157 offset:7168
	s_waitcnt vmcnt(8)
	s_waitcnt lgkmcnt(0)
	s_barrier
	s_setprio 1
	s_waitcnt lgkmcnt(0)
	v_mfma_f32_16x16x32_bf16 v[124:127], v[144:147], v[188:191], v[124:127]
	v_mfma_f32_16x16x32_bf16 v[116:119], v[164:167], v[188:191], v[116:119]
	v_mfma_f32_16x16x32_bf16 v[108:111], v[144:147], v[196:199], v[108:111]
	v_mfma_f32_16x16x32_bf16 v[100:103], v[164:167], v[196:199], v[100:103]
	v_mfma_f32_16x16x32_bf16 v[92:95], v[144:147], v[204:207], v[92:95]
	v_mfma_f32_16x16x32_bf16 v[84:87], v[164:167], v[204:207], v[84:87]
	v_mfma_f32_16x16x32_bf16 v[76:79], v[144:147], v[212:215], v[76:79]
	v_mfma_f32_16x16x32_bf16 v[68:71], v[164:167], v[212:215], v[68:71]
	v_mfma_f32_16x16x32_bf16 v[124:127], v[160:163], v[192:195], v[124:127]
	v_mfma_f32_16x16x32_bf16 v[116:119], v[168:171], v[192:195], v[116:119]
	v_mfma_f32_16x16x32_bf16 v[108:111], v[160:163], v[200:203], v[108:111]
	v_mfma_f32_16x16x32_bf16 v[100:103], v[168:171], v[200:203], v[100:103]
	v_mfma_f32_16x16x32_bf16 v[92:95], v[160:163], v[208:211], v[92:95]
	v_mfma_f32_16x16x32_bf16 v[84:87], v[168:171], v[208:211], v[84:87]
	v_mfma_f32_16x16x32_bf16 v[76:79], v[160:163], v[216:219], v[76:79]
	v_mfma_f32_16x16x32_bf16 v[68:71], v[168:171], v[216:219], v[68:71]
	s_nop 0
	s_nop 0
	v_mfma_f32_16x16x32_bf16 v[120:123], v[172:175], v[188:191], v[120:123]
	v_mfma_f32_16x16x32_bf16 v[112:115], v[180:183], v[188:191], v[112:115]
	v_mfma_f32_16x16x32_bf16 v[104:107], v[172:175], v[196:199], v[104:107]
	v_mfma_f32_16x16x32_bf16 v[96:99], v[180:183], v[196:199], v[96:99]
	v_mfma_f32_16x16x32_bf16 v[88:91], v[172:175], v[204:207], v[88:91]
	v_mfma_f32_16x16x32_bf16 v[80:83], v[180:183], v[204:207], v[80:83]
	v_mfma_f32_16x16x32_bf16 v[72:75], v[172:175], v[212:215], v[72:75]
	v_mfma_f32_16x16x32_bf16 v[64:67], v[180:183], v[212:215], v[64:67]
	v_mfma_f32_16x16x32_bf16 v[120:123], v[176:179], v[192:195], v[120:123]
	v_mfma_f32_16x16x32_bf16 v[112:115], v[184:187], v[192:195], v[112:115]
	v_mfma_f32_16x16x32_bf16 v[104:107], v[176:179], v[200:203], v[104:107]
	v_mfma_f32_16x16x32_bf16 v[96:99], v[184:187], v[200:203], v[96:99]
	v_mfma_f32_16x16x32_bf16 v[88:91], v[176:179], v[208:211], v[88:91]
	v_mfma_f32_16x16x32_bf16 v[80:83], v[184:187], v[208:211], v[80:83]
	v_mfma_f32_16x16x32_bf16 v[72:75], v[176:179], v[216:219], v[72:75]
	v_mfma_f32_16x16x32_bf16 v[64:67], v[184:187], v[216:219], v[64:67]
	s_setprio 0
	s_barrier
	s_add_i32 s56, s47, s36
	v_lshl_add_u64 v[152:153], s[6:7], 0, v[132:133]
	s_mov_b32 m0, s56
	v_lshl_add_u64 v[220:221], s[6:7], 0, v[128:129]
	global_load_lds_dwordx4 v[152:153], off
	s_add_i32 m0, s56, 0x2000
	s_add_u32 s56, s6, 0x40000
	s_addc_u32 s57, s7, 0
	s_add_i32 s58, s50, s36
	global_load_lds_dwordx4 v[220:221], off
	v_lshl_add_u64 v[222:223], s[56:57], 0, v[132:133]
	s_mov_b32 m0, s58
	v_lshl_add_u64 v[224:225], s[8:9], 0, v[130:131]
	global_load_lds_dwordx4 v[222:223], off
	v_lshl_add_u64 v[222:223], s[56:57], 0, v[128:129]
	s_add_i32 m0, s58, 0x2000
	ds_read_b128 v[188:191], v157 offset:16384
	global_load_lds_dwordx4 v[222:223], off
	v_lshl_add_u64 v[222:223], s[8:9], 0, v[134:135]
	s_mov_b32 m0, s39
	ds_read_b128 v[192:195], v157 offset:17408
	global_load_lds_dwordx4 v[222:223], off
	s_mov_b32 m0, s40
	ds_read_b128 v[196:199], v157 offset:18432
	global_load_lds_dwordx4 v[224:225], off
	ds_read_b128 v[200:203], v157 offset:19456
	ds_read_b128 v[204:207], v157 offset:20480
	ds_read_b128 v[208:211], v157 offset:21504
	ds_read_b128 v[212:215], v157 offset:22528
	ds_read_b128 v[216:219], v157 offset:23552
	s_waitcnt vmcnt(8)
	s_waitcnt lgkmcnt(0)
	s_barrier
; #define PG8_STAGE(bufoff, gbase, voff) do { _Pragma("unroll") for (int _i = 0; _i < 2; ++_i) \
;         __builtin_amdgcn_global_load_lds((const unsigned*)((const char*)(gbase) + (voff)[_i]), (PG8_LAS unsigned*)(lds + (bufoff) + ldsw + _i * 8192), 16, 0, 0); } while (0)
; #define PG8_LDA(dst, b, h) do { _Pragma("unroll") for (int m = 0; m < 4; ++m) _Pragma("unroll") for (int k = 0; k < 2; ++k) dst[m][k] = *(const PG8_LAS bf16x8*)(lds + PG8_SA(b, h) + aoff + m * 2048 + k * 1024); } while (0)
; #define PG8_LDB(dst, b, h) do { _Pragma("unroll") for (int n = 0; n < 2; ++n) _Pragma("unroll") for (int k = 0; k < 2; ++k) dst[n][k] = *(const PG8_LAS bf16x8*)(lds + PG8_SB(b, h) + boff + n * 2048 + k * 1024); } while (0)
; #define PG8_MMA(ai, bj, At, Bt) do { __builtin_amdgcn_s_setprio(1); _Pragma("unroll") for (int m = 0; m < 4; ++m) _Pragma("unroll") for (int n = 0; n < 2; ++n) _Pragma("unroll") for (int k = 0; k < 2; ++k) \
;         acc[ai][bj][m][n] = __builtin_amdgcn_mfma_f32_16x16x32_bf16(Bt[n][k], At[m][k], acc[ai][bj][m][n], 0, 0, 0); __builtin_amdgcn_s_setprio(0); } while (0)
; #define PG8_WAIT_V(n) asm volatile("s_waitcnt vmcnt(" #n ")" ::: "memory")
; #define PG8_WAIT_L(n) asm volatile("s_waitcnt lgkmcnt(" #n ")" ::: "memory")
; #define PG8_BAR __builtin_amdgcn_s_barrier()
; #define PG8_SCHED __builtin_amdgcn_sched_barrier(0)
; template <class Epi, class Sched, bool ALIGN_EPI = false, bool SP2 = false>
; __device__ __forceinline__ void gemm_phase(PG8_LAS unsigned char* lds, const Gemm g, const Sched& S, const Epi& E) {
;     ...
;             PG8_WAIT_V(8); PG8_WAIT_L(0); PG8_BAR; PG8_MMA(1, 0, At, B0); PG8_MMA(1, 1, At, B1); PG8_BAR; PG8_SCHED;
;             PG8_LDB(B0, 1, 0); PG8_LDB(B1, 1, 1); PG8_SCHED; PG8_LDA(At, 1, 0); PG8_STAGE(PG8_SA(0, 1), a2 + hstep, voffA);
;             PG8_WAIT_V(8); PG8_WAIT_L(0); PG8_BAR; PG8_MMA(0, 0, At, B0); PG8_MMA(0, 1, At, B1); PG8_BAR; PG8_SCHED;
	s_setprio 1
	s_waitcnt lgkmcnt(0)
	v_mfma_f32_16x16x32_bf16 v[60:63], v[144:147], v[188:191], v[60:63]
	v_mfma_f32_16x16x32_bf16 v[52:55], v[164:167], v[188:191], v[52:55]
	v_mfma_f32_16x16x32_bf16 v[44:47], v[144:147], v[196:199], v[44:47]
	v_mfma_f32_16x16x32_bf16 v[36:39], v[164:167], v[196:199], v[36:39]
	v_mfma_f32_16x16x32_bf16 v[28:31], v[144:147], v[204:207], v[28:31]
	v_mfma_f32_16x16x32_bf16 v[20:23], v[164:167], v[204:207], v[20:23]
	v_mfma_f32_16x16x32_bf16 v[12:15], v[144:147], v[212:215], v[12:15]
	v_mfma_f32_16x16x32_bf16 v[4:7], v[164:167], v[212:215], v[4:7]
	v_mfma_f32_16x16x32_bf16 v[60:63], v[160:163], v[192:195], v[60:63]
	v_mfma_f32_16x16x32_bf16 v[52:55], v[168:171], v[192:195], v[52:55]
	v_mfma_f32_16x16x32_bf16 v[44:47], v[160:163], v[200:203], v[44:47]
	v_mfma_f32_16x16x32_bf16 v[36:39], v[168:171], v[200:203], v[36:39]
	v_mfma_f32_16x16x32_bf16 v[28:31], v[160:163], v[208:211], v[28:31]
	v_mfma_f32_16x16x32_bf16 v[20:23], v[168:171], v[208:211], v[20:23]
	v_mfma_f32_16x16x32_bf16 v[12:15], v[160:163], v[216:219], v[12:15]
	v_mfma_f32_16x16x32_bf16 v[4:7], v[168:171], v[216:219], v[4:7]
	s_nop 0
	s_nop 0
	v_mfma_f32_16x16x32_bf16 v[56:59], v[172:175], v[188:191], v[56:59]
	v_mfma_f32_16x16x32_bf16 v[48:51], v[180:183], v[188:191], v[48:51]
	v_mfma_f32_16x16x32_bf16 v[40:43], v[172:175], v[196:199], v[40:43]
	v_mfma_f32_16x16x32_bf16 v[32:35], v[180:183], v[196:199], v[32:35]
	v_mfma_f32_16x16x32_bf16 v[24:27], v[172:175], v[204:207], v[24:27]
	v_mfma_f32_16x16x32_bf16 v[16:19], v[180:183], v[204:207], v[16:19]
	v_mfma_f32_16x16x32_bf16 v[8:11], v[172:175], v[212:215], v[8:11]
	v_mfma_f32_16x16x32_bf16 v[0:3], v[180:183], v[212:215], v[0:3]
	v_mfma_f32_16x16x32_bf16 v[56:59], v[176:179], v[192:195], v[56:59]
	v_mfma_f32_16x16x32_bf16 v[48:51], v[184:187], v[192:195], v[48:51]
	v_mfma_f32_16x16x32_bf16 v[40:43], v[176:179], v[200:203], v[40:43]
	v_mfma_f32_16x16x32_bf16 v[32:35], v[184:187], v[200:203], v[32:35]
	v_mfma_f32_16x16x32_bf16 v[24:27], v[176:179], v[208:211], v[24:27]
	v_mfma_f32_16x16x32_bf16 v[16:19], v[184:187], v[208:211], v[16:19]
	v_mfma_f32_16x16x32_bf16 v[8:11], v[176:179], v[216:219], v[8:11]
	v_mfma_f32_16x16x32_bf16 v[0:3], v[184:187], v[216:219], v[0:3]
	s_setprio 0
	s_barrier
	s_add_i32 s56, 0, 0x18000
	s_add_i32 s57, 0, 0x1c000
	s_add_u32 s8, s8, 0x40000
	s_addc_u32 s9, s9, 0
	s_mov_b32 m0, s41
	v_lshl_add_u64 v[226:227], s[8:9], 0, v[134:135]
	global_load_lds_dwordx4 v[226:227], off
	v_lshl_add_u64 v[226:227], s[8:9], 0, v[130:131]
	s_mov_b32 m0, s42
	v_add_u32_e32 v159, s56, v151
	global_load_lds_dwordx4 v[226:227], off
	ds_read_b128 v[144:147], v159
	ds_read_b128 v[160:163], v159 offset:1024
	ds_read_b128 v[164:167], v159 offset:2048
	ds_read_b128 v[168:171], v159 offset:3072
	v_add_u32_e32 v159, s57, v151
	ds_read_b128 v[172:175], v159
	ds_read_b128 v[176:179], v159 offset:1024
	ds_read_b128 v[180:183], v159 offset:2048
	ds_read_b128 v[184:187], v159 offset:3072
	ds_read_b128 v[188:191], v157 offset:32768
	ds_read_b128 v[192:195], v157 offset:33792
	ds_read_b128 v[196:199], v157 offset:34816
	ds_read_b128 v[200:203], v157 offset:35840
	ds_read_b128 v[204:207], v157 offset:36864
	ds_read_b128 v[208:211], v157 offset:37888
	ds_read_b128 v[212:215], v157 offset:38912
	ds_read_b128 v[216:219], v157 offset:39936
	s_waitcnt vmcnt(8)
	s_waitcnt lgkmcnt(0)
	s_barrier
	s_setprio 1
	s_waitcnt lgkmcnt(0)
	v_mfma_f32_16x16x32_bf16 v[124:127], v[144:147], v[188:191], v[124:127]
	v_mfma_f32_16x16x32_bf16 v[116:119], v[164:167], v[188:191], v[116:119]
	v_mfma_f32_16x16x32_bf16 v[108:111], v[144:147], v[196:199], v[108:111]
	v_mfma_f32_16x16x32_bf16 v[100:103], v[164:167], v[196:199], v[100:103]
	v_mfma_f32_16x16x32_bf16 v[92:95], v[144:147], v[204:207], v[92:95]
	v_mfma_f32_16x16x32_bf16 v[84:87], v[164:167], v[204:207], v[84:87]
	v_mfma_f32_16x16x32_bf16 v[76:79], v[144:147], v[212:215], v[76:79]
	v_mfma_f32_16x16x32_bf16 v[68:71], v[164:167], v[212:215], v[68:71]
	v_mfma_f32_16x16x32_bf16 v[124:127], v[160:163], v[192:195], v[124:127]
	v_mfma_f32_16x16x32_bf16 v[116:119], v[168:171], v[192:195], v[116:119]
	v_mfma_f32_16x16x32_bf16 v[108:111], v[160:163], v[200:203], v[108:111]
	v_mfma_f32_16x16x32_bf16 v[100:103], v[168:171], v[200:203], v[100:103]
	v_mfma_f32_16x16x32_bf16 v[92:95], v[160:163], v[208:211], v[92:95]
	v_mfma_f32_16x16x32_bf16 v[84:87], v[168:171], v[208:211], v[84:87]
	v_mfma_f32_16x16x32_bf16 v[76:79], v[160:163], v[216:219], v[76:79]
	v_mfma_f32_16x16x32_bf16 v[68:71], v[168:171], v[216:219], v[68:71]
	s_nop 0
	s_nop 0
	v_mfma_f32_16x16x32_bf16 v[120:123], v[172:175], v[188:191], v[120:123]
	v_mfma_f32_16x16x32_bf16 v[112:115], v[180:183], v[188:191], v[112:115]
	v_mfma_f32_16x16x32_bf16 v[104:107], v[172:175], v[196:199], v[104:107]
	v_mfma_f32_16x16x32_bf16 v[96:99], v[180:183], v[196:199], v[96:99]
	v_mfma_f32_16x16x32_bf16 v[88:91], v[172:175], v[204:207], v[88:91]
	v_mfma_f32_16x16x32_bf16 v[80:83], v[180:183], v[204:207], v[80:83]
	v_mfma_f32_16x16x32_bf16 v[72:75], v[172:175], v[212:215], v[72:75]
	v_mfma_f32_16x16x32_bf16 v[64:67], v[180:183], v[212:215], v[64:67]
	v_mfma_f32_16x16x32_bf16 v[120:123], v[176:179], v[192:195], v[120:123]
	v_mfma_f32_16x16x32_bf16 v[112:115], v[184:187], v[192:195], v[112:115]
	v_mfma_f32_16x16x32_bf16 v[104:107], v[176:179], v[200:203], v[104:107]
	v_mfma_f32_16x16x32_bf16 v[96:99], v[184:187], v[200:203], v[96:99]
	v_mfma_f32_16x16x32_bf16 v[88:91], v[176:179], v[208:211], v[88:91]
	v_mfma_f32_16x16x32_bf16 v[80:83], v[184:187], v[208:211], v[80:83]
	v_mfma_f32_16x16x32_bf16 v[72:75], v[176:179], v[216:219], v[72:75]
	v_mfma_f32_16x16x32_bf16 v[64:67], v[184:187], v[216:219], v[64:67]
	s_setprio 0
	s_barrier
; #define PG8_STAGE(bufoff, gbase, voff) do { _Pragma("unroll") for (int _i = 0; _i < 2; ++_i) \
;         __builtin_amdgcn_global_load_lds((const unsigned*)((const char*)(gbase) + (voff)[_i]), (PG8_LAS unsigned*)(lds + (bufoff) + ldsw + _i * 8192), 16, 0, 0); } while (0)
; #define PG8_LDA(dst, b, h) do { _Pragma("unroll") for (int m = 0; m < 4; ++m) _Pragma("unroll") for (int k = 0; k < 2; ++k) dst[m][k] = *(const PG8_LAS bf16x8*)(lds + PG8_SA(b, h) + aoff + m * 2048 + k * 1024); } while (0)
; #define PG8_MMA(ai, bj, At, Bt) do { __builtin_amdgcn_s_setprio(1); _Pragma("unroll") for (int m = 0; m < 4; ++m) _Pragma("unroll") for (int n = 0; n < 2; ++n) _Pragma("unroll") for (int k = 0; k < 2; ++k) \
;         acc[ai][bj][m][n] = __builtin_amdgcn_mfma_f32_16x16x32_bf16(Bt[n][k], At[m][k], acc[ai][bj][m][n], 0, 0, 0); __builtin_amdgcn_s_setprio(0); } while (0)
; #define PG8_WAIT_V(n) asm volatile("s_waitcnt vmcnt(" #n ")" ::: "memory")
; #define PG8_WAIT_L(n) asm volatile("s_waitcnt lgkmcnt(" #n ")" ::: "memory")
; #define PG8_BAR __builtin_amdgcn_s_barrier()
; #define PG8_SCHED __builtin_amdgcn_sched_barrier(0)
; template <class Epi, class Sched, bool ALIGN_EPI = false, bool SP2 = false>
; __device__ __forceinline__ void gemm_phase(PG8_LAS unsigned char* lds, const Gemm g, const Sched& S, const Epi& E) {
;     ...
;             PG8_LDA(At, 1, 1); PG8_STAGE(PG8_SB(1, 0), b3, voffB); PG8_STAGE(PG8_SB(1, 1), b3 + hstep, voffB); PG8_STAGE(PG8_SA(1, 0), a3, voffA);
;             PG8_WAIT_V(8); PG8_WAIT_L(0); PG8_BAR; PG8_MMA(1, 0, At, B0); PG8_MMA(1, 1, At, B1); PG8_BAR; PG8_SCHED;
;     ...
;         if constexpr (ALIGN_EPI) { if (wr == 0) PG8_BAR; }
	s_add_i32 s8, s56, s36
	v_lshl_add_u64 v[152:153], v[152:153], 0, s[20:21]
	s_mov_b32 m0, s8
	ds_read_b128 v[188:191], v157 offset:49152
	global_load_lds_dwordx4 v[152:153], off
	s_add_i32 m0, s8, 0x2000
	s_add_u32 s6, s6, 0x40080
	v_lshl_add_u64 v[152:153], v[220:221], 0, s[20:21]
	s_addc_u32 s7, s7, 0
	s_add_i32 s8, s57, s36
	global_load_lds_dwordx4 v[152:153], off
	v_lshl_add_u64 v[152:153], s[6:7], 0, v[132:133]
	s_mov_b32 m0, s8
	ds_read_b128 v[192:195], v157 offset:50176
	global_load_lds_dwordx4 v[152:153], off
	v_lshl_add_u64 v[152:153], s[6:7], 0, v[128:129]
	s_add_i32 m0, s8, 0x2000
	ds_read_b128 v[196:199], v157 offset:51200
	global_load_lds_dwordx4 v[152:153], off
	v_lshl_add_u64 v[152:153], v[222:223], 0, s[20:21]
	s_mov_b32 m0, s44
	ds_read_b128 v[200:203], v157 offset:52224
	global_load_lds_dwordx4 v[152:153], off
	v_lshl_add_u64 v[152:153], v[224:225], 0, s[20:21]
	s_mov_b32 m0, s45
	ds_read_b128 v[204:207], v157 offset:53248
	global_load_lds_dwordx4 v[152:153], off
	ds_read_b128 v[208:211], v157 offset:54272
	ds_read_b128 v[212:215], v157 offset:55296
	ds_read_b128 v[216:219], v157 offset:56320
	s_waitcnt vmcnt(8)
	s_waitcnt lgkmcnt(0)
	s_barrier
	s_setprio 1
	s_waitcnt lgkmcnt(0)
	v_mfma_f32_16x16x32_bf16 v[60:63], v[144:147], v[188:191], v[60:63]
	v_mfma_f32_16x16x32_bf16 v[52:55], v[164:167], v[188:191], v[52:55]
	v_mfma_f32_16x16x32_bf16 v[44:47], v[144:147], v[196:199], v[44:47]
	v_mfma_f32_16x16x32_bf16 v[36:39], v[164:167], v[196:199], v[36:39]
	v_mfma_f32_16x16x32_bf16 v[28:31], v[144:147], v[204:207], v[28:31]
	v_mfma_f32_16x16x32_bf16 v[20:23], v[164:167], v[204:207], v[20:23]
	v_mfma_f32_16x16x32_bf16 v[12:15], v[144:147], v[212:215], v[12:15]
	v_mfma_f32_16x16x32_bf16 v[4:7], v[164:167], v[212:215], v[4:7]
	v_mfma_f32_16x16x32_bf16 v[60:63], v[160:163], v[192:195], v[60:63]
	v_mfma_f32_16x16x32_bf16 v[52:55], v[168:171], v[192:195], v[52:55]
	v_mfma_f32_16x16x32_bf16 v[44:47], v[160:163], v[200:203], v[44:47]
	v_mfma_f32_16x16x32_bf16 v[36:39], v[168:171], v[200:203], v[36:39]
	v_mfma_f32_16x16x32_bf16 v[28:31], v[160:163], v[208:211], v[28:31]
	v_mfma_f32_16x16x32_bf16 v[20:23], v[168:171], v[208:211], v[20:23]
	v_mfma_f32_16x16x32_bf16 v[12:15], v[160:163], v[216:219], v[12:15]
	v_mfma_f32_16x16x32_bf16 v[4:7], v[168:171], v[216:219], v[4:7]
	s_nop 0
	s_nop 0
	v_mfma_f32_16x16x32_bf16 v[56:59], v[172:175], v[188:191], v[56:59]
	v_mfma_f32_16x16x32_bf16 v[48:51], v[180:183], v[188:191], v[48:51]
	v_mfma_f32_16x16x32_bf16 v[40:43], v[172:175], v[196:199], v[40:43]
	v_mfma_f32_16x16x32_bf16 v[32:35], v[180:183], v[196:199], v[32:35]
	v_mfma_f32_16x16x32_bf16 v[24:27], v[172:175], v[204:207], v[24:27]
	v_mfma_f32_16x16x32_bf16 v[16:19], v[180:183], v[204:207], v[16:19]
	v_mfma_f32_16x16x32_bf16 v[8:11], v[172:175], v[212:215], v[8:11]
	v_mfma_f32_16x16x32_bf16 v[0:3], v[180:183], v[212:215], v[0:3]
	v_mfma_f32_16x16x32_bf16 v[56:59], v[176:179], v[192:195], v[56:59]
	v_mfma_f32_16x16x32_bf16 v[48:51], v[184:187], v[192:195], v[48:51]
	v_mfma_f32_16x16x32_bf16 v[40:43], v[176:179], v[200:203], v[40:43]
	v_mfma_f32_16x16x32_bf16 v[32:35], v[184:187], v[200:203], v[32:35]
	v_mfma_f32_16x16x32_bf16 v[24:27], v[176:179], v[208:211], v[24:27]
	v_mfma_f32_16x16x32_bf16 v[16:19], v[184:187], v[208:211], v[16:19]
	v_mfma_f32_16x16x32_bf16 v[8:11], v[176:179], v[216:219], v[8:11]
	v_mfma_f32_16x16x32_bf16 v[0:3], v[184:187], v[216:219], v[0:3]
	s_setprio 0
	s_barrier
	s_add_i32 s55, s55, 2
	s_add_u32 s4, s4, 0x100
	s_addc_u32 s5, s5, 0
	s_add_u32 s53, s53, 0x100
	s_addc_u32 s54, s54, 0
	s_cmp_gt_u32 s55, 13
	s_cbranch_scc0 .LBB0_1666
	s_nop 0
	s_nop 0
	s_nop 0
	s_nop 0
	s_nop 0
	s_nop 0
	s_nop 0
	s_nop 0
	s_nop 0
	s_and_b64 vcc, exec, s[22:23]
	s_cbranch_vccz .LBB0_1669
	s_barrier

; #define PG8_STAGE(bufoff, gbase, voff) do { _Pragma("unroll") for (int _i = 0; _i < 2; ++_i) \
;         __builtin_amdgcn_global_load_lds((const unsigned*)((const char*)(gbase) + (voff)[_i]), (PG8_LAS unsigned*)(lds + (bufoff) + ldsw + _i * 8192), 16, 0, 0); } while (0)
; #define PG8_LDA(dst, b, h) do { _Pragma("unroll") for (int m = 0; m < 4; ++m) _Pragma("unroll") for (int k = 0; k < 2; ++k) dst[m][k] = *(const PG8_LAS bf16x8*)(lds + PG8_SA(b, h) + aoff + m * 2048 + k * 1024); } while (0)
; #define PG8_LDB(dst, b, h) do { _Pragma("unroll") for (int n = 0; n < 2; ++n) _Pragma("unroll") for (int k = 0; k < 2; ++k) dst[n][k] = *(const PG8_LAS bf16x8*)(lds + PG8_SB(b, h) + boff + n * 2048 + k * 1024); } while (0)
; #define PG8_MMA(ai, bj, At, Bt) do { __builtin_amdgcn_s_setprio(1); _Pragma("unroll") for (int m = 0; m < 4; ++m) _Pragma("unroll") for (int n = 0; n < 2; ++n) _Pragma("unroll") for (int k = 0; k < 2; ++k) \
;         acc[ai][bj][m][n] = __builtin_amdgcn_mfma_f32_16x16x32_bf16(Bt[n][k], At[m][k], acc[ai][bj][m][n], 0, 0, 0); __builtin_amdgcn_s_setprio(0); } while (0)
; #define PG8_WAIT_V(n) asm volatile("s_waitcnt vmcnt(" #n ")" ::: "memory")
; #define PG8_WAIT_L(n) asm volatile("s_waitcnt lgkmcnt(" #n ")" ::: "memory")
; template <class Epi, class Sched, bool ALIGN_EPI = false, bool SP2 = false>
; __device__ __forceinline__ void gemm_phase(PG8_LAS unsigned char* lds, const Gemm g, const Sched& S, const Epi& E) {
;     ...
;             const bool last = (t == nt - 2);
;             const char* a1 = cA + (size_t)(t + 1) * kstep;
;             const char* a2 = last ? nA : cA + (size_t)(t + 2) * kstep; const char* b2 = last ? nB : cB + (size_t)(t + 2) * kstep;
;             const char* a3 = a2 + kstep; const char* b3 = b2 + kstep;
;             if (last && has_next) S.a_ready(nxt);
;             if constexpr (SP2) {
;             PG8_LDB(B0, 0, 0); PG8_LDB(B1, 0, 1); PG8_SCHED; PG8_LDA(At, 0, 0); PG8_STAGE(PG8_SA(1, 1), a1 + hstep, voffA);
;             PG8_WAIT_V(8); PG8_WAIT_L(0); PG8_BAR; PG8_MMA(0, 0, At, B0); PG8_MMA(0, 1, At, B1); PG8_BAR; PG8_SCHED;
;             PG8_LDA(At, 0, 1); PG8_STAGE(PG8_SB(0, 0), b2, voffB); PG8_STAGE(PG8_SB(0, 1), b2 + hstep, voffB); PG8_STAGE(PG8_SA(0, 0), a2, voffA);
;             PG8_WAIT_V(8); PG8_WAIT_L(0); PG8_BAR; PG8_MMA(1, 0, At, B0); PG8_MMA(1, 1, At, B1); PG8_BAR; PG8_SCHED;
.LBB0_1751:
	s_add_u32 s22, s20, 0xfff50080
	s_addc_u32 s23, s21, -1
	s_cmp_eq_u32 s47, 40
	s_cselect_b32 s25, s1, s23
	s_cselect_b32 s24, s0, s22
	s_cselect_b32 s23, s19, s46
	s_cselect_b32 s22, s18, s45
	v_lshl_add_u64 v[190:191], s[20:21], 0, v[132:133]
	s_add_i32 m0, s27, 0xc000
	ds_read_b128 v[140:143], v194
	global_load_lds_dwordx4 v[190:191], off
	v_lshl_add_u64 v[190:191], s[20:21], 0, v[134:135]
	s_add_i32 m0, s27, 0xe000
	ds_read_b128 v[144:147], v194 offset:1024
	global_load_lds_dwordx4 v[190:191], off
	ds_read_b128 v[150:153], v194 offset:2048
	ds_read_b128 v[154:157], v194 offset:3072
	ds_read_b128 v[158:161], v195
	ds_read_b128 v[162:165], v195 offset:1024
	ds_read_b128 v[166:169], v195 offset:2048
	ds_read_b128 v[170:173], v195 offset:3072
	ds_read_b128 v[174:177], v196
	ds_read_b128 v[178:181], v196 offset:1024
	ds_read_b128 v[182:185], v196 offset:2048
	ds_read_b128 v[186:189], v196 offset:3072
	ds_read_b128 v[200:203], v196 offset:4096
	ds_read_b128 v[204:207], v196 offset:5120
	ds_read_b128 v[208:211], v196 offset:6144
	ds_read_b128 v[212:215], v196 offset:7168
	s_waitcnt vmcnt(8)
	s_waitcnt lgkmcnt(0)
	s_barrier
	s_setprio 1
	s_waitcnt lgkmcnt(0)
	v_mfma_f32_16x16x32_bf16 v[124:127], v[140:143], v[174:177], v[124:127]
	v_mfma_f32_16x16x32_bf16 v[120:123], v[150:153], v[174:177], v[120:123]
	v_mfma_f32_16x16x32_bf16 v[108:111], v[140:143], v[182:185], v[108:111]
	v_mfma_f32_16x16x32_bf16 v[104:107], v[150:153], v[182:185], v[104:107]
	v_mfma_f32_16x16x32_bf16 v[92:95], v[140:143], v[200:203], v[92:95]
	v_mfma_f32_16x16x32_bf16 v[88:91], v[150:153], v[200:203], v[88:91]
	v_mfma_f32_16x16x32_bf16 v[76:79], v[140:143], v[208:211], v[76:79]
	v_mfma_f32_16x16x32_bf16 v[72:75], v[150:153], v[208:211], v[72:75]
	v_mfma_f32_16x16x32_bf16 v[124:127], v[144:147], v[178:181], v[124:127]
	v_mfma_f32_16x16x32_bf16 v[120:123], v[154:157], v[178:181], v[120:123]
	v_mfma_f32_16x16x32_bf16 v[108:111], v[144:147], v[186:189], v[108:111]
	v_mfma_f32_16x16x32_bf16 v[104:107], v[154:157], v[186:189], v[104:107]
	v_mfma_f32_16x16x32_bf16 v[92:95], v[144:147], v[204:207], v[92:95]
	v_mfma_f32_16x16x32_bf16 v[88:91], v[154:157], v[204:207], v[88:91]
	v_mfma_f32_16x16x32_bf16 v[76:79], v[144:147], v[212:215], v[76:79]
	v_mfma_f32_16x16x32_bf16 v[72:75], v[154:157], v[212:215], v[72:75]
	s_nop 0
	s_nop 0
	v_mfma_f32_16x16x32_bf16 v[116:119], v[158:161], v[174:177], v[116:119]
	v_mfma_f32_16x16x32_bf16 v[112:115], v[166:169], v[174:177], v[112:115]
	v_mfma_f32_16x16x32_bf16 v[100:103], v[158:161], v[182:185], v[100:103]
	v_mfma_f32_16x16x32_bf16 v[96:99], v[166:169], v[182:185], v[96:99]
	v_mfma_f32_16x16x32_bf16 v[84:87], v[158:161], v[200:203], v[84:87]
	v_mfma_f32_16x16x32_bf16 v[80:83], v[166:169], v[200:203], v[80:83]
	v_mfma_f32_16x16x32_bf16 v[68:71], v[158:161], v[208:211], v[68:71]
	v_mfma_f32_16x16x32_bf16 v[64:67], v[166:169], v[208:211], v[64:67]
	v_mfma_f32_16x16x32_bf16 v[116:119], v[162:165], v[178:181], v[116:119]
	v_mfma_f32_16x16x32_bf16 v[112:115], v[170:173], v[178:181], v[112:115]
	v_mfma_f32_16x16x32_bf16 v[100:103], v[162:165], v[186:189], v[100:103]
	v_mfma_f32_16x16x32_bf16 v[96:99], v[170:173], v[186:189], v[96:99]
	v_mfma_f32_16x16x32_bf16 v[84:87], v[162:165], v[204:207], v[84:87]
	v_mfma_f32_16x16x32_bf16 v[80:83], v[170:173], v[204:207], v[80:83]
	v_mfma_f32_16x16x32_bf16 v[68:71], v[162:165], v[212:215], v[68:71]
	v_mfma_f32_16x16x32_bf16 v[64:67], v[170:173], v[212:215], v[64:67]
	s_setprio 0
	s_barrier
	s_add_i32 s50, s38, s26
	v_lshl_add_u64 v[190:191], s[22:23], 0, v[128:129]
	s_mov_b32 m0, s50
	v_lshl_add_u64 v[216:217], s[22:23], 0, v[130:131]
	global_load_lds_dwordx4 v[190:191], off
	s_add_i32 m0, s50, 0x2000
	s_add_u32 s50, s22, 0xb0000
	s_addc_u32 s51, s23, 0
	s_add_i32 s52, s39, s26
	global_load_lds_dwordx4 v[216:217], off
	v_lshl_add_u64 v[218:219], s[50:51], 0, v[128:129]
	s_mov_b32 m0, s52
	v_lshl_add_u64 v[220:221], s[24:25], 0, v[130:131]
	global_load_lds_dwordx4 v[218:219], off
	v_lshl_add_u64 v[218:219], s[50:51], 0, v[130:131]
	s_add_i32 m0, s52, 0x2000
	ds_read_b128 v[174:177], v196 offset:16384
	global_load_lds_dwordx4 v[218:219], off
	v_lshl_add_u64 v[218:219], s[24:25], 0, v[128:129]
	s_mov_b32 m0, s27
	ds_read_b128 v[178:181], v196 offset:17408
	global_load_lds_dwordx4 v[218:219], off
	s_mov_b32 m0, s28
	ds_read_b128 v[182:185], v196 offset:18432
	global_load_lds_dwordx4 v[220:221], off
	ds_read_b128 v[186:189], v196 offset:19456
	ds_read_b128 v[200:203], v196 offset:20480
	ds_read_b128 v[204:207], v196 offset:21504
	ds_read_b128 v[208:211], v196 offset:22528
	ds_read_b128 v[212:215], v196 offset:23552
	s_waitcnt vmcnt(8)
	s_waitcnt lgkmcnt(0)
	s_barrier
; #define PG8_STAGE(bufoff, gbase, voff) do { _Pragma("unroll") for (int _i = 0; _i < 2; ++_i) \
;         __builtin_amdgcn_global_load_lds((const unsigned*)((const char*)(gbase) + (voff)[_i]), (PG8_LAS unsigned*)(lds + (bufoff) + ldsw + _i * 8192), 16, 0, 0); } while (0)
; #define PG8_LDA(dst, b, h) do { _Pragma("unroll") for (int m = 0; m < 4; ++m) _Pragma("unroll") for (int k = 0; k < 2; ++k) dst[m][k] = *(const PG8_LAS bf16x8*)(lds + PG8_SA(b, h) + aoff + m * 2048 + k * 1024); } while (0)
; #define PG8_LDB(dst, b, h) do { _Pragma("unroll") for (int n = 0; n < 2; ++n) _Pragma("unroll") for (int k = 0; k < 2; ++k) dst[n][k] = *(const PG8_LAS bf16x8*)(lds + PG8_SB(b, h) + boff + n * 2048 + k * 1024); } while (0)
; #define PG8_MMA(ai, bj, At, Bt) do { __builtin_amdgcn_s_setprio(1); _Pragma("unroll") for (int m = 0; m < 4; ++m) _Pragma("unroll") for (int n = 0; n < 2; ++n) _Pragma("unroll") for (int k = 0; k < 2; ++k) \
;         acc[ai][bj][m][n] = __builtin_amdgcn_mfma_f32_16x16x32_bf16(Bt[n][k], At[m][k], acc[ai][bj][m][n], 0, 0, 0); __builtin_amdgcn_s_setprio(0); } while (0)
; #define PG8_WAIT_V(n) asm volatile("s_waitcnt vmcnt(" #n ")" ::: "memory")
; #define PG8_WAIT_L(n) asm volatile("s_waitcnt lgkmcnt(" #n ")" ::: "memory")
; #define PG8_BAR __builtin_amdgcn_s_barrier()
; #define PG8_SCHED __builtin_amdgcn_sched_barrier(0)
; template <class Epi, class Sched, bool ALIGN_EPI = false, bool SP2 = false>
; __device__ __forceinline__ void gemm_phase(PG8_LAS unsigned char* lds, const Gemm g, const Sched& S, const Epi& E) {
;     ...
;             PG8_WAIT_V(8); PG8_WAIT_L(0); PG8_BAR; PG8_MMA(1, 0, At, B0); PG8_MMA(1, 1, At, B1); PG8_BAR; PG8_SCHED;
;             PG8_LDB(B0, 1, 0); PG8_LDB(B1, 1, 1); PG8_SCHED; PG8_LDA(At, 1, 0); PG8_STAGE(PG8_SA(0, 1), a2 + hstep, voffA);
;             PG8_WAIT_V(8); PG8_WAIT_L(0); PG8_BAR; PG8_MMA(0, 0, At, B0); PG8_MMA(0, 1, At, B1); PG8_BAR; PG8_SCHED;
	s_setprio 1
	s_waitcnt lgkmcnt(0)
	v_mfma_f32_16x16x32_bf16 v[60:63], v[140:143], v[174:177], v[60:63]
	v_mfma_f32_16x16x32_bf16 v[56:59], v[150:153], v[174:177], v[56:59]
	v_mfma_f32_16x16x32_bf16 v[44:47], v[140:143], v[182:185], v[44:47]
	v_mfma_f32_16x16x32_bf16 v[40:43], v[150:153], v[182:185], v[40:43]
	v_mfma_f32_16x16x32_bf16 v[28:31], v[140:143], v[200:203], v[28:31]
	v_mfma_f32_16x16x32_bf16 v[24:27], v[150:153], v[200:203], v[24:27]
	v_mfma_f32_16x16x32_bf16 v[12:15], v[140:143], v[208:211], v[12:15]
	v_mfma_f32_16x16x32_bf16 v[8:11], v[150:153], v[208:211], v[8:11]
	v_mfma_f32_16x16x32_bf16 v[60:63], v[144:147], v[178:181], v[60:63]
	v_mfma_f32_16x16x32_bf16 v[56:59], v[154:157], v[178:181], v[56:59]
	v_mfma_f32_16x16x32_bf16 v[44:47], v[144:147], v[186:189], v[44:47]
	v_mfma_f32_16x16x32_bf16 v[40:43], v[154:157], v[186:189], v[40:43]
	v_mfma_f32_16x16x32_bf16 v[28:31], v[144:147], v[204:207], v[28:31]
	v_mfma_f32_16x16x32_bf16 v[24:27], v[154:157], v[204:207], v[24:27]
	v_mfma_f32_16x16x32_bf16 v[12:15], v[144:147], v[212:215], v[12:15]
	v_mfma_f32_16x16x32_bf16 v[8:11], v[154:157], v[212:215], v[8:11]
	s_nop 0
	s_nop 0
	v_mfma_f32_16x16x32_bf16 v[52:55], v[158:161], v[174:177], v[52:55]
	v_mfma_f32_16x16x32_bf16 v[48:51], v[166:169], v[174:177], v[48:51]
	v_mfma_f32_16x16x32_bf16 v[36:39], v[158:161], v[182:185], v[36:39]
	v_mfma_f32_16x16x32_bf16 v[32:35], v[166:169], v[182:185], v[32:35]
	v_mfma_f32_16x16x32_bf16 v[20:23], v[158:161], v[200:203], v[20:23]
	v_mfma_f32_16x16x32_bf16 v[16:19], v[166:169], v[200:203], v[16:19]
	v_mfma_f32_16x16x32_bf16 v[4:7], v[158:161], v[208:211], v[4:7]
	v_mfma_f32_16x16x32_bf16 v[0:3], v[166:169], v[208:211], v[0:3]
	v_mfma_f32_16x16x32_bf16 v[52:55], v[162:165], v[178:181], v[52:55]
	v_mfma_f32_16x16x32_bf16 v[48:51], v[170:173], v[178:181], v[48:51]
	v_mfma_f32_16x16x32_bf16 v[36:39], v[162:165], v[186:189], v[36:39]
	v_mfma_f32_16x16x32_bf16 v[32:35], v[170:173], v[186:189], v[32:35]
	v_mfma_f32_16x16x32_bf16 v[20:23], v[162:165], v[204:207], v[20:23]
	v_mfma_f32_16x16x32_bf16 v[16:19], v[170:173], v[204:207], v[16:19]
	v_mfma_f32_16x16x32_bf16 v[4:7], v[162:165], v[212:215], v[4:7]
	v_mfma_f32_16x16x32_bf16 v[0:3], v[170:173], v[212:215], v[0:3]
	s_setprio 0
	s_barrier
	s_add_i32 s50, 0, 0x18000
	s_add_i32 s51, 0, 0x1c000
	s_add_u32 s24, s24, 0xb0000
	s_addc_u32 s25, s25, 0
	s_mov_b32 m0, s29
	v_lshl_add_u64 v[222:223], s[24:25], 0, v[128:129]
	global_load_lds_dwordx4 v[222:223], off
	v_lshl_add_u64 v[222:223], s[24:25], 0, v[130:131]
	s_mov_b32 m0, s30
	v_add_u32_e32 v154, s50, v192
	global_load_lds_dwordx4 v[222:223], off
	v_add_u32_e32 v170, s51, v192
	ds_read_b128 v[140:143], v154
	ds_read_b128 v[144:147], v154 offset:1024
	ds_read_b128 v[150:153], v154 offset:2048
	ds_read_b128 v[154:157], v154 offset:3072
	ds_read_b128 v[158:161], v170
	ds_read_b128 v[162:165], v170 offset:1024
	ds_read_b128 v[166:169], v170 offset:2048
	ds_read_b128 v[170:173], v170 offset:3072
	ds_read_b128 v[174:177], v196 offset:32768
	ds_read_b128 v[178:181], v196 offset:33792
	ds_read_b128 v[182:185], v196 offset:34816
	ds_read_b128 v[186:189], v196 offset:35840
	ds_read_b128 v[200:203], v196 offset:36864
	ds_read_b128 v[204:207], v196 offset:37888
	ds_read_b128 v[208:211], v196 offset:38912
	ds_read_b128 v[212:215], v196 offset:39936
	s_waitcnt vmcnt(8)
	s_waitcnt lgkmcnt(0)
	s_barrier
	s_setprio 1
	s_waitcnt lgkmcnt(0)
	v_mfma_f32_16x16x32_bf16 v[124:127], v[140:143], v[174:177], v[124:127]
	v_mfma_f32_16x16x32_bf16 v[120:123], v[150:153], v[174:177], v[120:123]
	v_mfma_f32_16x16x32_bf16 v[108:111], v[140:143], v[182:185], v[108:111]
	v_mfma_f32_16x16x32_bf16 v[104:107], v[150:153], v[182:185], v[104:107]
	v_mfma_f32_16x16x32_bf16 v[92:95], v[140:143], v[200:203], v[92:95]
	v_mfma_f32_16x16x32_bf16 v[88:91], v[150:153], v[200:203], v[88:91]
	v_mfma_f32_16x16x32_bf16 v[76:79], v[140:143], v[208:211], v[76:79]
	v_mfma_f32_16x16x32_bf16 v[72:75], v[150:153], v[208:211], v[72:75]
	v_mfma_f32_16x16x32_bf16 v[124:127], v[144:147], v[178:181], v[124:127]
	v_mfma_f32_16x16x32_bf16 v[120:123], v[154:157], v[178:181], v[120:123]
	v_mfma_f32_16x16x32_bf16 v[108:111], v[144:147], v[186:189], v[108:111]
	v_mfma_f32_16x16x32_bf16 v[104:107], v[154:157], v[186:189], v[104:107]
	v_mfma_f32_16x16x32_bf16 v[92:95], v[144:147], v[204:207], v[92:95]
	v_mfma_f32_16x16x32_bf16 v[88:91], v[154:157], v[204:207], v[88:91]
	v_mfma_f32_16x16x32_bf16 v[76:79], v[144:147], v[212:215], v[76:79]
	v_mfma_f32_16x16x32_bf16 v[72:75], v[154:157], v[212:215], v[72:75]
	s_nop 0
	s_nop 0
	v_mfma_f32_16x16x32_bf16 v[116:119], v[158:161], v[174:177], v[116:119]
	v_mfma_f32_16x16x32_bf16 v[112:115], v[166:169], v[174:177], v[112:115]
	v_mfma_f32_16x16x32_bf16 v[100:103], v[158:161], v[182:185], v[100:103]
	v_mfma_f32_16x16x32_bf16 v[96:99], v[166:169], v[182:185], v[96:99]
	v_mfma_f32_16x16x32_bf16 v[84:87], v[158:161], v[200:203], v[84:87]
	v_mfma_f32_16x16x32_bf16 v[80:83], v[166:169], v[200:203], v[80:83]
	v_mfma_f32_16x16x32_bf16 v[68:71], v[158:161], v[208:211], v[68:71]
	v_mfma_f32_16x16x32_bf16 v[64:67], v[166:169], v[208:211], v[64:67]
	v_mfma_f32_16x16x32_bf16 v[116:119], v[162:165], v[178:181], v[116:119]
	v_mfma_f32_16x16x32_bf16 v[112:115], v[170:173], v[178:181], v[112:115]
	v_mfma_f32_16x16x32_bf16 v[100:103], v[162:165], v[186:189], v[100:103]
	v_mfma_f32_16x16x32_bf16 v[96:99], v[170:173], v[186:189], v[96:99]
	v_mfma_f32_16x16x32_bf16 v[84:87], v[162:165], v[204:207], v[84:87]
	v_mfma_f32_16x16x32_bf16 v[80:83], v[170:173], v[204:207], v[80:83]
	v_mfma_f32_16x16x32_bf16 v[68:71], v[162:165], v[212:215], v[68:71]
	v_mfma_f32_16x16x32_bf16 v[64:67], v[170:173], v[212:215], v[64:67]
	s_setprio 0
	s_barrier
; #define PG8_STAGE(bufoff, gbase, voff) do { _Pragma("unroll") for (int _i = 0; _i < 2; ++_i) \
;         __builtin_amdgcn_global_load_lds((const unsigned*)((const char*)(gbase) + (voff)[_i]), (PG8_LAS unsigned*)(lds + (bufoff) + ldsw + _i * 8192), 16, 0, 0); } while (0)
; #define PG8_LDA(dst, b, h) do { _Pragma("unroll") for (int m = 0; m < 4; ++m) _Pragma("unroll") for (int k = 0; k < 2; ++k) dst[m][k] = *(const PG8_LAS bf16x8*)(lds + PG8_SA(b, h) + aoff + m * 2048 + k * 1024); } while (0)
; #define PG8_MMA(ai, bj, At, Bt) do { __builtin_amdgcn_s_setprio(1); _Pragma("unroll") for (int m = 0; m < 4; ++m) _Pragma("unroll") for (int n = 0; n < 2; ++n) _Pragma("unroll") for (int k = 0; k < 2; ++k) \
;         acc[ai][bj][m][n] = __builtin_amdgcn_mfma_f32_16x16x32_bf16(Bt[n][k], At[m][k], acc[ai][bj][m][n], 0, 0, 0); __builtin_amdgcn_s_setprio(0); } while (0)
; #define PG8_WAIT_V(n) asm volatile("s_waitcnt vmcnt(" #n ")" ::: "memory")
; #define PG8_WAIT_L(n) asm volatile("s_waitcnt lgkmcnt(" #n ")" ::: "memory")
; #define PG8_BAR __builtin_amdgcn_s_barrier()
; #define PG8_SCHED __builtin_amdgcn_sched_barrier(0)
; template <class Epi, class Sched, bool ALIGN_EPI = false, bool SP2 = false>
; __device__ __forceinline__ void gemm_phase(PG8_LAS unsigned char* lds, const Gemm g, const Sched& S, const Epi& E) {
;     ...
;             PG8_LDA(At, 1, 1); PG8_STAGE(PG8_SB(1, 0), b3, voffB); PG8_STAGE(PG8_SB(1, 1), b3 + hstep, voffB); PG8_STAGE(PG8_SA(1, 0), a3, voffA);
;             PG8_WAIT_V(8); PG8_WAIT_L(0); PG8_BAR; PG8_MMA(1, 0, At, B0); PG8_MMA(1, 1, At, B1); PG8_BAR; PG8_SCHED;
;     ...
;         if constexpr (ALIGN_EPI) { if (wr == 0) PG8_BAR; }
	s_add_i32 s24, s50, s26
	v_lshl_add_u64 v[190:191], v[190:191], 0, s[14:15]
	s_mov_b32 m0, s24
	ds_read_b128 v[174:177], v196 offset:49152
	global_load_lds_dwordx4 v[190:191], off
	s_add_i32 m0, s24, 0x2000
	s_add_u32 s22, s22, 0xb0080
	v_lshl_add_u64 v[190:191], v[216:217], 0, s[14:15]
	s_addc_u32 s23, s23, 0
	s_add_i32 s24, s51, s26
	global_load_lds_dwordx4 v[190:191], off
	v_lshl_add_u64 v[190:191], s[22:23], 0, v[128:129]
	s_mov_b32 m0, s24
	ds_read_b128 v[178:181], v196 offset:50176
	global_load_lds_dwordx4 v[190:191], off
	v_lshl_add_u64 v[190:191], s[22:23], 0, v[130:131]
	s_add_i32 m0, s24, 0x2000
	ds_read_b128 v[182:185], v196 offset:51200
	global_load_lds_dwordx4 v[190:191], off
	v_lshl_add_u64 v[190:191], v[218:219], 0, s[14:15]
	s_mov_b32 m0, s34
	ds_read_b128 v[186:189], v196 offset:52224
	global_load_lds_dwordx4 v[190:191], off
	v_lshl_add_u64 v[190:191], v[220:221], 0, s[14:15]
	s_mov_b32 m0, s35
	ds_read_b128 v[200:203], v196 offset:53248
	global_load_lds_dwordx4 v[190:191], off
	ds_read_b128 v[204:207], v196 offset:54272
	ds_read_b128 v[208:211], v196 offset:55296
	ds_read_b128 v[212:215], v196 offset:56320
	s_waitcnt vmcnt(8)
	s_waitcnt lgkmcnt(0)
	s_barrier
	s_setprio 1
	s_waitcnt lgkmcnt(0)
	v_mfma_f32_16x16x32_bf16 v[60:63], v[140:143], v[174:177], v[60:63]
	v_mfma_f32_16x16x32_bf16 v[56:59], v[150:153], v[174:177], v[56:59]
	v_mfma_f32_16x16x32_bf16 v[44:47], v[140:143], v[182:185], v[44:47]
	v_mfma_f32_16x16x32_bf16 v[40:43], v[150:153], v[182:185], v[40:43]
	v_mfma_f32_16x16x32_bf16 v[28:31], v[140:143], v[200:203], v[28:31]
	v_mfma_f32_16x16x32_bf16 v[24:27], v[150:153], v[200:203], v[24:27]
	v_mfma_f32_16x16x32_bf16 v[12:15], v[140:143], v[208:211], v[12:15]
	v_mfma_f32_16x16x32_bf16 v[8:11], v[150:153], v[208:211], v[8:11]
	v_mfma_f32_16x16x32_bf16 v[60:63], v[144:147], v[178:181], v[60:63]
	v_mfma_f32_16x16x32_bf16 v[56:59], v[154:157], v[178:181], v[56:59]
	v_mfma_f32_16x16x32_bf16 v[44:47], v[144:147], v[186:189], v[44:47]
	v_mfma_f32_16x16x32_bf16 v[40:43], v[154:157], v[186:189], v[40:43]
	v_mfma_f32_16x16x32_bf16 v[28:31], v[144:147], v[204:207], v[28:31]
	v_mfma_f32_16x16x32_bf16 v[24:27], v[154:157], v[204:207], v[24:27]
	v_mfma_f32_16x16x32_bf16 v[12:15], v[144:147], v[212:215], v[12:15]
	v_mfma_f32_16x16x32_bf16 v[8:11], v[154:157], v[212:215], v[8:11]
	s_nop 0
	s_nop 0
	v_mfma_f32_16x16x32_bf16 v[52:55], v[158:161], v[174:177], v[52:55]
	v_mfma_f32_16x16x32_bf16 v[48:51], v[166:169], v[174:177], v[48:51]
	v_mfma_f32_16x16x32_bf16 v[36:39], v[158:161], v[182:185], v[36:39]
	v_mfma_f32_16x16x32_bf16 v[32:35], v[166:169], v[182:185], v[32:35]
	v_mfma_f32_16x16x32_bf16 v[20:23], v[158:161], v[200:203], v[20:23]
	v_mfma_f32_16x16x32_bf16 v[16:19], v[166:169], v[200:203], v[16:19]
	v_mfma_f32_16x16x32_bf16 v[4:7], v[158:161], v[208:211], v[4:7]
	v_mfma_f32_16x16x32_bf16 v[0:3], v[166:169], v[208:211], v[0:3]
	v_mfma_f32_16x16x32_bf16 v[52:55], v[162:165], v[178:181], v[52:55]
	v_mfma_f32_16x16x32_bf16 v[48:51], v[170:173], v[178:181], v[48:51]
	v_mfma_f32_16x16x32_bf16 v[36:39], v[162:165], v[186:189], v[36:39]
	v_mfma_f32_16x16x32_bf16 v[32:35], v[170:173], v[186:189], v[32:35]
	v_mfma_f32_16x16x32_bf16 v[20:23], v[162:165], v[204:207], v[20:23]
	v_mfma_f32_16x16x32_bf16 v[16:19], v[170:173], v[204:207], v[16:19]
	v_mfma_f32_16x16x32_bf16 v[4:7], v[162:165], v[212:215], v[4:7]
	v_mfma_f32_16x16x32_bf16 v[0:3], v[170:173], v[212:215], v[0:3]
	s_setprio 0
	s_barrier
	s_add_i32 s47, s47, 2
	s_add_u32 s20, s20, 0x100
	s_addc_u32 s21, s21, 0
	s_add_u32 s45, s45, 0x100
	s_addc_u32 s46, s46, 0
	s_cmp_gt_u32 s47, 41
	s_cbranch_scc0 .LBB0_1751
	s_nop 0
	s_nop 0
	s_nop 0
	s_nop 0
	s_nop 0
	s_nop 0
	s_nop 0
	s_nop 0
	s_nop 0
	s_and_b64 vcc, exec, s[16:17]
	s_cbranch_vccz .LBB0_1754
	s_barrier
